# mixer phase: nt hint on the branch-output (Y) stores, read once by the merge GEMM behind the grid barrier
# baseline (speedup 1.0000x reference)
.LBB0_650:
	s_mov_b64 s[10:11], 0
	s_and_b64 vcc, exec, s[6:7]
	s_cbranch_vccz .LBB0_652
	s_lshl_b32 s0, s12, 6
	v_ashrrev_i32_e32 v0, 3, v206
	s_addk_i32 s0, 0x8000
	v_and_b32_e32 v0, -4, v0
	v_add_u32_e32 v34, s0, v0
	v_lshlrev_b32_e32 v0, 3, v206
	s_movk_i32 s13, 0x4000
	v_and_b32_e32 v18, 0xf8, v0
	v_cmp_gt_i32_e32 vcc, s13, v34
	v_bfrev_b32_e32 v0, 0.5
	v_mov_b32_e32 v1, 0xffc
	v_cndmask_b32_e32 v0, v0, v1, vcc
	v_ashrrev_i32_e32 v35, 31, v34
	v_and_b32_e32 v2, v0, v34
	v_lshlrev_b64 v[0:1], 13, v[34:35]
	v_lshl_add_u64 v[0:1], s[70:71], 0, v[0:1]
	v_lshlrev_b32_e32 v32, 1, v18
	v_lshl_add_u64 v[8:9], v[0:1], 0, v[32:33]
	s_movk_i32 s0, 0x2000
	v_add_co_u32_e64 v10, s[8:9], s0, v8
	v_cmp_ne_u32_e64 s[6:7], 0, v2
	s_nop 0
	v_addc_co_u32_e64 v11, s[8:9], 0, v9, s[8:9]
	v_cndmask_b32_e64 v0, 0, -1, s[6:7]
	v_add_co_u32_e64 v12, s[8:9], s13, v8
	v_mov_b32_e32 v1, v0
	s_nop 0
	v_addc_co_u32_e64 v13, s[8:9], 0, v9, s[8:9]
	s_movk_i32 s0, 0x6000
	v_lshlrev_b64 v[0:1], 13, v[0:1]
	v_add_co_u32_e64 v14, s[8:9], s0, v8
	v_lshl_add_u64 v[0:1], v[8:9], 0, v[0:1]
	s_nop 0
	v_addc_co_u32_e64 v15, s[8:9], 0, v9, s[8:9]
	v_cndmask_b32_e64 v122, 0, 1.0, s[6:7]
	s_lshl_b32 s6, s5, 8
	global_load_dwordx4 v[116:119], v[0:1], off offset:2560
	global_load_dwordx4 v[98:101], v[0:1], off offset:3584
	global_load_dwordx4 v[86:89], v[8:9], off offset:2560
	global_load_dwordx4 v[90:93], v[8:9], off offset:3584
	v_or_b32_e32 v0, 3, v2
	v_mov_b32_e32 v1, 0xff
	v_mov_b32_e32 v2, 0xfff
	s_ashr_i32 s7, s6, 31
	s_mul_i32 s8, s5, 0x300
	v_cndmask_b32_e32 v1, v1, v2, vcc
	s_ashr_i32 s9, s8, 31
	s_lshl_b64 s[6:7], s[6:7], 2
	v_cmp_lt_u32_e32 vcc, v0, v1
	v_mov_b32_e32 v0, 0x6000
	v_mov_b32_e32 v1, 0x8000
	s_add_u32 s16, s40, s6
	s_movk_i32 s0, 0x1000
	v_cndmask_b32_e32 v0, v0, v1, vcc
	v_mov_b32_e32 v1, v33
	s_addc_u32 s17, s41, s7
	v_add_co_u32_e64 v16, s[6:7], s0, v8
	v_lshl_add_u64 v[0:1], v[8:9], 0, v[0:1]
	s_nop 0
	v_addc_co_u32_e64 v17, s[6:7], 0, v9, s[6:7]
	s_movk_i32 s0, 0x3000
	global_load_dwordx4 v[102:105], v[10:11], off offset:2560
	global_load_dwordx4 v[94:97], v[10:11], off offset:3584
	global_load_dwordx4 v[74:77], v[12:13], off offset:2560
	global_load_dwordx4 v[70:73], v[12:13], off offset:3584
	global_load_dwordx4 v[58:61], v[14:15], off offset:2560
	global_load_dwordx4 v[54:57], v[14:15], off offset:3584
	global_load_dwordx4 v[4:7], v[0:1], off offset:2560
	s_nop 0
	global_load_dwordx4 v[0:3], v[0:1], off offset:3584
	v_lshlrev_b32_e32 v35, 2, v18
	global_load_dwordx4 v[110:113], v[8:9], off offset:3072
	global_load_dwordx4 v[106:109], v[16:17], off
	global_load_dwordx4 v[82:85], v[10:11], off offset:3072
	v_add_co_u32_e64 v10, s[6:7], s0, v8
	s_movk_i32 s0, 0x5000
	s_nop 0
	v_addc_co_u32_e64 v11, s[6:7], 0, v9, s[6:7]
	global_load_dwordx4 v[78:81], v[10:11], off
	global_load_dwordx4 v[66:69], v[12:13], off offset:3072
	v_add_co_u32_e64 v10, s[6:7], s0, v8
	s_movk_i32 s0, 0x7000
	s_nop 0
	v_addc_co_u32_e64 v11, s[6:7], 0, v9, s[6:7]
	v_add_co_u32_e64 v8, s[6:7], s0, v8
	global_load_dwordx4 v[62:65], v[10:11], off
	global_load_dwordx4 v[28:31], v[14:15], off offset:3072
	v_addc_co_u32_e64 v9, s[6:7], 0, v9, s[6:7]
	s_lshl_b64 s[6:7], s[8:9], 2
	s_add_u32 s6, s38, s6
	global_load_dwordx4 v[24:27], v[8:9], off
	s_addc_u32 s7, s39, s7
	global_load_dwordx4 v[8:11], v35, s[16:17] offset:16
	global_load_dwordx4 v[38:41], v35, s[16:17]
	global_load_dwordx4 v[12:15], v35, s[6:7] offset:16
	global_load_dwordx4 v[42:45], v35, s[6:7]
	global_load_dwordx4 v[16:19], v35, s[6:7] offset:1040
	global_load_dwordx4 v[46:49], v35, s[6:7] offset:1024
	global_load_dwordx4 v[20:23], v35, s[6:7] offset:2064
	global_load_dwordx4 v[50:53], v35, s[6:7] offset:2048
	v_cndmask_b32_e64 v114, 0, 1.0, vcc
	s_waitcnt vmcnt(14)
	v_lshlrev_b32_e32 v132, 16, v106
	v_mul_f32_e32 v35, 0xbfb8aa3b, v132
	v_exp_f32_e32 v35, v35
	v_and_b32_e32 v133, 0xffff0000, v106
	v_lshlrev_b32_e32 v120, 16, v116
	v_and_b32_e32 v121, 0xffff0000, v116
	v_add_f32_e32 v35, 1.0, v35
	v_rcp_f32_e32 v134, v35
	v_mul_f32_e32 v35, 0xbfb8aa3b, v133
	v_exp_f32_e32 v35, v35
	v_lshlrev_b32_e32 v128, 16, v117
	v_and_b32_e32 v129, 0xffff0000, v117
	v_lshlrev_b32_e32 v126, 16, v118
	v_and_b32_e32 v127, 0xffff0000, v118
	v_lshlrev_b32_e32 v124, 16, v119
	v_and_b32_e32 v125, 0xffff0000, v119
	v_lshlrev_b32_e32 v116, 16, v98
	v_and_b32_e32 v117, 0xffff0000, v98
	v_pk_mul_f32 v[118:119], v[122:123], v[120:121] op_sel_hi:[0,1]
	v_pk_mul_f32 v[120:121], v[118:119], v[116:117]
	v_lshlrev_b32_e32 v116, 16, v86
	v_and_b32_e32 v117, 0xffff0000, v86
	v_lshlrev_b32_e32 v118, 16, v90
	v_and_b32_e32 v119, 0xffff0000, v90
	v_pk_mul_f32 v[118:119], v[116:117], v[118:119]
	v_add_f32_e32 v35, 1.0, v35
	v_lshlrev_b32_e32 v116, 16, v102
	v_and_b32_e32 v117, 0xffff0000, v102
	v_lshlrev_b32_e32 v130, 16, v94
	v_and_b32_e32 v131, 0xffff0000, v94
	s_waitcnt vmcnt(2)
	v_pk_mul_f32 v[136:137], v[118:119], v[46:47]
	v_rcp_f32_e32 v135, v35
	v_pk_mul_f32 v[116:117], v[116:117], v[130:131]
	v_pk_fma_f32 v[120:121], v[120:121], v[42:43], v[136:137]
	v_lshlrev_b32_e32 v102, 16, v107
	s_waitcnt vmcnt(0)
	v_pk_fma_f32 v[120:121], v[116:117], v[50:51], v[120:121]
	v_lshlrev_b32_e32 v130, 16, v110
	v_and_b32_e32 v131, 0xffff0000, v110
	v_pk_add_f32 v[120:121], v[38:39], v[120:121]
	v_mul_f32_e32 v35, 0xbfb8aa3b, v102
	v_pk_mul_f32 v[120:121], v[120:121], v[130:131]
	v_pk_mul_f32 v[130:131], v[134:135], v[132:133]
	v_exp_f32_e32 v35, v35
	v_pk_mul_f32 v[120:121], v[130:131], v[120:121]
	v_lshlrev_b32_e32 v98, 16, v99
	v_cvt_pk_bf16_f32 v86, v120, v121
	v_and_b32_e32 v99, 0xffff0000, v99
	v_pk_mul_f32 v[120:121], v[122:123], v[128:129] op_sel_hi:[0,1]
	v_pk_mul_f32 v[98:99], v[120:121], v[98:99]
	v_lshlrev_b32_e32 v120, 16, v87
	v_and_b32_e32 v121, 0xffff0000, v87
	v_lshlrev_b32_e32 v90, 16, v91
	v_and_b32_e32 v91, 0xffff0000, v91
	v_pk_mul_f32 v[120:121], v[120:121], v[90:91]
	v_lshlrev_b32_e32 v90, 16, v103
	v_and_b32_e32 v91, 0xffff0000, v103
	v_and_b32_e32 v103, 0xffff0000, v107
	v_add_f32_e32 v35, 1.0, v35
	v_rcp_f32_e32 v106, v35
	v_mul_f32_e32 v35, 0xbfb8aa3b, v103
	v_exp_f32_e32 v35, v35
	v_lshlrev_b32_e32 v94, 16, v95
	v_and_b32_e32 v95, 0xffff0000, v95
	v_pk_mul_f32 v[94:95], v[90:91], v[94:95]
	v_lshlrev_b32_e32 v90, 16, v111
	v_and_b32_e32 v91, 0xffff0000, v111
	v_pk_mul_f32 v[110:111], v[120:121], v[48:49]
	v_add_f32_e32 v35, 1.0, v35
	v_pk_fma_f32 v[98:99], v[98:99], v[44:45], v[110:111]
	v_lshlrev_b32_e32 v110, 16, v108
	v_rcp_f32_e32 v107, v35
	v_mul_f32_e32 v35, 0xbfb8aa3b, v110
	v_exp_f32_e32 v35, v35
	v_pk_fma_f32 v[98:99], v[94:95], v[52:53], v[98:99]
	v_and_b32_e32 v111, 0xffff0000, v108
	v_pk_add_f32 v[98:99], v[40:41], v[98:99]
	v_add_f32_e32 v35, 1.0, v35
	v_pk_mul_f32 v[90:91], v[98:99], v[90:91]
	v_pk_mul_f32 v[98:99], v[106:107], v[102:103]
	v_lshlrev_b32_e32 v102, 16, v92
	v_pk_mul_f32 v[90:91], v[98:99], v[90:91]
	v_pk_mul_f32 v[98:99], v[122:123], v[126:127] op_sel_hi:[0,1]
	v_rcp_f32_e32 v126, v35
	v_mul_f32_e32 v35, 0xbfb8aa3b, v111
	v_exp_f32_e32 v35, v35
	v_cvt_pk_bf16_f32 v87, v90, v91
	v_lshlrev_b32_e32 v90, 16, v100
	v_and_b32_e32 v91, 0xffff0000, v100
	v_pk_mul_f32 v[90:91], v[98:99], v[90:91]
	v_lshlrev_b32_e32 v98, 16, v88
	v_and_b32_e32 v99, 0xffff0000, v88
	v_and_b32_e32 v103, 0xffff0000, v92
	v_pk_mul_f32 v[102:103], v[98:99], v[102:103]
	v_add_f32_e32 v35, 1.0, v35
	v_lshlrev_b32_e32 v98, 16, v104
	v_and_b32_e32 v99, 0xffff0000, v104
	v_lshlrev_b32_e32 v106, 16, v96
	v_and_b32_e32 v107, 0xffff0000, v96
	v_pk_mul_f32 v[128:129], v[102:103], v[16:17]
	v_rcp_f32_e32 v127, v35
	v_pk_mul_f32 v[98:99], v[98:99], v[106:107]
	v_pk_fma_f32 v[90:91], v[90:91], v[12:13], v[128:129]
	v_lshlrev_b32_e32 v104, 16, v109
	v_pk_fma_f32 v[90:91], v[98:99], v[20:21], v[90:91]
	v_lshlrev_b32_e32 v106, 16, v112
	v_and_b32_e32 v107, 0xffff0000, v112
	v_pk_add_f32 v[90:91], v[8:9], v[90:91]
	v_mul_f32_e32 v35, 0xbfb8aa3b, v104
	v_pk_mul_f32 v[90:91], v[90:91], v[106:107]
	v_pk_mul_f32 v[106:107], v[126:127], v[110:111]
	v_exp_f32_e32 v35, v35
	v_pk_mul_f32 v[90:91], v[106:107], v[90:91]
	v_lshlrev_b32_e32 v92, 16, v93
	v_cvt_pk_bf16_f32 v88, v90, v91
	v_lshlrev_b32_e32 v90, 16, v101
	v_and_b32_e32 v91, 0xffff0000, v101
	v_pk_mul_f32 v[100:101], v[122:123], v[124:125] op_sel_hi:[0,1]
	v_pk_mul_f32 v[90:91], v[100:101], v[90:91]
	v_lshlrev_b32_e32 v100, 16, v89
	v_and_b32_e32 v101, 0xffff0000, v89
	v_and_b32_e32 v93, 0xffff0000, v93
	v_pk_mul_f32 v[100:101], v[100:101], v[92:93]
	v_lshlrev_b32_e32 v92, 16, v105
	v_and_b32_e32 v93, 0xffff0000, v105
	v_and_b32_e32 v105, 0xffff0000, v109
	v_add_f32_e32 v35, 1.0, v35
	v_rcp_f32_e32 v106, v35
	v_mul_f32_e32 v35, 0xbfb8aa3b, v105
	v_exp_f32_e32 v35, v35
	v_lshlrev_b32_e32 v96, 16, v97
	v_and_b32_e32 v97, 0xffff0000, v97
	v_pk_mul_f32 v[108:109], v[100:101], v[18:19]
	v_add_f32_e32 v35, 1.0, v35
	v_rcp_f32_e32 v107, v35
	v_pk_mul_f32 v[92:93], v[92:93], v[96:97]
	v_pk_fma_f32 v[90:91], v[90:91], v[14:15], v[108:109]
	v_lshlrev_b32_e32 v96, 16, v113
	v_pk_fma_f32 v[90:91], v[92:93], v[22:23], v[90:91]
	v_and_b32_e32 v97, 0xffff0000, v113
	v_pk_add_f32 v[90:91], v[10:11], v[90:91]
	s_mov_b32 s0, 0x18c00000
	v_pk_mul_f32 v[90:91], v[90:91], v[96:97]
	v_pk_mul_f32 v[96:97], v[106:107], v[104:105]
	v_pk_mul_f32 v[106:107], v[116:117], v[46:47]
	v_pk_mul_f32 v[90:91], v[96:97], v[90:91]
	v_pk_fma_f32 v[106:107], v[118:119], v[42:43], v[106:107]
	v_cvt_pk_bf16_f32 v89, v90, v91
	v_mov_b64_e32 v[90:91], s[48:49]
	v_mad_i64_i32 v[96:97], s[6:7], v34, s44, v[90:91]
	v_lshl_add_u64 v[96:97], v[96:97], 0, v[32:33]
	v_add_co_u32_e32 v96, vcc, s0, v96
	s_mov_b64 s[76:77], 0
	s_nop 0
	v_addc_co_u32_e32 v97, vcc, 0, v97, vcc
	global_store_dwordx4 v[96:97], v[86:89], off offset:1024 nt
	v_lshlrev_b32_e32 v96, 16, v78
	v_mul_f32_e32 v35, 0xbfb8aa3b, v96
	v_exp_f32_e32 v35, v35
	v_and_b32_e32 v97, 0xffff0000, v78
	v_lshlrev_b32_e32 v78, 16, v79
	v_lshlrev_b32_e32 v86, 16, v74
	v_add_f32_e32 v35, 1.0, v35
	v_rcp_f32_e32 v104, v35
	v_mul_f32_e32 v35, 0xbfb8aa3b, v97
	v_exp_f32_e32 v35, v35
	v_and_b32_e32 v87, 0xffff0000, v74
	v_lshlrev_b32_e32 v88, 16, v70
	v_and_b32_e32 v89, 0xffff0000, v70
	v_add_f32_e32 v35, 1.0, v35
	v_rcp_f32_e32 v105, v35
	v_mul_f32_e32 v35, 0xbfb8aa3b, v78
	v_exp_f32_e32 v35, v35
	v_and_b32_e32 v79, 0xffff0000, v79
	v_pk_mul_f32 v[88:89], v[86:87], v[88:89]
	v_lshlrev_b32_e32 v86, 16, v82
	v_add_f32_e32 v35, 1.0, v35
	v_and_b32_e32 v87, 0xffff0000, v82
	v_rcp_f32_e32 v82, v35
	v_mul_f32_e32 v35, 0xbfb8aa3b, v79
	v_pk_fma_f32 v[106:107], v[88:89], v[50:51], v[106:107]
	v_exp_f32_e32 v35, v35
	v_pk_add_f32 v[106:107], v[38:39], v[106:107]
	v_pk_mul_f32 v[96:97], v[104:105], v[96:97]
	v_pk_mul_f32 v[86:87], v[106:107], v[86:87]
	v_lshlrev_b32_e32 v74, 16, v75
	v_pk_mul_f32 v[86:87], v[96:97], v[86:87]
	v_and_b32_e32 v75, 0xffff0000, v75
	v_cvt_pk_bf16_f32 v70, v86, v87
	v_lshlrev_b32_e32 v86, 16, v71
	v_and_b32_e32 v87, 0xffff0000, v71
	v_add_f32_e32 v35, 1.0, v35
	v_pk_mul_f32 v[86:87], v[74:75], v[86:87]
	v_lshlrev_b32_e32 v74, 16, v83
	v_and_b32_e32 v75, 0xffff0000, v83
	v_rcp_f32_e32 v83, v35
	v_pk_mul_f32 v[96:97], v[94:95], v[48:49]
	v_pk_mul_f32 v[104:105], v[98:99], v[16:17]
	v_pk_fma_f32 v[96:97], v[120:121], v[44:45], v[96:97]
	v_pk_mul_f32 v[78:79], v[82:83], v[78:79]
	v_lshlrev_b32_e32 v82, 16, v80
	v_mul_f32_e32 v35, 0xbfb8aa3b, v82
	v_exp_f32_e32 v35, v35
	v_pk_fma_f32 v[96:97], v[86:87], v[52:53], v[96:97]
	v_and_b32_e32 v83, 0xffff0000, v80
	v_pk_add_f32 v[96:97], v[40:41], v[96:97]
	v_add_f32_e32 v35, 1.0, v35
	v_pk_mul_f32 v[74:75], v[96:97], v[74:75]
	v_rcp_f32_e32 v96, v35
	v_mul_f32_e32 v35, 0xbfb8aa3b, v83
	v_exp_f32_e32 v35, v35
	v_lshlrev_b32_e32 v80, 16, v81
	v_pk_mul_f32 v[74:75], v[78:79], v[74:75]
	v_lshlrev_b32_e32 v78, 16, v72
	v_add_f32_e32 v35, 1.0, v35
	v_rcp_f32_e32 v97, v35
	v_mul_f32_e32 v35, 0xbfb8aa3b, v80
	v_cvt_pk_bf16_f32 v71, v74, v75
	v_lshlrev_b32_e32 v74, 16, v76
	v_and_b32_e32 v75, 0xffff0000, v76
	v_and_b32_e32 v79, 0xffff0000, v72
	v_exp_f32_e32 v35, v35
	v_pk_mul_f32 v[78:79], v[74:75], v[78:79]
	v_pk_fma_f32 v[102:103], v[102:103], v[12:13], v[104:105]
	v_lshlrev_b32_e32 v74, 16, v84
	v_pk_fma_f32 v[102:103], v[78:79], v[20:21], v[102:103]
	v_and_b32_e32 v75, 0xffff0000, v84
	v_pk_add_f32 v[102:103], v[8:9], v[102:103]
	v_pk_mul_f32 v[82:83], v[96:97], v[82:83]
	v_pk_mul_f32 v[74:75], v[102:103], v[74:75]
	v_and_b32_e32 v81, 0xffff0000, v81
	v_add_f32_e32 v35, 1.0, v35
	v_pk_mul_f32 v[74:75], v[82:83], v[74:75]
	v_rcp_f32_e32 v82, v35
	v_mul_f32_e32 v35, 0xbfb8aa3b, v81
	v_exp_f32_e32 v35, v35
	v_cvt_pk_bf16_f32 v72, v74, v75
	v_lshlrev_b32_e32 v74, 16, v77
	v_and_b32_e32 v75, 0xffff0000, v77
	v_lshlrev_b32_e32 v76, 16, v73
	v_and_b32_e32 v77, 0xffff0000, v73
	v_add_f32_e32 v35, 1.0, v35
	v_pk_mul_f32 v[74:75], v[74:75], v[76:77]
	v_lshlrev_b32_e32 v76, 16, v85
	v_and_b32_e32 v77, 0xffff0000, v85
	v_pk_mul_f32 v[84:85], v[92:93], v[18:19]
	v_rcp_f32_e32 v83, v35
	v_pk_fma_f32 v[84:85], v[100:101], v[14:15], v[84:85]
	v_or_b32_e32 v35, 1, v34
	v_pk_fma_f32 v[84:85], v[74:75], v[22:23], v[84:85]
	v_pk_mul_f32 v[80:81], v[82:83], v[80:81]
	v_pk_add_f32 v[84:85], v[10:11], v[84:85]
	v_pk_mul_f32 v[82:83], v[88:89], v[46:47]
	v_pk_mul_f32 v[76:77], v[84:85], v[76:77]
	v_pk_fma_f32 v[82:83], v[116:117], v[42:43], v[82:83]
	v_pk_mul_f32 v[76:77], v[80:81], v[76:77]
	s_mov_b32 s94, s18
	v_cvt_pk_bf16_f32 v73, v76, v77
	v_mad_i64_i32 v[76:77], s[6:7], v35, s44, v[90:91]
	v_lshl_add_u64 v[76:77], v[76:77], 0, v[32:33]
	v_add_co_u32_e32 v76, vcc, s0, v76
	s_nop 1
	v_addc_co_u32_e32 v77, vcc, 0, v77, vcc
	global_store_dwordx4 v[76:77], v[70:73], off offset:1024 nt
	v_lshlrev_b32_e32 v76, 16, v62
	v_mul_f32_e32 v35, 0xbfb8aa3b, v76
	v_exp_f32_e32 v35, v35
	v_and_b32_e32 v77, 0xffff0000, v62
	v_lshlrev_b32_e32 v62, 16, v63
	v_lshlrev_b32_e32 v70, 16, v58
	v_add_f32_e32 v35, 1.0, v35
	v_rcp_f32_e32 v80, v35
	v_mul_f32_e32 v35, 0xbfb8aa3b, v77
	v_exp_f32_e32 v35, v35
	v_and_b32_e32 v71, 0xffff0000, v58
	v_lshlrev_b32_e32 v72, 16, v54
	v_and_b32_e32 v73, 0xffff0000, v54
	v_add_f32_e32 v35, 1.0, v35
	v_rcp_f32_e32 v81, v35
	v_mul_f32_e32 v35, 0xbfb8aa3b, v62
	v_exp_f32_e32 v35, v35
	v_and_b32_e32 v63, 0xffff0000, v63
	v_pk_mul_f32 v[72:73], v[70:71], v[72:73]
	v_lshlrev_b32_e32 v70, 16, v66
	v_add_f32_e32 v35, 1.0, v35
	v_and_b32_e32 v71, 0xffff0000, v66
	v_rcp_f32_e32 v66, v35
	v_mul_f32_e32 v35, 0xbfb8aa3b, v63
	v_pk_fma_f32 v[82:83], v[72:73], v[50:51], v[82:83]
	v_exp_f32_e32 v35, v35
	v_pk_add_f32 v[82:83], v[38:39], v[82:83]
	v_pk_mul_f32 v[76:77], v[80:81], v[76:77]
	v_pk_mul_f32 v[70:71], v[82:83], v[70:71]
	v_lshlrev_b32_e32 v58, 16, v59
	v_pk_mul_f32 v[70:71], v[76:77], v[70:71]
	v_and_b32_e32 v59, 0xffff0000, v59
	v_cvt_pk_bf16_f32 v54, v70, v71
	v_lshlrev_b32_e32 v70, 16, v55
	v_and_b32_e32 v71, 0xffff0000, v55
	v_add_f32_e32 v35, 1.0, v35
	v_pk_mul_f32 v[70:71], v[58:59], v[70:71]
	v_lshlrev_b32_e32 v58, 16, v67
	v_and_b32_e32 v59, 0xffff0000, v67
	v_rcp_f32_e32 v67, v35
	v_pk_mul_f32 v[76:77], v[86:87], v[48:49]
	v_pk_mul_f32 v[80:81], v[78:79], v[16:17]
	v_pk_fma_f32 v[76:77], v[94:95], v[44:45], v[76:77]
	v_pk_mul_f32 v[62:63], v[66:67], v[62:63]
	v_lshlrev_b32_e32 v66, 16, v64
	v_mul_f32_e32 v35, 0xbfb8aa3b, v66
	v_exp_f32_e32 v35, v35
	v_pk_fma_f32 v[76:77], v[70:71], v[52:53], v[76:77]
	v_and_b32_e32 v67, 0xffff0000, v64
	v_pk_add_f32 v[76:77], v[40:41], v[76:77]
	v_add_f32_e32 v35, 1.0, v35
	v_pk_mul_f32 v[58:59], v[76:77], v[58:59]
	v_rcp_f32_e32 v76, v35
	v_mul_f32_e32 v35, 0xbfb8aa3b, v67
	v_exp_f32_e32 v35, v35
	v_lshlrev_b32_e32 v64, 16, v65
	v_pk_mul_f32 v[58:59], v[62:63], v[58:59]
	v_lshlrev_b32_e32 v62, 16, v56
	v_add_f32_e32 v35, 1.0, v35
	v_rcp_f32_e32 v77, v35
	v_mul_f32_e32 v35, 0xbfb8aa3b, v64
	v_cvt_pk_bf16_f32 v55, v58, v59
	v_lshlrev_b32_e32 v58, 16, v60
	v_and_b32_e32 v59, 0xffff0000, v60
	v_and_b32_e32 v63, 0xffff0000, v56
	v_exp_f32_e32 v35, v35
	v_pk_mul_f32 v[62:63], v[58:59], v[62:63]
	v_pk_fma_f32 v[80:81], v[98:99], v[12:13], v[80:81]
	v_lshlrev_b32_e32 v58, 16, v68
	v_pk_fma_f32 v[80:81], v[62:63], v[20:21], v[80:81]
	v_and_b32_e32 v59, 0xffff0000, v68
	v_pk_add_f32 v[80:81], v[8:9], v[80:81]
	v_pk_mul_f32 v[66:67], v[76:77], v[66:67]
	v_pk_mul_f32 v[58:59], v[80:81], v[58:59]
	v_and_b32_e32 v65, 0xffff0000, v65
	v_add_f32_e32 v35, 1.0, v35
	v_pk_mul_f32 v[58:59], v[66:67], v[58:59]
	v_rcp_f32_e32 v66, v35
	v_mul_f32_e32 v35, 0xbfb8aa3b, v65
	v_exp_f32_e32 v35, v35
	v_cvt_pk_bf16_f32 v56, v58, v59
	v_lshlrev_b32_e32 v58, 16, v61
	v_and_b32_e32 v59, 0xffff0000, v61
	v_lshlrev_b32_e32 v60, 16, v57
	v_and_b32_e32 v61, 0xffff0000, v57
	v_add_f32_e32 v35, 1.0, v35
	v_pk_mul_f32 v[58:59], v[58:59], v[60:61]
	v_lshlrev_b32_e32 v60, 16, v69
	v_and_b32_e32 v61, 0xffff0000, v69
	v_pk_mul_f32 v[68:69], v[74:75], v[18:19]
	v_rcp_f32_e32 v67, v35
	v_pk_fma_f32 v[68:69], v[92:93], v[14:15], v[68:69]
	v_or_b32_e32 v35, 2, v34
	v_pk_fma_f32 v[68:69], v[58:59], v[22:23], v[68:69]
	v_pk_mul_f32 v[64:65], v[66:67], v[64:65]
	v_pk_add_f32 v[68:69], v[10:11], v[68:69]
	v_pk_mul_f32 v[46:47], v[72:73], v[46:47]
	v_pk_mul_f32 v[60:61], v[68:69], v[60:61]
	v_pk_fma_f32 v[42:43], v[88:89], v[42:43], v[46:47]
	v_pk_mul_f32 v[60:61], v[64:65], v[60:61]
	v_pk_mul_f32 v[16:17], v[62:63], v[16:17]
	v_cvt_pk_bf16_f32 v57, v60, v61
	v_mad_i64_i32 v[60:61], s[6:7], v35, s44, v[90:91]
	v_lshl_add_u64 v[60:61], v[60:61], 0, v[32:33]
	v_add_co_u32_e32 v60, vcc, s0, v60
	v_pk_fma_f32 v[12:13], v[78:79], v[12:13], v[16:17]
	s_nop 0
	v_addc_co_u32_e32 v61, vcc, 0, v61, vcc
	global_store_dwordx4 v[60:61], v[54:57], off offset:1024 nt
	v_lshlrev_b32_e32 v60, 16, v24
	v_and_b32_e32 v61, 0xffff0000, v24
	v_lshlrev_b32_e32 v56, 16, v0
	v_and_b32_e32 v57, 0xffff0000, v0
	v_mul_f32_e32 v0, 0xbfb8aa3b, v60
	v_exp_f32_e32 v0, v0
	v_lshlrev_b32_e32 v54, 16, v4
	v_and_b32_e32 v55, 0xffff0000, v4
	v_pk_mul_f32 v[54:55], v[114:115], v[54:55] op_sel_hi:[0,1]
	v_add_f32_e32 v0, 1.0, v0
	v_rcp_f32_e32 v64, v0
	v_mul_f32_e32 v0, 0xbfb8aa3b, v61
	v_exp_f32_e32 v0, v0
	v_pk_mul_f32 v[54:55], v[54:55], v[56:57]
	v_lshlrev_b32_e32 v56, 16, v28
	v_pk_fma_f32 v[42:43], v[54:55], v[50:51], v[42:43]
	v_add_f32_e32 v0, 1.0, v0
	v_rcp_f32_e32 v65, v0
	v_and_b32_e32 v57, 0xffff0000, v28
	v_pk_add_f32 v[38:39], v[38:39], v[42:43]
	v_lshlrev_b32_e32 v24, 16, v25
	v_pk_mul_f32 v[38:39], v[38:39], v[56:57]
	v_pk_mul_f32 v[42:43], v[64:65], v[60:61]
	v_lshlrev_b32_e32 v4, 16, v5
	v_pk_mul_f32 v[38:39], v[42:43], v[38:39]
	v_and_b32_e32 v5, 0xffff0000, v5
	v_cvt_pk_bf16_f32 v0, v38, v39
	v_lshlrev_b32_e32 v38, 16, v1
	v_and_b32_e32 v39, 0xffff0000, v1
	v_mul_f32_e32 v1, 0xbfb8aa3b, v24
	v_exp_f32_e32 v1, v1
	v_pk_mul_f32 v[4:5], v[114:115], v[4:5] op_sel_hi:[0,1]
	v_and_b32_e32 v25, 0xffff0000, v25
	v_pk_mul_f32 v[4:5], v[4:5], v[38:39]
	v_add_f32_e32 v1, 1.0, v1
	v_rcp_f32_e32 v38, v1
	v_mul_f32_e32 v1, 0xbfb8aa3b, v25
	v_exp_f32_e32 v1, v1
	v_pk_mul_f32 v[42:43], v[70:71], v[48:49]
	v_lshlrev_b32_e32 v28, 16, v29
	v_pk_fma_f32 v[42:43], v[86:87], v[44:45], v[42:43]
	v_add_f32_e32 v1, 1.0, v1
	v_rcp_f32_e32 v39, v1
	v_pk_fma_f32 v[4:5], v[4:5], v[52:53], v[42:43]
	v_and_b32_e32 v29, 0xffff0000, v29
	v_pk_add_f32 v[4:5], v[40:41], v[4:5]
	v_pk_mul_f32 v[24:25], v[38:39], v[24:25]
	v_pk_mul_f32 v[4:5], v[4:5], v[28:29]
	v_lshlrev_b32_e32 v28, 16, v26
	v_pk_mul_f32 v[4:5], v[24:25], v[4:5]
	v_lshlrev_b32_e32 v24, 16, v2
	v_and_b32_e32 v25, 0xffff0000, v2
	v_mul_f32_e32 v2, 0xbfb8aa3b, v28
	v_exp_f32_e32 v2, v2
	v_and_b32_e32 v29, 0xffff0000, v26
	v_cvt_pk_bf16_f32 v1, v4, v5
	v_lshlrev_b32_e32 v4, 16, v6
	v_add_f32_e32 v2, 1.0, v2
	v_rcp_f32_e32 v38, v2
	v_mul_f32_e32 v2, 0xbfb8aa3b, v29
	v_exp_f32_e32 v2, v2
	v_and_b32_e32 v5, 0xffff0000, v6
	v_pk_mul_f32 v[4:5], v[114:115], v[4:5] op_sel_hi:[0,1]
	v_pk_mul_f32 v[4:5], v[4:5], v[24:25]
	v_add_f32_e32 v2, 1.0, v2
	v_rcp_f32_e32 v39, v2
	v_pk_fma_f32 v[4:5], v[4:5], v[20:21], v[12:13]
	v_lshlrev_b32_e32 v24, 16, v30
	v_and_b32_e32 v25, 0xffff0000, v30
	v_pk_add_f32 v[4:5], v[8:9], v[4:5]
	v_pk_mul_f32 v[8:9], v[38:39], v[28:29]
	v_pk_mul_f32 v[4:5], v[4:5], v[24:25]
	v_lshlrev_b32_e32 v6, 16, v3
	v_pk_mul_f32 v[4:5], v[8:9], v[4:5]
	v_lshlrev_b32_e32 v8, 16, v27
	v_cvt_pk_bf16_f32 v2, v4, v5
	v_lshlrev_b32_e32 v4, 16, v7
	v_and_b32_e32 v5, 0xffff0000, v7
	v_and_b32_e32 v7, 0xffff0000, v3
	v_mul_f32_e32 v3, 0xbfb8aa3b, v8
	v_exp_f32_e32 v3, v3
	v_and_b32_e32 v9, 0xffff0000, v27
	v_pk_mul_f32 v[4:5], v[114:115], v[4:5] op_sel_hi:[0,1]
	v_pk_mul_f32 v[16:17], v[58:59], v[18:19]
	v_add_f32_e32 v3, 1.0, v3
	v_rcp_f32_e32 v12, v3
	v_mul_f32_e32 v3, 0xbfb8aa3b, v9
	v_exp_f32_e32 v3, v3
	v_pk_mul_f32 v[4:5], v[4:5], v[6:7]
	v_pk_fma_f32 v[14:15], v[74:75], v[14:15], v[16:17]
	v_lshlrev_b32_e32 v6, 16, v31
	v_add_f32_e32 v3, 1.0, v3
	v_rcp_f32_e32 v13, v3
	v_pk_fma_f32 v[4:5], v[4:5], v[22:23], v[14:15]
	v_and_b32_e32 v7, 0xffff0000, v31
	v_pk_add_f32 v[4:5], v[10:11], v[4:5]
	s_nop 0
	v_pk_mul_f32 v[4:5], v[4:5], v[6:7]
	v_pk_mul_f32 v[6:7], v[12:13], v[8:9]
	s_nop 0
	v_pk_mul_f32 v[4:5], v[6:7], v[4:5]
	s_nop 0
	v_cvt_pk_bf16_f32 v3, v4, v5
	v_or_b32_e32 v4, 3, v34
	v_mad_i64_i32 v[4:5], s[6:7], v4, s44, v[90:91]
	v_lshl_add_u64 v[4:5], v[4:5], 0, v[32:33]
	v_add_co_u32_e32 v4, vcc, 0x18c00000, v4
	s_nop 1
	v_addc_co_u32_e32 v5, vcc, 0, v5, vcc
	global_store_dwordx4 v[4:5], v[0:3], off offset:1024 nt

.LBB0_656:
	s_andn2_b64 vcc, exec, s[6:7]
	s_cbranch_vccnz .LBB0_661
	s_cmp_lg_u32 s16, 1
	s_mov_b64 s[10:11], -1
	s_cbranch_scc1 .LBB0_659
	v_ashrrev_i32_e32 v0, 3, v206
	v_and_b32_e32 v0, -4, v0
	v_lshl_add_u32 v34, s13, 6, v0
	v_lshlrev_b32_e32 v0, 3, v206
	s_movk_i32 s10, 0x4000
	v_and_b32_e32 v18, 0xf8, v0
	v_cmp_gt_i32_e32 vcc, s10, v34
	v_bfrev_b32_e32 v0, 0.5
	v_mov_b32_e32 v1, 0xffc
	v_cndmask_b32_e32 v0, v0, v1, vcc
	v_ashrrev_i32_e32 v35, 31, v34
	v_and_b32_e32 v2, v0, v34
	v_lshlrev_b64 v[0:1], 13, v[34:35]
	v_lshl_add_u64 v[0:1], s[70:71], 0, v[0:1]
	v_lshlrev_b32_e32 v32, 1, v18
	v_lshl_add_u64 v[8:9], v[0:1], 0, v[32:33]
	s_movk_i32 s0, 0x2000
	v_add_co_u32_e64 v10, s[8:9], s0, v8
	v_cmp_ne_u32_e64 s[6:7], 0, v2
	s_nop 0
	v_addc_co_u32_e64 v11, s[8:9], 0, v9, s[8:9]
	v_cndmask_b32_e64 v0, 0, -1, s[6:7]
	v_add_co_u32_e64 v12, s[8:9], s10, v8
	v_mov_b32_e32 v1, v0
	s_nop 0
	v_addc_co_u32_e64 v13, s[8:9], 0, v9, s[8:9]
	s_movk_i32 s0, 0x6000
	v_lshlrev_b64 v[0:1], 13, v[0:1]
	v_add_co_u32_e64 v14, s[8:9], s0, v8
	v_lshl_add_u64 v[0:1], v[8:9], 0, v[0:1]
	s_nop 0
	v_addc_co_u32_e64 v15, s[8:9], 0, v9, s[8:9]
	v_cndmask_b32_e64 v122, 0, 1.0, s[6:7]
	s_lshl_b32 s6, s5, 8
	global_load_dwordx4 v[116:119], v[0:1], off offset:2560
	global_load_dwordx4 v[98:101], v[0:1], off offset:3584
	global_load_dwordx4 v[86:89], v[8:9], off offset:2560
	global_load_dwordx4 v[90:93], v[8:9], off offset:3584
	v_or_b32_e32 v0, 3, v2
	v_mov_b32_e32 v1, 0xff
	v_mov_b32_e32 v2, 0xfff
	s_ashr_i32 s7, s6, 31
	s_mul_i32 s8, s5, 0x300
	v_cndmask_b32_e32 v1, v1, v2, vcc
	s_ashr_i32 s9, s8, 31
	s_lshl_b64 s[6:7], s[6:7], 2
	v_cmp_lt_u32_e32 vcc, v0, v1
	v_mov_b32_e32 v0, 0x6000
	v_mov_b32_e32 v1, 0x8000
	s_add_u32 s10, s40, s6
	s_movk_i32 s0, 0x1000
	v_cndmask_b32_e32 v0, v0, v1, vcc
	v_mov_b32_e32 v1, v33
	s_addc_u32 s11, s41, s7
	v_add_co_u32_e64 v16, s[6:7], s0, v8
	v_lshl_add_u64 v[0:1], v[8:9], 0, v[0:1]
	s_nop 0
	v_addc_co_u32_e64 v17, s[6:7], 0, v9, s[6:7]
	s_movk_i32 s0, 0x3000
	global_load_dwordx4 v[102:105], v[10:11], off offset:2560
	global_load_dwordx4 v[94:97], v[10:11], off offset:3584
	global_load_dwordx4 v[74:77], v[12:13], off offset:2560
	global_load_dwordx4 v[70:73], v[12:13], off offset:3584
	global_load_dwordx4 v[58:61], v[14:15], off offset:2560
	global_load_dwordx4 v[54:57], v[14:15], off offset:3584
	global_load_dwordx4 v[4:7], v[0:1], off offset:2560
	s_nop 0
	global_load_dwordx4 v[0:3], v[0:1], off offset:3584
	v_lshlrev_b32_e32 v35, 2, v18
	global_load_dwordx4 v[110:113], v[8:9], off offset:3072
	global_load_dwordx4 v[106:109], v[16:17], off
	global_load_dwordx4 v[82:85], v[10:11], off offset:3072
	v_add_co_u32_e64 v10, s[6:7], s0, v8
	s_movk_i32 s0, 0x5000
	s_nop 0
	v_addc_co_u32_e64 v11, s[6:7], 0, v9, s[6:7]
	global_load_dwordx4 v[78:81], v[10:11], off
	global_load_dwordx4 v[66:69], v[12:13], off offset:3072
	v_add_co_u32_e64 v10, s[6:7], s0, v8
	s_movk_i32 s0, 0x7000
	s_nop 0
	v_addc_co_u32_e64 v11, s[6:7], 0, v9, s[6:7]
	v_add_co_u32_e64 v8, s[6:7], s0, v8
	global_load_dwordx4 v[62:65], v[10:11], off
	global_load_dwordx4 v[28:31], v[14:15], off offset:3072
	v_addc_co_u32_e64 v9, s[6:7], 0, v9, s[6:7]
	s_lshl_b64 s[6:7], s[8:9], 2
	s_add_u32 s6, s38, s6
	global_load_dwordx4 v[24:27], v[8:9], off
	s_addc_u32 s7, s39, s7
	global_load_dwordx4 v[8:11], v35, s[10:11] offset:16
	global_load_dwordx4 v[38:41], v35, s[10:11]
	global_load_dwordx4 v[12:15], v35, s[6:7] offset:16
	global_load_dwordx4 v[42:45], v35, s[6:7]
	global_load_dwordx4 v[16:19], v35, s[6:7] offset:1040
	global_load_dwordx4 v[46:49], v35, s[6:7] offset:1024
	global_load_dwordx4 v[20:23], v35, s[6:7] offset:2064
	global_load_dwordx4 v[50:53], v35, s[6:7] offset:2048
	v_cndmask_b32_e64 v114, 0, 1.0, vcc
	s_waitcnt vmcnt(14)
	v_lshlrev_b32_e32 v132, 16, v106
	v_mul_f32_e32 v35, 0xbfb8aa3b, v132
	v_exp_f32_e32 v35, v35
	v_and_b32_e32 v133, 0xffff0000, v106
	v_lshlrev_b32_e32 v120, 16, v116
	v_and_b32_e32 v121, 0xffff0000, v116
	v_add_f32_e32 v35, 1.0, v35
	v_rcp_f32_e32 v134, v35
	v_mul_f32_e32 v35, 0xbfb8aa3b, v133
	v_exp_f32_e32 v35, v35
	v_lshlrev_b32_e32 v128, 16, v117
	v_and_b32_e32 v129, 0xffff0000, v117
	v_lshlrev_b32_e32 v126, 16, v118
	v_and_b32_e32 v127, 0xffff0000, v118
	v_lshlrev_b32_e32 v124, 16, v119
	v_and_b32_e32 v125, 0xffff0000, v119
	v_lshlrev_b32_e32 v116, 16, v98
	v_and_b32_e32 v117, 0xffff0000, v98
	v_pk_mul_f32 v[118:119], v[122:123], v[120:121] op_sel_hi:[0,1]
	v_pk_mul_f32 v[120:121], v[118:119], v[116:117]
	v_lshlrev_b32_e32 v116, 16, v86
	v_and_b32_e32 v117, 0xffff0000, v86
	v_lshlrev_b32_e32 v118, 16, v90
	v_and_b32_e32 v119, 0xffff0000, v90
	v_pk_mul_f32 v[118:119], v[116:117], v[118:119]
	v_add_f32_e32 v35, 1.0, v35
	v_lshlrev_b32_e32 v116, 16, v102
	v_and_b32_e32 v117, 0xffff0000, v102
	v_lshlrev_b32_e32 v130, 16, v94
	v_and_b32_e32 v131, 0xffff0000, v94
	s_waitcnt vmcnt(2)
	v_pk_mul_f32 v[136:137], v[118:119], v[46:47]
	v_rcp_f32_e32 v135, v35
	v_pk_mul_f32 v[116:117], v[116:117], v[130:131]
	v_pk_fma_f32 v[120:121], v[120:121], v[42:43], v[136:137]
	v_lshlrev_b32_e32 v102, 16, v107
	s_waitcnt vmcnt(0)
	v_pk_fma_f32 v[120:121], v[116:117], v[50:51], v[120:121]
	v_lshlrev_b32_e32 v130, 16, v110
	v_and_b32_e32 v131, 0xffff0000, v110
	v_pk_add_f32 v[120:121], v[38:39], v[120:121]
	v_mul_f32_e32 v35, 0xbfb8aa3b, v102
	v_pk_mul_f32 v[120:121], v[120:121], v[130:131]
	v_pk_mul_f32 v[130:131], v[134:135], v[132:133]
	v_exp_f32_e32 v35, v35
	v_pk_mul_f32 v[120:121], v[130:131], v[120:121]
	v_lshlrev_b32_e32 v98, 16, v99
	v_cvt_pk_bf16_f32 v86, v120, v121
	v_and_b32_e32 v99, 0xffff0000, v99
	v_pk_mul_f32 v[120:121], v[122:123], v[128:129] op_sel_hi:[0,1]
	v_pk_mul_f32 v[98:99], v[120:121], v[98:99]
	v_lshlrev_b32_e32 v120, 16, v87
	v_and_b32_e32 v121, 0xffff0000, v87
	v_lshlrev_b32_e32 v90, 16, v91
	v_and_b32_e32 v91, 0xffff0000, v91
	v_pk_mul_f32 v[120:121], v[120:121], v[90:91]
	v_lshlrev_b32_e32 v90, 16, v103
	v_and_b32_e32 v91, 0xffff0000, v103
	v_and_b32_e32 v103, 0xffff0000, v107
	v_add_f32_e32 v35, 1.0, v35
	v_rcp_f32_e32 v106, v35
	v_mul_f32_e32 v35, 0xbfb8aa3b, v103
	v_exp_f32_e32 v35, v35
	v_lshlrev_b32_e32 v94, 16, v95
	v_and_b32_e32 v95, 0xffff0000, v95
	v_pk_mul_f32 v[94:95], v[90:91], v[94:95]
	v_lshlrev_b32_e32 v90, 16, v111
	v_and_b32_e32 v91, 0xffff0000, v111
	v_pk_mul_f32 v[110:111], v[120:121], v[48:49]
	v_add_f32_e32 v35, 1.0, v35
	v_pk_fma_f32 v[98:99], v[98:99], v[44:45], v[110:111]
	v_lshlrev_b32_e32 v110, 16, v108
	v_rcp_f32_e32 v107, v35
	v_mul_f32_e32 v35, 0xbfb8aa3b, v110
	v_exp_f32_e32 v35, v35
	v_pk_fma_f32 v[98:99], v[94:95], v[52:53], v[98:99]
	v_and_b32_e32 v111, 0xffff0000, v108
	v_pk_add_f32 v[98:99], v[40:41], v[98:99]
	v_add_f32_e32 v35, 1.0, v35
	v_pk_mul_f32 v[90:91], v[98:99], v[90:91]
	v_pk_mul_f32 v[98:99], v[106:107], v[102:103]
	v_lshlrev_b32_e32 v102, 16, v92
	v_pk_mul_f32 v[90:91], v[98:99], v[90:91]
	v_pk_mul_f32 v[98:99], v[122:123], v[126:127] op_sel_hi:[0,1]
	v_rcp_f32_e32 v126, v35
	v_mul_f32_e32 v35, 0xbfb8aa3b, v111
	v_exp_f32_e32 v35, v35
	v_cvt_pk_bf16_f32 v87, v90, v91
	v_lshlrev_b32_e32 v90, 16, v100
	v_and_b32_e32 v91, 0xffff0000, v100
	v_pk_mul_f32 v[90:91], v[98:99], v[90:91]
	v_lshlrev_b32_e32 v98, 16, v88
	v_and_b32_e32 v99, 0xffff0000, v88
	v_and_b32_e32 v103, 0xffff0000, v92
	v_pk_mul_f32 v[102:103], v[98:99], v[102:103]
	v_add_f32_e32 v35, 1.0, v35
	v_lshlrev_b32_e32 v98, 16, v104
	v_and_b32_e32 v99, 0xffff0000, v104
	v_lshlrev_b32_e32 v106, 16, v96
	v_and_b32_e32 v107, 0xffff0000, v96
	v_pk_mul_f32 v[128:129], v[102:103], v[16:17]
	v_rcp_f32_e32 v127, v35
	v_pk_mul_f32 v[98:99], v[98:99], v[106:107]
	v_pk_fma_f32 v[90:91], v[90:91], v[12:13], v[128:129]
	v_lshlrev_b32_e32 v104, 16, v109
	v_pk_fma_f32 v[90:91], v[98:99], v[20:21], v[90:91]
	v_lshlrev_b32_e32 v106, 16, v112
	v_and_b32_e32 v107, 0xffff0000, v112
	v_pk_add_f32 v[90:91], v[8:9], v[90:91]
	v_mul_f32_e32 v35, 0xbfb8aa3b, v104
	v_pk_mul_f32 v[90:91], v[90:91], v[106:107]
	v_pk_mul_f32 v[106:107], v[126:127], v[110:111]
	v_exp_f32_e32 v35, v35
	v_pk_mul_f32 v[90:91], v[106:107], v[90:91]
	v_lshlrev_b32_e32 v92, 16, v93
	v_cvt_pk_bf16_f32 v88, v90, v91
	v_lshlrev_b32_e32 v90, 16, v101
	v_and_b32_e32 v91, 0xffff0000, v101
	v_pk_mul_f32 v[100:101], v[122:123], v[124:125] op_sel_hi:[0,1]
	v_pk_mul_f32 v[90:91], v[100:101], v[90:91]
	v_lshlrev_b32_e32 v100, 16, v89
	v_and_b32_e32 v101, 0xffff0000, v89
	v_and_b32_e32 v93, 0xffff0000, v93
	v_pk_mul_f32 v[100:101], v[100:101], v[92:93]
	v_lshlrev_b32_e32 v92, 16, v105
	v_and_b32_e32 v93, 0xffff0000, v105
	v_and_b32_e32 v105, 0xffff0000, v109
	v_add_f32_e32 v35, 1.0, v35
	v_rcp_f32_e32 v106, v35
	v_mul_f32_e32 v35, 0xbfb8aa3b, v105
	v_exp_f32_e32 v35, v35
	v_lshlrev_b32_e32 v96, 16, v97
	v_and_b32_e32 v97, 0xffff0000, v97
	v_pk_mul_f32 v[108:109], v[100:101], v[18:19]
	v_add_f32_e32 v35, 1.0, v35
	v_rcp_f32_e32 v107, v35
	v_pk_mul_f32 v[92:93], v[92:93], v[96:97]
	v_pk_fma_f32 v[90:91], v[90:91], v[14:15], v[108:109]
	v_lshlrev_b32_e32 v96, 16, v113
	v_pk_fma_f32 v[90:91], v[92:93], v[22:23], v[90:91]
	v_and_b32_e32 v97, 0xffff0000, v113
	v_pk_add_f32 v[90:91], v[10:11], v[90:91]
	s_mov_b32 s0, 0x18c00000
	v_pk_mul_f32 v[90:91], v[90:91], v[96:97]
	v_pk_mul_f32 v[96:97], v[106:107], v[104:105]
	v_pk_mul_f32 v[106:107], v[116:117], v[46:47]
	v_pk_mul_f32 v[90:91], v[96:97], v[90:91]
	v_pk_fma_f32 v[106:107], v[118:119], v[42:43], v[106:107]
	v_cvt_pk_bf16_f32 v89, v90, v91
	v_mov_b64_e32 v[90:91], s[48:49]
	v_mad_i64_i32 v[96:97], s[6:7], v34, s44, v[90:91]
	v_lshl_add_u64 v[96:97], v[96:97], 0, v[32:33]
	v_add_co_u32_e32 v96, vcc, s0, v96
	s_mov_b64 s[10:11], 0
	s_nop 0
	v_addc_co_u32_e32 v97, vcc, 0, v97, vcc
	global_store_dwordx4 v[96:97], v[86:89], off offset:1024 nt
	v_lshlrev_b32_e32 v96, 16, v78
	v_mul_f32_e32 v35, 0xbfb8aa3b, v96
	v_exp_f32_e32 v35, v35
	v_and_b32_e32 v97, 0xffff0000, v78
	v_lshlrev_b32_e32 v78, 16, v79
	v_lshlrev_b32_e32 v86, 16, v74
	v_add_f32_e32 v35, 1.0, v35
	v_rcp_f32_e32 v104, v35
	v_mul_f32_e32 v35, 0xbfb8aa3b, v97
	v_exp_f32_e32 v35, v35
	v_and_b32_e32 v87, 0xffff0000, v74
	v_lshlrev_b32_e32 v88, 16, v70
	v_and_b32_e32 v89, 0xffff0000, v70
	v_add_f32_e32 v35, 1.0, v35
	v_rcp_f32_e32 v105, v35
	v_mul_f32_e32 v35, 0xbfb8aa3b, v78
	v_exp_f32_e32 v35, v35
	v_and_b32_e32 v79, 0xffff0000, v79
	v_pk_mul_f32 v[88:89], v[86:87], v[88:89]
	v_lshlrev_b32_e32 v86, 16, v82
	v_add_f32_e32 v35, 1.0, v35
	v_and_b32_e32 v87, 0xffff0000, v82
	v_rcp_f32_e32 v82, v35
	v_mul_f32_e32 v35, 0xbfb8aa3b, v79
	v_pk_fma_f32 v[106:107], v[88:89], v[50:51], v[106:107]
	v_exp_f32_e32 v35, v35
	v_pk_add_f32 v[106:107], v[38:39], v[106:107]
	v_pk_mul_f32 v[96:97], v[104:105], v[96:97]
	v_pk_mul_f32 v[86:87], v[106:107], v[86:87]
	v_lshlrev_b32_e32 v74, 16, v75
	v_pk_mul_f32 v[86:87], v[96:97], v[86:87]
	v_and_b32_e32 v75, 0xffff0000, v75
	v_cvt_pk_bf16_f32 v70, v86, v87
	v_lshlrev_b32_e32 v86, 16, v71
	v_and_b32_e32 v87, 0xffff0000, v71
	v_add_f32_e32 v35, 1.0, v35
	v_pk_mul_f32 v[86:87], v[74:75], v[86:87]
	v_lshlrev_b32_e32 v74, 16, v83
	v_and_b32_e32 v75, 0xffff0000, v83
	v_rcp_f32_e32 v83, v35
	v_pk_mul_f32 v[96:97], v[94:95], v[48:49]
	v_pk_mul_f32 v[104:105], v[98:99], v[16:17]
	v_pk_fma_f32 v[96:97], v[120:121], v[44:45], v[96:97]
	v_pk_mul_f32 v[78:79], v[82:83], v[78:79]
	v_lshlrev_b32_e32 v82, 16, v80
	v_mul_f32_e32 v35, 0xbfb8aa3b, v82
	v_exp_f32_e32 v35, v35
	v_pk_fma_f32 v[96:97], v[86:87], v[52:53], v[96:97]
	v_and_b32_e32 v83, 0xffff0000, v80
	v_pk_add_f32 v[96:97], v[40:41], v[96:97]
	v_add_f32_e32 v35, 1.0, v35
	v_pk_mul_f32 v[74:75], v[96:97], v[74:75]
	v_rcp_f32_e32 v96, v35
	v_mul_f32_e32 v35, 0xbfb8aa3b, v83
	v_exp_f32_e32 v35, v35
	v_lshlrev_b32_e32 v80, 16, v81
	v_pk_mul_f32 v[74:75], v[78:79], v[74:75]
	v_lshlrev_b32_e32 v78, 16, v72
	v_add_f32_e32 v35, 1.0, v35
	v_rcp_f32_e32 v97, v35
	v_mul_f32_e32 v35, 0xbfb8aa3b, v80
	v_cvt_pk_bf16_f32 v71, v74, v75
	v_lshlrev_b32_e32 v74, 16, v76
	v_and_b32_e32 v75, 0xffff0000, v76
	v_and_b32_e32 v79, 0xffff0000, v72
	v_exp_f32_e32 v35, v35
	v_pk_mul_f32 v[78:79], v[74:75], v[78:79]
	v_pk_fma_f32 v[102:103], v[102:103], v[12:13], v[104:105]
	v_lshlrev_b32_e32 v74, 16, v84
	v_pk_fma_f32 v[102:103], v[78:79], v[20:21], v[102:103]
	v_and_b32_e32 v75, 0xffff0000, v84
	v_pk_add_f32 v[102:103], v[8:9], v[102:103]
	v_pk_mul_f32 v[82:83], v[96:97], v[82:83]
	v_pk_mul_f32 v[74:75], v[102:103], v[74:75]
	v_and_b32_e32 v81, 0xffff0000, v81
	v_add_f32_e32 v35, 1.0, v35
	v_pk_mul_f32 v[74:75], v[82:83], v[74:75]
	v_rcp_f32_e32 v82, v35
	v_mul_f32_e32 v35, 0xbfb8aa3b, v81
	v_exp_f32_e32 v35, v35
	v_cvt_pk_bf16_f32 v72, v74, v75
	v_lshlrev_b32_e32 v74, 16, v77
	v_and_b32_e32 v75, 0xffff0000, v77
	v_lshlrev_b32_e32 v76, 16, v73
	v_and_b32_e32 v77, 0xffff0000, v73
	v_add_f32_e32 v35, 1.0, v35
	v_pk_mul_f32 v[74:75], v[74:75], v[76:77]
	v_lshlrev_b32_e32 v76, 16, v85
	v_and_b32_e32 v77, 0xffff0000, v85
	v_pk_mul_f32 v[84:85], v[92:93], v[18:19]
	v_rcp_f32_e32 v83, v35
	v_pk_fma_f32 v[84:85], v[100:101], v[14:15], v[84:85]
	v_or_b32_e32 v35, 1, v34
	v_pk_fma_f32 v[84:85], v[74:75], v[22:23], v[84:85]
	v_pk_mul_f32 v[80:81], v[82:83], v[80:81]
	v_pk_add_f32 v[84:85], v[10:11], v[84:85]
	v_pk_mul_f32 v[82:83], v[88:89], v[46:47]
	v_pk_mul_f32 v[76:77], v[84:85], v[76:77]
	v_pk_fma_f32 v[82:83], v[116:117], v[42:43], v[82:83]
	v_pk_mul_f32 v[76:77], v[80:81], v[76:77]
	s_nop 0
	v_cvt_pk_bf16_f32 v73, v76, v77
	v_mad_i64_i32 v[76:77], s[6:7], v35, s44, v[90:91]
	v_lshl_add_u64 v[76:77], v[76:77], 0, v[32:33]
	v_add_co_u32_e32 v76, vcc, s0, v76
	s_nop 1
	v_addc_co_u32_e32 v77, vcc, 0, v77, vcc
	global_store_dwordx4 v[76:77], v[70:73], off offset:1024 nt
	v_lshlrev_b32_e32 v76, 16, v62
	v_mul_f32_e32 v35, 0xbfb8aa3b, v76
	v_exp_f32_e32 v35, v35
	v_and_b32_e32 v77, 0xffff0000, v62
	v_lshlrev_b32_e32 v62, 16, v63
	v_lshlrev_b32_e32 v70, 16, v58
	v_add_f32_e32 v35, 1.0, v35
	v_rcp_f32_e32 v80, v35
	v_mul_f32_e32 v35, 0xbfb8aa3b, v77
	v_exp_f32_e32 v35, v35
	v_and_b32_e32 v71, 0xffff0000, v58
	v_lshlrev_b32_e32 v72, 16, v54
	v_and_b32_e32 v73, 0xffff0000, v54
	v_add_f32_e32 v35, 1.0, v35
	v_rcp_f32_e32 v81, v35
	v_mul_f32_e32 v35, 0xbfb8aa3b, v62
	v_exp_f32_e32 v35, v35
	v_and_b32_e32 v63, 0xffff0000, v63
	v_pk_mul_f32 v[72:73], v[70:71], v[72:73]
	v_lshlrev_b32_e32 v70, 16, v66
	v_add_f32_e32 v35, 1.0, v35
	v_and_b32_e32 v71, 0xffff0000, v66
	v_rcp_f32_e32 v66, v35
	v_mul_f32_e32 v35, 0xbfb8aa3b, v63
	v_pk_fma_f32 v[82:83], v[72:73], v[50:51], v[82:83]
	v_exp_f32_e32 v35, v35
	v_pk_add_f32 v[82:83], v[38:39], v[82:83]
	v_pk_mul_f32 v[76:77], v[80:81], v[76:77]
	v_pk_mul_f32 v[70:71], v[82:83], v[70:71]
	v_lshlrev_b32_e32 v58, 16, v59
	v_pk_mul_f32 v[70:71], v[76:77], v[70:71]
	v_and_b32_e32 v59, 0xffff0000, v59
	v_cvt_pk_bf16_f32 v54, v70, v71
	v_lshlrev_b32_e32 v70, 16, v55
	v_and_b32_e32 v71, 0xffff0000, v55
	v_add_f32_e32 v35, 1.0, v35
	v_pk_mul_f32 v[70:71], v[58:59], v[70:71]
	v_lshlrev_b32_e32 v58, 16, v67
	v_and_b32_e32 v59, 0xffff0000, v67
	v_rcp_f32_e32 v67, v35
	v_pk_mul_f32 v[76:77], v[86:87], v[48:49]
	v_pk_mul_f32 v[80:81], v[78:79], v[16:17]
	v_pk_fma_f32 v[76:77], v[94:95], v[44:45], v[76:77]
	v_pk_mul_f32 v[62:63], v[66:67], v[62:63]
	v_lshlrev_b32_e32 v66, 16, v64
	v_mul_f32_e32 v35, 0xbfb8aa3b, v66
	v_exp_f32_e32 v35, v35
	v_pk_fma_f32 v[76:77], v[70:71], v[52:53], v[76:77]
	v_and_b32_e32 v67, 0xffff0000, v64
	v_pk_add_f32 v[76:77], v[40:41], v[76:77]
	v_add_f32_e32 v35, 1.0, v35
	v_pk_mul_f32 v[58:59], v[76:77], v[58:59]
	v_rcp_f32_e32 v76, v35
	v_mul_f32_e32 v35, 0xbfb8aa3b, v67
	v_exp_f32_e32 v35, v35
	v_lshlrev_b32_e32 v64, 16, v65
	v_pk_mul_f32 v[58:59], v[62:63], v[58:59]
	v_lshlrev_b32_e32 v62, 16, v56
	v_add_f32_e32 v35, 1.0, v35
	v_rcp_f32_e32 v77, v35
	v_mul_f32_e32 v35, 0xbfb8aa3b, v64
	v_cvt_pk_bf16_f32 v55, v58, v59
	v_lshlrev_b32_e32 v58, 16, v60
	v_and_b32_e32 v59, 0xffff0000, v60
	v_and_b32_e32 v63, 0xffff0000, v56
	v_exp_f32_e32 v35, v35
	v_pk_mul_f32 v[62:63], v[58:59], v[62:63]
	v_pk_fma_f32 v[80:81], v[98:99], v[12:13], v[80:81]
	v_lshlrev_b32_e32 v58, 16, v68
	v_pk_fma_f32 v[80:81], v[62:63], v[20:21], v[80:81]
	v_and_b32_e32 v59, 0xffff0000, v68
	v_pk_add_f32 v[80:81], v[8:9], v[80:81]
	v_pk_mul_f32 v[66:67], v[76:77], v[66:67]
	v_pk_mul_f32 v[58:59], v[80:81], v[58:59]
	v_and_b32_e32 v65, 0xffff0000, v65
	v_add_f32_e32 v35, 1.0, v35
	v_pk_mul_f32 v[58:59], v[66:67], v[58:59]
	v_rcp_f32_e32 v66, v35
	v_mul_f32_e32 v35, 0xbfb8aa3b, v65
	v_exp_f32_e32 v35, v35
	v_cvt_pk_bf16_f32 v56, v58, v59
	v_lshlrev_b32_e32 v58, 16, v61
	v_and_b32_e32 v59, 0xffff0000, v61
	v_lshlrev_b32_e32 v60, 16, v57
	v_and_b32_e32 v61, 0xffff0000, v57
	v_add_f32_e32 v35, 1.0, v35
	v_pk_mul_f32 v[58:59], v[58:59], v[60:61]
	v_lshlrev_b32_e32 v60, 16, v69
	v_and_b32_e32 v61, 0xffff0000, v69
	v_pk_mul_f32 v[68:69], v[74:75], v[18:19]
	v_rcp_f32_e32 v67, v35
	v_pk_fma_f32 v[68:69], v[92:93], v[14:15], v[68:69]
	v_or_b32_e32 v35, 2, v34
	v_pk_fma_f32 v[68:69], v[58:59], v[22:23], v[68:69]
	v_pk_mul_f32 v[64:65], v[66:67], v[64:65]
	v_pk_add_f32 v[68:69], v[10:11], v[68:69]
	v_pk_mul_f32 v[46:47], v[72:73], v[46:47]
	v_pk_mul_f32 v[60:61], v[68:69], v[60:61]
	v_pk_fma_f32 v[42:43], v[88:89], v[42:43], v[46:47]
	v_pk_mul_f32 v[60:61], v[64:65], v[60:61]
	v_pk_mul_f32 v[16:17], v[62:63], v[16:17]
	v_cvt_pk_bf16_f32 v57, v60, v61
	v_mad_i64_i32 v[60:61], s[6:7], v35, s44, v[90:91]
	v_lshl_add_u64 v[60:61], v[60:61], 0, v[32:33]
	v_add_co_u32_e32 v60, vcc, s0, v60
	v_pk_fma_f32 v[12:13], v[78:79], v[12:13], v[16:17]
	s_nop 0
	v_addc_co_u32_e32 v61, vcc, 0, v61, vcc
	global_store_dwordx4 v[60:61], v[54:57], off offset:1024 nt
	v_lshlrev_b32_e32 v60, 16, v24
	v_and_b32_e32 v61, 0xffff0000, v24
	v_lshlrev_b32_e32 v56, 16, v0
	v_and_b32_e32 v57, 0xffff0000, v0
	v_mul_f32_e32 v0, 0xbfb8aa3b, v60
	v_exp_f32_e32 v0, v0
	v_lshlrev_b32_e32 v54, 16, v4
	v_and_b32_e32 v55, 0xffff0000, v4
	v_pk_mul_f32 v[54:55], v[114:115], v[54:55] op_sel_hi:[0,1]
	v_add_f32_e32 v0, 1.0, v0
	v_rcp_f32_e32 v64, v0
	v_mul_f32_e32 v0, 0xbfb8aa3b, v61
	v_exp_f32_e32 v0, v0
	v_pk_mul_f32 v[54:55], v[54:55], v[56:57]
	v_lshlrev_b32_e32 v56, 16, v28
	v_pk_fma_f32 v[42:43], v[54:55], v[50:51], v[42:43]
	v_add_f32_e32 v0, 1.0, v0
	v_rcp_f32_e32 v65, v0
	v_and_b32_e32 v57, 0xffff0000, v28
	v_pk_add_f32 v[38:39], v[38:39], v[42:43]
	v_lshlrev_b32_e32 v24, 16, v25
	v_pk_mul_f32 v[38:39], v[38:39], v[56:57]
	v_pk_mul_f32 v[42:43], v[64:65], v[60:61]
	v_lshlrev_b32_e32 v4, 16, v5
	v_pk_mul_f32 v[38:39], v[42:43], v[38:39]
	v_and_b32_e32 v5, 0xffff0000, v5
	v_cvt_pk_bf16_f32 v0, v38, v39
	v_lshlrev_b32_e32 v38, 16, v1
	v_and_b32_e32 v39, 0xffff0000, v1
	v_mul_f32_e32 v1, 0xbfb8aa3b, v24
	v_exp_f32_e32 v1, v1
	v_pk_mul_f32 v[4:5], v[114:115], v[4:5] op_sel_hi:[0,1]
	v_and_b32_e32 v25, 0xffff0000, v25
	v_pk_mul_f32 v[4:5], v[4:5], v[38:39]
	v_add_f32_e32 v1, 1.0, v1
	v_rcp_f32_e32 v38, v1
	v_mul_f32_e32 v1, 0xbfb8aa3b, v25
	v_exp_f32_e32 v1, v1
	v_pk_mul_f32 v[42:43], v[70:71], v[48:49]
	v_lshlrev_b32_e32 v28, 16, v29
	v_pk_fma_f32 v[42:43], v[86:87], v[44:45], v[42:43]
	v_add_f32_e32 v1, 1.0, v1
	v_rcp_f32_e32 v39, v1
	v_pk_fma_f32 v[4:5], v[4:5], v[52:53], v[42:43]
	v_and_b32_e32 v29, 0xffff0000, v29
	v_pk_add_f32 v[4:5], v[40:41], v[4:5]
	v_pk_mul_f32 v[24:25], v[38:39], v[24:25]
	v_pk_mul_f32 v[4:5], v[4:5], v[28:29]
	v_lshlrev_b32_e32 v28, 16, v26
	v_pk_mul_f32 v[4:5], v[24:25], v[4:5]
	v_lshlrev_b32_e32 v24, 16, v2
	v_and_b32_e32 v25, 0xffff0000, v2
	v_mul_f32_e32 v2, 0xbfb8aa3b, v28
	v_exp_f32_e32 v2, v2
	v_and_b32_e32 v29, 0xffff0000, v26
	v_cvt_pk_bf16_f32 v1, v4, v5
	v_lshlrev_b32_e32 v4, 16, v6
	v_add_f32_e32 v2, 1.0, v2
	v_rcp_f32_e32 v38, v2
	v_mul_f32_e32 v2, 0xbfb8aa3b, v29
	v_exp_f32_e32 v2, v2
	v_and_b32_e32 v5, 0xffff0000, v6
	v_pk_mul_f32 v[4:5], v[114:115], v[4:5] op_sel_hi:[0,1]
	v_pk_mul_f32 v[4:5], v[4:5], v[24:25]
	v_add_f32_e32 v2, 1.0, v2
	v_rcp_f32_e32 v39, v2
	v_pk_fma_f32 v[4:5], v[4:5], v[20:21], v[12:13]
	v_lshlrev_b32_e32 v24, 16, v30
	v_and_b32_e32 v25, 0xffff0000, v30
	v_pk_add_f32 v[4:5], v[8:9], v[4:5]
	v_pk_mul_f32 v[8:9], v[38:39], v[28:29]
	v_pk_mul_f32 v[4:5], v[4:5], v[24:25]
	v_lshlrev_b32_e32 v6, 16, v3
	v_pk_mul_f32 v[4:5], v[8:9], v[4:5]
	v_lshlrev_b32_e32 v8, 16, v27
	v_cvt_pk_bf16_f32 v2, v4, v5
	v_lshlrev_b32_e32 v4, 16, v7
	v_and_b32_e32 v5, 0xffff0000, v7
	v_and_b32_e32 v7, 0xffff0000, v3
	v_mul_f32_e32 v3, 0xbfb8aa3b, v8
	v_exp_f32_e32 v3, v3
	v_and_b32_e32 v9, 0xffff0000, v27
	v_pk_mul_f32 v[4:5], v[114:115], v[4:5] op_sel_hi:[0,1]
	v_pk_mul_f32 v[16:17], v[58:59], v[18:19]
	v_add_f32_e32 v3, 1.0, v3
	v_rcp_f32_e32 v12, v3
	v_mul_f32_e32 v3, 0xbfb8aa3b, v9
	v_exp_f32_e32 v3, v3
	v_pk_mul_f32 v[4:5], v[4:5], v[6:7]
	v_pk_fma_f32 v[14:15], v[74:75], v[14:15], v[16:17]
	v_lshlrev_b32_e32 v6, 16, v31
	v_add_f32_e32 v3, 1.0, v3
	v_rcp_f32_e32 v13, v3
	v_pk_fma_f32 v[4:5], v[4:5], v[22:23], v[14:15]
	v_and_b32_e32 v7, 0xffff0000, v31
	v_pk_add_f32 v[4:5], v[10:11], v[4:5]
	s_nop 0
	v_pk_mul_f32 v[4:5], v[4:5], v[6:7]
	v_pk_mul_f32 v[6:7], v[12:13], v[8:9]
	s_nop 0
	v_pk_mul_f32 v[4:5], v[6:7], v[4:5]
	s_nop 0
	v_cvt_pk_bf16_f32 v3, v4, v5
	v_or_b32_e32 v4, 3, v34
	v_mad_i64_i32 v[4:5], s[6:7], v4, s44, v[90:91]
	v_lshl_add_u64 v[4:5], v[4:5], 0, v[32:33]
	v_add_co_u32_e32 v4, vcc, 0x18c00000, v4
	s_nop 1
	v_addc_co_u32_e32 v5, vcc, 0, v5, vcc
	global_store_dwordx4 v[4:5], v[0:3], off offset:1024 nt
	s_branch .LBB0_660

.LBB0_694:
	s_or_b64 exec, exec, s[6:7]
	v_readlane_b32 s6, v254, 52
	s_movk_i32 s13, 0x48
	v_or_b32_e32 v21, 32, v38
	v_or_b32_e32 v69, s6, v37
	v_mad_u64_u32 v[0:1], s[6:7], v69, s13, v[38:39]
	v_lshl_add_u32 v70, v0, 1, 0
	v_mad_u32_u24 v0, v37, s13, v38
	v_lshl_add_u32 v71, v0, 1, 0
	v_mov_b32_e32 v0, 0x480
	v_mad_u32_u24 v4, v37, s13, v0
	v_add_u32_e32 v0, v38, v4
	v_lshl_add_u32 v72, v0, 1, 0
	v_mov_b32_e32 v0, 0x900
	v_mad_u32_u24 v5, v37, s13, v0
	v_add_u32_e32 v0, v38, v5
	v_lshl_add_u32 v74, v0, 1, 0
	v_mov_b32_e32 v0, 0xd80
	v_mad_u32_u24 v6, v37, s13, v0
	v_add_u32_e32 v0, v38, v6
	v_lshl_add_u32 v76, v0, 1, 0
	v_mov_b32_e32 v0, 0x1200
	v_mad_u32_u24 v7, v37, s13, v0
	v_add_u32_e32 v0, v38, v7
	v_lshl_add_u32 v73, v0, 1, 0
	v_mov_b32_e32 v0, 0x1680
	v_mad_u32_u24 v8, v37, s13, v0
	v_add_u32_e32 v0, v38, v8
	v_lshl_add_u32 v75, v0, 1, 0
	v_mov_b32_e32 v0, 0x1b00
	v_mad_u32_u24 v9, v37, s13, v0
	v_add_u32_e32 v0, v38, v9
	v_lshl_add_u32 v77, v0, 1, 0
	v_mov_b32_e32 v0, 0x1f80
	v_add_u32_e32 v4, v21, v4
	v_mad_u32_u24 v20, v37, s13, v0
	v_lshl_add_u32 v80, v4, 1, 0
	v_add_u32_e32 v4, v21, v5
	v_add_u32_e32 v0, v38, v20
	v_lshl_add_u32 v82, v4, 1, 0
	v_add_u32_e32 v4, v21, v6
	v_add_u32_e32 v8, v21, v8
	v_lshl_add_u32 v78, v0, 1, 0
	v_mad_u32_u24 v10, v37, s13, v21
	v_lshl_add_u32 v118, v4, 1, 0
	v_add_u32_e32 v4, v21, v7
	v_lshl_add_u32 v83, v8, 1, 0
	v_add_u32_e32 v8, v21, v9
	v_add_u32_e32 v20, v21, v20
	v_lshlrev_b32_e32 v68, 2, v41
	s_waitcnt lgkmcnt(0)
	s_barrier
	ds_read_b128 v[46:49], v70 offset:18432
	ds_read_b128 v[24:27], v71 offset:55296
	ds_read_b128 v[28:31], v72 offset:55296
	ds_read_b128 v[54:57], v73 offset:55296
	ds_read_b128 v[40:43], v74 offset:55296
	ds_read_b128 v[58:61], v75 offset:55296
	ds_read_b128 v[50:53], v76 offset:55296
	ds_read_b128 v[84:87], v77 offset:55296
	ds_read_b128 v[88:91], v78 offset:55296
	ds_read_b128 v[0:3], v70 offset:18496
	v_lshl_add_u32 v79, v10, 1, 0
	v_lshl_add_u32 v81, v4, 1, 0
	v_lshl_add_u32 v119, v8, 1, 0
	v_lshl_add_u32 v120, v20, 1, 0
	ds_read_b128 v[92:95], v79 offset:55296
	ds_read_b128 v[96:99], v80 offset:55296
	ds_read_b128 v[100:103], v82 offset:55296
	ds_read_b128 v[4:7], v81 offset:55296
	ds_read_b128 v[12:15], v118 offset:55296
	ds_read_b128 v[16:19], v83 offset:55296
	ds_read_b128 v[8:11], v119 offset:55296
	ds_read_b128 v[20:23], v120 offset:55296
	s_waitcnt lgkmcnt(14)
	v_mfma_f32_16x16x32_bf16 v[104:107], v[24:27], v[46:49], 0
	v_add_u32_e32 v24, 1, v69
	v_cvt_f32_i32_e32 v24, v24
	s_add_i32 s6, 0, 0x17000
	s_waitcnt lgkmcnt(13)
	v_mfma_f32_16x16x32_bf16 v[112:115], v[40:43], v[46:49], 0
	v_sub_u32_e32 v42, v69, v68
	v_mul_f32_e64 v24, v24, -v39
	v_lshl_add_u32 v121, v42, 2, s6
	v_lshrrev_b32_e32 v42, 2, v37
	v_exp_f32_e32 v32, v24
	s_waitcnt lgkmcnt(11)
	v_mfma_f32_16x16x32_bf16 v[24:27], v[50:53], v[46:49], 0
	v_or_b32_e32 v50, v68, v42
	v_lshlrev_b32_e32 v37, 2, v37
	v_mul_u32_u24_e32 v50, 0x50, v50
	v_mfma_f32_16x16x32_bf16 v[108:111], v[28:31], v[46:49], 0
	v_not_b32_e32 v28, v68
	v_lshlrev_b32_e32 v38, 2, v69
	v_lshlrev_b32_e32 v39, 2, v28
	v_and_or_b32 v37, v37, 12, v50
	v_mfma_f32_16x16x32_bf16 v[28:31], v[54:57], v[46:49], 0
	v_add3_u32 v38, s6, v38, v39
	v_lshlrev_b32_e32 v37, 1, v37
	v_readlane_b32 s6, v254, 11
	v_readlane_b32 s7, v254, 12
	v_readlane_b32 s13, v254, 13
	v_add_u32_e32 v50, s0, v37
	v_add_u32_e32 v52, s6, v37
	v_add_u32_e32 v54, s7, v37
	v_add_u32_e32 v55, s13, v37
	ds_read2_b32 v[116:117], v38 offset0:127 offset1:128
	v_mfma_f32_16x16x32_bf16 v[38:41], v[58:61], v[46:49], 0
	ds_read_b64_tr_b16 v[58:59], v50
	ds_read_b64_tr_b16 v[60:61], v50 offset:2560
	ds_read_b64_tr_b16 v[50:51], v52
	ds_read_b64_tr_b16 v[52:53], v52 offset:2560
	s_waitcnt lgkmcnt(14)
	v_mfma_f32_16x16x32_bf16 v[42:45], v[84:87], v[46:49], 0
	v_mfma_f32_16x16x32_bf16 v[46:49], v[88:91], v[46:49], 0
	s_waitcnt lgkmcnt(12)
	v_mfma_f32_16x16x32_bf16 v[84:87], v[92:95], v[0:3], v[104:107]
	s_waitcnt lgkmcnt(11)
	v_mfma_f32_16x16x32_bf16 v[88:91], v[96:99], v[0:3], v[108:111]
	ds_read_b64_tr_b16 v[92:93], v54
	ds_read_b64_tr_b16 v[94:95], v54 offset:2560
	ds_read_b64_tr_b16 v[96:97], v55
	ds_read_b64_tr_b16 v[98:99], v55 offset:2560
	s_waitcnt lgkmcnt(8)
	v_pk_mul_f32 v[106:107], v[32:33], v[116:117] op_sel:[0,1] op_sel_hi:[0,0]
	v_mfma_f32_16x16x32_bf16 v[54:57], v[100:103], v[0:3], v[112:115]
	ds_read2_b32 v[100:101], v121 offset0:28 offset1:29
	ds_read2_b32 v[102:103], v121 offset0:14 offset1:15
	ds_read2_b32 v[104:105], v121 offset0:12 offset1:13
	v_mfma_f32_16x16x32_bf16 v[12:15], v[12:15], v[0:3], v[24:27]
	s_nop 2
	ds_read2_b32 v[26:27], v121 offset0:124 offset1:125
	v_mfma_f32_16x16x32_bf16 v[4:7], v[4:7], v[0:3], v[28:31]
	v_mul_f32_e64 v24, v84, v106
	v_mul_f32_e64 v25, v85, v107
	ds_read2_b32 v[84:85], v121 offset0:94 offset1:95
	v_cvt_pk_bf16_f32 v24, v24, v25
	ds_read2_b32 v[28:29], v121 offset0:110 offset1:111
	ds_read2_b32 v[30:31], v121 offset0:108 offset1:109
	s_waitcnt lgkmcnt(3)
	v_pk_mul_f32 v[26:27], v[32:33], v[26:27] op_sel_hi:[0,1]
	v_pk_mul_f32 v[26:27], v[86:87], v[26:27] op_sel:[0,1] op_sel_hi:[1,0]
	v_mfma_f32_16x16x32_bf16 v[16:19], v[16:19], v[0:3], v[38:41]
	v_cvt_pk_bf16_f32 v25, v26, v27
	s_waitcnt lgkmcnt(1)
	v_pk_mul_f32 v[26:27], v[32:33], v[28:29] op_sel_hi:[0,1]
	v_pk_mul_f32 v[26:27], v[88:89], v[26:27] op_sel:[0,1] op_sel_hi:[1,0]
	v_mfma_f32_16x16x32_bf16 v[8:11], v[8:11], v[0:3], v[42:45]
	v_cvt_pk_bf16_f32 v26, v26, v27
	v_pk_mul_f32 v[84:85], v[32:33], v[84:85] op_sel_hi:[0,1]
	v_pk_mul_f32 v[54:55], v[54:55], v[84:85] op_sel:[0,1] op_sel_hi:[1,0]
	v_mfma_f32_16x16x32_bf16 v[0:3], v[20:23], v[0:3], v[46:49]
	s_waitcnt lgkmcnt(0)
	v_pk_mul_f32 v[20:21], v[32:33], v[30:31] op_sel_hi:[0,1]
	v_pk_mul_f32 v[20:21], v[90:91], v[20:21] op_sel:[0,1] op_sel_hi:[1,0]
	v_cvt_pk_bf16_f32 v54, v54, v55
	v_cvt_pk_bf16_f32 v27, v20, v21
	v_add_u32_e32 v46, 0x1400, v37
	v_add_u32_e32 v40, s0, v46
	v_mfma_f32_16x16x32_bf16 v[20:23], v[58:61], v[24:27], 0
	v_add_u32_e32 v44, s6, v46
	v_add_u32_e32 v60, s13, v46
	ds_read_b64_tr_b16 v[38:39], v40
	ds_read_b64_tr_b16 v[40:41], v40 offset:2560
	ds_read_b64_tr_b16 v[42:43], v44
	ds_read_b64_tr_b16 v[44:45], v44 offset:2560
	v_mfma_f32_16x16x32_bf16 v[28:31], v[50:53], v[24:27], 0
	v_add_u32_e32 v52, s7, v46
	ds_read_b64_tr_b16 v[50:51], v52
	ds_read_b64_tr_b16 v[52:53], v52 offset:2560
	ds_read_b64_tr_b16 v[58:59], v60
	ds_read_b64_tr_b16 v[60:61], v60 offset:2560
	ds_read2_b32 v[86:87], v121 offset0:92 offset1:93
	ds_read2_b32 v[84:85], v121 offset0:78 offset1:79
	v_mfma_f32_16x16x32_bf16 v[46:49], v[92:95], v[24:27], 0
	s_waitcnt lgkmcnt(1)
	v_pk_mul_f32 v[86:87], v[32:33], v[86:87] op_sel_hi:[0,1]
	v_pk_mul_f32 v[56:57], v[56:57], v[86:87] op_sel:[0,1] op_sel_hi:[1,0]
	ds_read2_b32 v[86:87], v121 offset0:76 offset1:77
	v_cvt_pk_bf16_f32 v55, v56, v57
	s_waitcnt lgkmcnt(1)
	v_pk_mul_f32 v[56:57], v[32:33], v[84:85] op_sel_hi:[0,1]
	v_pk_mul_f32 v[12:13], v[12:13], v[56:57] op_sel:[0,1] op_sel_hi:[1,0]
	v_mfma_f32_16x16x32_bf16 v[24:27], v[96:99], v[24:27], 0
	v_cvt_pk_bf16_f32 v56, v12, v13
	ds_read2_b32 v[84:85], v121 offset0:62 offset1:63
	s_waitcnt lgkmcnt(1)
	v_pk_mul_f32 v[12:13], v[32:33], v[86:87] op_sel_hi:[0,1]
	v_pk_mul_f32 v[12:13], v[14:15], v[12:13] op_sel:[0,1] op_sel_hi:[1,0]
	v_add_u32_e32 v86, 0x2800, v37
	v_cvt_pk_bf16_f32 v57, v12, v13
	v_add_u32_e32 v87, s7, v86
	v_add_u32_e32 v37, 0x3c00, v37
	v_mfma_f32_16x16x32_bf16 v[12:15], v[38:41], v[54:57], v[20:23]
	v_add_u32_e32 v38, s0, v86
	v_add_u32_e32 v40, s6, v86
	v_add_u32_e32 v86, s13, v86
	v_mfma_f32_16x16x32_bf16 v[20:23], v[42:45], v[54:57], v[28:31]
	s_nop 2
	ds_read_b64_tr_b16 v[28:29], v38
	ds_read_b64_tr_b16 v[30:31], v38 offset:2560
	ds_read_b64_tr_b16 v[38:39], v40
	ds_read_b64_tr_b16 v[40:41], v40 offset:2560
	v_mfma_f32_16x16x32_bf16 v[42:45], v[50:53], v[54:57], v[46:49]
	s_nop 2
	ds_read_b64_tr_b16 v[46:47], v87
	ds_read_b64_tr_b16 v[48:49], v87 offset:2560
	ds_read_b64_tr_b16 v[50:51], v86
	ds_read_b64_tr_b16 v[52:53], v86 offset:2560
	v_mfma_f32_16x16x32_bf16 v[24:27], v[58:61], v[54:57], v[24:27]
	ds_read2_b32 v[54:55], v121 offset0:60 offset1:61
	s_waitcnt lgkmcnt(9)
	v_pk_mul_f32 v[56:57], v[32:33], v[84:85] op_sel_hi:[0,1]
	v_pk_mul_f32 v[4:5], v[4:5], v[56:57] op_sel:[0,1] op_sel_hi:[1,0]
	ds_read2_b32 v[56:57], v121 offset0:46 offset1:47
	v_cvt_pk_bf16_f32 v4, v4, v5
	s_waitcnt lgkmcnt(1)
	v_pk_mul_f32 v[54:55], v[32:33], v[54:55] op_sel_hi:[0,1]
	v_pk_mul_f32 v[6:7], v[6:7], v[54:55] op_sel:[0,1] op_sel_hi:[1,0]
	ds_read2_b32 v[54:55], v121 offset0:44 offset1:45
	v_cvt_pk_bf16_f32 v5, v6, v7
	s_waitcnt lgkmcnt(1)
	v_pk_mul_f32 v[6:7], v[32:33], v[56:57] op_sel_hi:[0,1]
	v_pk_mul_f32 v[6:7], v[16:17], v[6:7] op_sel:[0,1] op_sel_hi:[1,0]
	ds_read2_b32 v[56:57], v121 offset0:30 offset1:31
	s_waitcnt lgkmcnt(1)
	v_pk_mul_f32 v[16:17], v[32:33], v[54:55] op_sel_hi:[0,1]
	v_pk_mul_f32 v[16:17], v[18:19], v[16:17] op_sel:[0,1] op_sel_hi:[1,0]
	v_cvt_pk_bf16_f32 v6, v6, v7
	v_cvt_pk_bf16_f32 v7, v16, v17
	v_add_u32_e32 v54, s7, v37
	s_nop 0
	v_mfma_f32_16x16x32_bf16 v[12:15], v[28:31], v[4:7], v[12:15]
	v_add_u32_e32 v28, s0, v37
	v_add_u32_e32 v30, s6, v37
	v_add_u32_e32 v37, s13, v37
	v_mfma_f32_16x16x32_bf16 v[16:19], v[38:41], v[4:7], v[20:23]
	s_nop 2
	ds_read_b64_tr_b16 v[20:21], v28
	ds_read_b64_tr_b16 v[22:23], v28 offset:2560
	ds_read_b64_tr_b16 v[28:29], v30
	ds_read_b64_tr_b16 v[30:31], v30 offset:2560
	v_mfma_f32_16x16x32_bf16 v[38:41], v[46:49], v[4:7], v[42:45]
	s_nop 2
	ds_read_b64_tr_b16 v[42:43], v54
	ds_read_b64_tr_b16 v[44:45], v54 offset:2560
	ds_read_b64_tr_b16 v[46:47], v37
	ds_read_b64_tr_b16 v[48:49], v37 offset:2560
	v_mfma_f32_16x16x32_bf16 v[4:7], v[50:53], v[4:7], v[24:27]
	s_waitcnt lgkmcnt(8)
	s_nop 1
	v_pk_mul_f32 v[24:25], v[32:33], v[56:57] op_sel_hi:[0,1]
	v_pk_mul_f32 v[8:9], v[8:9], v[24:25] op_sel:[0,1] op_sel_hi:[1,0]
	v_pk_mul_f32 v[24:25], v[32:33], v[100:101] op_sel_hi:[0,1]
	v_pk_mul_f32 v[10:11], v[10:11], v[24:25] op_sel:[0,1] op_sel_hi:[1,0]
	v_cvt_pk_bf16_f32 v8, v8, v9
	v_cvt_pk_bf16_f32 v9, v10, v11
	v_pk_mul_f32 v[10:11], v[32:33], v[102:103] op_sel_hi:[0,1]
	v_pk_mul_f32 v[0:1], v[0:1], v[10:11] op_sel:[0,1] op_sel_hi:[1,0]
	s_nop 0
	v_cvt_pk_bf16_f32 v10, v0, v1
	v_pk_mul_f32 v[0:1], v[32:33], v[104:105] op_sel_hi:[0,1]
	v_pk_mul_f32 v[0:1], v[2:3], v[0:1] op_sel:[0,1] op_sel_hi:[1,0]
	s_nop 0
	v_cvt_pk_bf16_f32 v11, v0, v1
	s_waitcnt lgkmcnt(6)
	s_nop 0
	v_mfma_f32_16x16x32_bf16 v[0:3], v[20:23], v[8:11], v[12:15]
	s_waitcnt lgkmcnt(4)
	v_mfma_f32_16x16x32_bf16 v[12:15], v[28:31], v[8:11], v[16:19]
	s_waitcnt lgkmcnt(2)
	v_mfma_f32_16x16x32_bf16 v[16:19], v[42:45], v[8:11], v[38:41]
	s_waitcnt lgkmcnt(0)
	v_mfma_f32_16x16x32_bf16 v[4:7], v[46:49], v[8:11], v[4:7]
	ds_read_b128 v[8:11], v70 offset:18432
	ds_read_b128 v[20:23], v71
	ds_read_b128 v[24:27], v72
	ds_read_b128 v[28:31], v74
	ds_read_b128 v[38:41], v76
	ds_read_b128 v[42:45], v70 offset:18496
	ds_read_b128 v[46:49], v79
	ds_read_b128 v[50:53], v80
	ds_read_b128 v[54:57], v82
	ds_read_b128 v[58:61], v118
	ds_read_b128 v[84:87], v70 offset:36864
	ds_read_b128 v[88:91], v73
	ds_read_b128 v[72:75], v75
	ds_read_b128 v[92:95], v77
	ds_read_b128 v[76:79], v78
	ds_read_b128 v[96:99], v70 offset:36928
	ds_read_b128 v[100:103], v81
	ds_read_b128 v[80:83], v83
	ds_read_b128 v[104:107], v119
	ds_read_b128 v[108:111], v120
	s_waitcnt lgkmcnt(14)
	v_mfma_f32_16x16x32_bf16 v[0:3], v[20:23], v[8:11], v[0:3]
	s_mov_b32 s0, 0x800000
	v_mfma_f32_16x16x32_bf16 v[12:15], v[24:27], v[8:11], v[12:15]
	s_waitcnt lgkmcnt(13)
	v_mfma_f32_16x16x32_bf16 v[0:3], v[46:49], v[42:45], v[0:3]
	v_mfma_f32_16x16x32_bf16 v[16:19], v[28:31], v[8:11], v[16:19]
	v_or_b32_e32 v28, s12, v68
	v_lshlrev_b32_e32 v32, 1, v28
	v_mfma_f32_16x16x32_bf16 v[4:7], v[38:41], v[8:11], v[4:7]
	s_waitcnt lgkmcnt(12)
	v_mfma_f32_16x16x32_bf16 v[8:11], v[50:53], v[42:45], v[12:15]
	s_waitcnt lgkmcnt(8)
	v_mfma_f32_16x16x32_bf16 v[0:3], v[88:91], v[84:87], v[0:3]
	s_waitcnt lgkmcnt(7)
	v_mfma_f32_16x16x32_bf16 v[8:11], v[72:75], v[84:87], v[8:11]
	v_mfma_f32_16x16x32_bf16 v[12:15], v[54:57], v[42:45], v[16:19]
	v_mfma_f32_16x16x32_bf16 v[4:7], v[58:61], v[42:45], v[4:7]
	s_waitcnt lgkmcnt(3)
	v_mfma_f32_16x16x32_bf16 v[16:19], v[100:103], v[96:99], v[0:3]
	s_waitcnt lgkmcnt(2)
	v_mfma_f32_16x16x32_bf16 v[8:11], v[80:83], v[96:99], v[8:11]
	v_mfma_f32_16x16x32_bf16 v[0:3], v[92:95], v[84:87], v[12:15]
	s_nop 4
	v_mov_b32_e32 v20, v17
	v_mov_b32_e32 v21, v18
	v_mov_b32_e32 v22, v16
	v_mov_b32_e32 v23, v19
	v_mfma_f32_16x16x32_bf16 v[4:7], v[76:79], v[84:87], v[4:7]
	v_add_f32_e64 v12, v20, v22
	v_add_f32_e64 v13, v21, v23
	v_mov_b32_e32 v14, v8
	v_add_f32_e32 v12, v12, v13
	v_add_f32_e32 v20, 0, v12
	v_mov_b32_e32 v12, v9
	v_mov_b32_e32 v13, v10
	v_mov_b32_e32 v15, v11
	v_pk_add_f32 v[22:23], v[12:13], v[14:15]
	s_waitcnt lgkmcnt(1)
	v_mfma_f32_16x16x32_bf16 v[12:15], v[104:107], v[96:99], v[0:3]
	v_pk_add_f32 v[22:23], v[22:23], v[22:23] op_sel:[0,1] op_sel_hi:[1,0]
	s_waitcnt lgkmcnt(0)
	v_mfma_f32_16x16x32_bf16 v[0:3], v[108:111], v[96:99], v[4:7]
	s_nop 4
	v_add_f32_e32 v24, v12, v13
	v_add_f32_e32 v26, v14, v15
	s_nop 0
	v_mov_b32_e32 v21, v0
	v_mov_b32_e32 v23, v1
	v_mov_b32_e32 v25, v2
	v_mov_b32_e32 v27, v3
	v_pk_add_f32 v[4:5], v[20:21], v[22:23]
	v_pk_add_f32 v[6:7], v[24:25], v[26:27]
	v_and_b32_e32 v25, 0xffff0000, v67
	v_pk_add_f32 v[4:5], v[4:5], v[6:7]
	s_nop 0
	v_add_f32_e32 v4, v4, v5
	v_mov_b32_e32 v5, v4
	s_nop 1
	v_permlane16_swap_b32 v4, v5
	s_nop 1
	s_nop 0
	v_add_f32_e32 v4, v4, v5
	v_mov_b32_e32 v5, v4
	s_nop 1
	v_permlane32_swap_b32 v4, v5
	s_nop 1
	s_nop 0
	v_add_f32_e32 v24, v4, v5
	v_fmamk_f32 v5, v24, 0xbc800000, v17
	v_fmamk_f32 v4, v24, 0xbc800000, v16
	v_fmamk_f32 v19, v24, 0xbc800000, v19
	v_fmac_f32_e32 v18, 0xbc800000, v24
	v_pk_mul_f32 v[6:7], v[18:19], v[18:19]
	v_pk_mul_f32 v[16:17], v[4:5], v[4:5]
	v_fmamk_f32 v9, v24, 0xbc800000, v9
	v_pk_mov_b32 v[20:21], v[16:17], v[6:7] op_sel:[1,0]
	v_mov_b32_e32 v17, v7
	v_pk_add_f32 v[6:7], v[20:21], v[16:17]
	v_fmamk_f32 v8, v24, 0xbc800000, v8
	v_fmamk_f32 v11, v24, 0xbc800000, v11
	v_fmac_f32_e32 v10, 0xbc800000, v24
	v_pk_add_f32 v[6:7], v[6:7], v[6:7] op_sel_hi:[0,1]
	v_pk_mul_f32 v[16:17], v[10:11], v[10:11]
	v_pk_mul_f32 v[20:21], v[8:9], v[8:9]
	v_fmamk_f32 v12, v24, 0xbc800000, v12
	v_pk_mov_b32 v[22:23], v[20:21], v[16:17] op_sel:[1,0]
	v_mov_b32_e32 v21, v17
	v_fmamk_f32 v13, v24, 0xbc800000, v13
	v_fmac_f32_e32 v14, 0xbc800000, v24
	v_mul_f32_e32 v6, v12, v12
	v_pk_add_f32 v[16:17], v[22:23], v[20:21]
	v_fmamk_f32 v15, v24, 0xbc800000, v15
	v_pk_fma_f32 v[20:21], v[12:13], v[12:13], v[6:7] op_sel_hi:[1,1,0]
	v_mul_f32_e32 v6, v14, v14
	v_pk_add_f32 v[16:17], v[16:17], v[16:17] op_sel_hi:[0,1]
	v_pk_fma_f32 v[22:23], v[14:15], v[14:15], v[6:7] op_sel_hi:[1,1,0]
	v_fmamk_f32 v3, v24, 0xbc800000, v3
	v_fmamk_f32 v2, v24, 0xbc800000, v2
	v_fmamk_f32 v1, v24, 0xbc800000, v1
	v_fmac_f32_e32 v0, 0xbc800000, v24
	v_mul_f32_e32 v20, v0, v0
	v_mul_f32_e32 v22, v1, v1
	v_mul_f32_e32 v6, v2, v2
	v_mul_f32_e32 v16, v3, v3
	v_pk_add_f32 v[20:21], v[20:21], v[22:23]
	v_pk_add_f32 v[6:7], v[6:7], v[16:17]
	v_mov_b64_e32 v[16:17], s[48:49]
	v_pk_add_f32 v[6:7], v[20:21], v[6:7]
	v_lshlrev_b32_e32 v20, 16, v66
	v_add_f32_e32 v6, v6, v7
	v_mov_b32_e32 v7, v6
	s_nop 1
	v_permlane16_swap_b32 v6, v7
	s_nop 1
	v_and_b32_e32 v21, 0xffff0000, v66
	v_add_f32_e32 v6, v6, v7
	v_mov_b32_e32 v7, v6
	s_nop 1
	v_permlane32_swap_b32 v6, v7
	s_nop 1
	v_mul_f32_e32 v22, 0xbfb8aa3b, v21
	v_add_f32_e32 v6, v6, v7
	v_fmamk_f32 v6, v6, 0x3c800000, v239
	v_mul_f32_e32 v7, 0x4b800000, v6
	v_cmp_gt_f32_e32 vcc, s0, v6
	v_exp_f32_e32 v23, v22
	v_lshlrev_b32_e32 v24, 16, v67
	v_cndmask_b32_e32 v6, v6, v7, vcc
	v_rsq_f32_e32 v6, v6
	s_mov_b32 s0, 0x18c00000
	v_mul_f32_e32 v7, 0x45800000, v6
	v_cndmask_b32_e32 v6, v6, v7, vcc
	v_add_u32_e32 v7, s8, v69
	v_mad_i64_i32 v[16:17], s[6:7], v7, s44, v[16:17]
	v_pk_mul_f32 v[18:19], v[18:19], v[6:7] op_sel_hi:[1,0]
	v_mul_f32_e32 v7, 0xbfb8aa3b, v20
	v_exp_f32_e32 v7, v7
	v_lshl_add_u64 v[16:17], v[16:17], 0, v[32:33]
	s_mov_b64 s[6:7], 0x18c00600
	v_pk_mul_f32 v[4:5], v[4:5], v[6:7] op_sel_hi:[1,0]
	v_add_f32_e32 v7, 1.0, v7
	v_rcp_f32_e32 v22, v7
	v_add_f32_e32 v7, 1.0, v23
	v_mul_f32_e32 v23, 0xbfb8aa3b, v24
	v_exp_f32_e32 v26, v23
	v_mul_f32_e32 v23, 0xbfb8aa3b, v25
	v_exp_f32_e32 v27, v23
	v_rcp_f32_e32 v23, v7
	v_add_f32_e32 v7, 1.0, v26
	v_rcp_f32_e32 v26, v7
	v_add_f32_e32 v7, 1.0, v27
	v_rcp_f32_e32 v27, v7
	v_pk_mul_f32 v[20:21], v[22:23], v[20:21]
	s_nop 0
	v_pk_mul_f32 v[4:5], v[20:21], v[4:5]
	v_pk_mul_f32 v[20:21], v[26:27], v[24:25]
	v_cvt_pk_bf16_f32 v4, v4, v5
	v_pk_mul_f32 v[18:19], v[20:21], v[18:19]
	v_lshlrev_b32_e32 v20, 16, v65
	v_cvt_pk_bf16_f32 v5, v18, v19
	v_lshl_add_u64 v[18:19], v[16:17], 0, s[6:7]
	v_add_co_u32_e32 v16, vcc, s0, v16
	v_and_b32_e32 v21, 0xffff0000, v65
	s_nop 0
	v_addc_co_u32_e32 v17, vcc, 0, v17, vcc
	global_store_dwordx2 v[16:17], v[4:5], off offset:1536 nt
	v_pk_mul_f32 v[4:5], v[10:11], v[6:7] op_sel_hi:[1,0]
	v_lshlrev_b32_e32 v10, 16, v64
	v_and_b32_e32 v11, 0xffff0000, v64
	v_mul_f32_e32 v7, 0xbfb8aa3b, v10
	v_exp_f32_e32 v7, v7
	v_mul_f32_e32 v16, 0xbfb8aa3b, v11
	v_exp_f32_e32 v17, v16
	v_pk_mul_f32 v[8:9], v[8:9], v[6:7] op_sel_hi:[1,0]
	v_add_f32_e32 v7, 1.0, v7
	v_rcp_f32_e32 v16, v7
	v_add_f32_e32 v7, 1.0, v17
	v_mul_f32_e32 v17, 0xbfb8aa3b, v20
	v_exp_f32_e32 v22, v17
	v_mul_f32_e32 v17, 0xbfb8aa3b, v21
	v_exp_f32_e32 v23, v17
	v_rcp_f32_e32 v17, v7
	v_add_f32_e32 v7, 1.0, v22
	v_rcp_f32_e32 v22, v7
	v_add_f32_e32 v7, 1.0, v23
	v_rcp_f32_e32 v23, v7
	v_pk_mul_f32 v[10:11], v[16:17], v[10:11]
	s_nop 0
	v_pk_mul_f32 v[8:9], v[10:11], v[8:9]
	v_pk_mul_f32 v[10:11], v[22:23], v[20:21]
	v_cvt_pk_bf16_f32 v8, v8, v9
	v_pk_mul_f32 v[4:5], v[10:11], v[4:5]
	s_nop 0
	v_cvt_pk_bf16_f32 v9, v4, v5
	global_store_dwordx2 v[18:19], v[8:9], off offset:32 nt
	v_lshlrev_b32_e32 v8, 16, v62
	v_pk_mul_f32 v[4:5], v[14:15], v[6:7] op_sel_hi:[1,0]
	v_and_b32_e32 v9, 0xffff0000, v62
	v_mul_f32_e32 v7, 0xbfb8aa3b, v8
	v_exp_f32_e32 v7, v7
	v_mul_f32_e32 v10, 0xbfb8aa3b, v9
	v_exp_f32_e32 v14, v10
	v_and_b32_e32 v15, 0xffff0000, v63
	v_pk_mul_f32 v[10:11], v[12:13], v[6:7] op_sel_hi:[1,0]
	v_add_f32_e32 v7, 1.0, v7
	v_rcp_f32_e32 v12, v7
	v_add_f32_e32 v7, 1.0, v14
	v_lshlrev_b32_e32 v14, 16, v63
	v_mul_f32_e32 v13, 0xbfb8aa3b, v14
	v_exp_f32_e32 v16, v13
	v_mul_f32_e32 v13, 0xbfb8aa3b, v15
	v_exp_f32_e32 v17, v13
	v_rcp_f32_e32 v13, v7
	v_add_f32_e32 v7, 1.0, v16
	v_rcp_f32_e32 v16, v7
	v_add_f32_e32 v7, 1.0, v17
	v_rcp_f32_e32 v17, v7
	v_pk_mul_f32 v[8:9], v[12:13], v[8:9]
	v_pk_mul_f32 v[2:3], v[2:3], v[6:7] op_sel_hi:[1,0]
	v_pk_mul_f32 v[8:9], v[8:9], v[10:11]
	v_pk_mul_f32 v[10:11], v[16:17], v[14:15]
	v_cvt_pk_bf16_f32 v8, v8, v9
	v_pk_mul_f32 v[4:5], v[10:11], v[4:5]
	s_nop 0
	v_cvt_pk_bf16_f32 v9, v4, v5
	v_lshlrev_b32_e32 v4, 16, v34
	v_and_b32_e32 v5, 0xffff0000, v34
	global_store_dwordx2 v[18:19], v[8:9], off offset:64 nt
	v_mul_f32_e32 v7, 0xbfb8aa3b, v4
	v_mul_f32_e32 v8, 0xbfb8aa3b, v5
	v_exp_f32_e32 v7, v7
	v_exp_f32_e32 v8, v8
	v_and_b32_e32 v9, 0xffff0000, v35
	v_mul_f32_e32 v11, 0xbfb8aa3b, v9
	v_pk_mul_f32 v[0:1], v[0:1], v[6:7] op_sel_hi:[1,0]
	v_add_f32_e32 v6, 1.0, v7
	v_add_f32_e32 v7, 1.0, v8
	v_lshlrev_b32_e32 v8, 16, v35
	v_mul_f32_e32 v10, 0xbfb8aa3b, v8
	v_exp_f32_e32 v10, v10
	v_exp_f32_e32 v11, v11
	v_rcp_f32_e32 v6, v6
	v_rcp_f32_e32 v7, v7
	v_add_f32_e32 v10, 1.0, v10
	v_add_f32_e32 v11, 1.0, v11
	v_rcp_f32_e32 v10, v10
	v_rcp_f32_e32 v11, v11
	v_pk_mul_f32 v[4:5], v[6:7], v[4:5]
	s_nop 0
	v_pk_mul_f32 v[0:1], v[4:5], v[0:1]
	v_pk_mul_f32 v[4:5], v[10:11], v[8:9]
	v_cvt_pk_bf16_f32 v0, v0, v1
	v_pk_mul_f32 v[2:3], v[4:5], v[2:3]
	s_nop 0
	v_cvt_pk_bf16_f32 v1, v2, v3
	global_store_dwordx2 v[18:19], v[0:1], off offset:96 nt

.LBB0_711:
	s_or_b64 exec, exec, s[6:7]
	s_lshl_b32 s6, s8, 16
	v_readlane_b32 s16, v254, 23
	v_add_u32_e32 v17, 0x200, v206
	s_add_u32 s6, s16, s6
	v_readlane_b32 s7, v255, 3
	v_ashrrev_i32_e32 v24, 5, v206
	v_ashrrev_i32_e32 v22, 5, v17
	s_addc_u32 s7, s7, 0
	v_ashrrev_i32_e32 v25, 31, v24
	v_ashrrev_i32_e32 v23, 31, v22
	v_lshl_add_u64 v[30:31], s[6:7], 0, v[32:33]
	v_lshlrev_b64 v[18:19], 9, v[24:25]
	v_lshlrev_b64 v[20:21], 9, v[22:23]
	v_lshl_add_u64 v[18:19], v[30:31], 0, v[18:19]
	v_lshl_add_u64 v[20:21], v[30:31], 0, v[20:21]
	v_add_u32_e32 v17, 0x400, v206
	s_barrier
	global_load_dwordx4 v[26:29], v[18:19], off
	global_load_dwordx4 v[38:41], v[20:21], off
	v_ashrrev_i32_e32 v20, 5, v17
	v_ashrrev_i32_e32 v21, 31, v20
	v_lshlrev_b64 v[18:19], 9, v[20:21]
	v_add_u32_e32 v17, 0x600, v206
	v_lshl_add_u64 v[34:35], v[30:31], 0, v[18:19]
	v_ashrrev_i32_e32 v18, 5, v17
	v_ashrrev_i32_e32 v19, 31, v18
	v_lshlrev_b64 v[42:43], 9, v[18:19]
	v_lshl_add_u64 v[46:47], v[30:31], 0, v[42:43]
	v_add_u32_e32 v17, 0x800, v206
	global_load_dwordx4 v[42:45], v[34:35], off
	s_nop 0
	global_load_dwordx4 v[46:49], v[46:47], off
	v_ashrrev_i32_e32 v34, 5, v17
	v_add_u32_e32 v17, 0xa00, v206
	v_ashrrev_i32_e32 v66, 5, v17
	v_add_u32_e32 v17, 0xc00, v206
	v_ashrrev_i32_e32 v68, 5, v17
	v_add_u32_e32 v17, 0xe00, v206
	v_ashrrev_i32_e32 v35, 31, v34
	v_ashrrev_i32_e32 v67, 31, v66
	v_ashrrev_i32_e32 v69, 31, v68
	v_ashrrev_i32_e32 v70, 5, v17
	v_lshlrev_b64 v[50:51], 9, v[34:35]
	v_lshlrev_b64 v[52:53], 9, v[66:67]
	v_lshlrev_b64 v[58:59], 9, v[68:69]
	v_ashrrev_i32_e32 v71, 31, v70
	v_lshl_add_u64 v[50:51], v[30:31], 0, v[50:51]
	v_lshl_add_u64 v[54:55], v[30:31], 0, v[52:53]
	v_lshl_add_u64 v[58:59], v[30:31], 0, v[58:59]
	v_lshlrev_b64 v[60:61], 9, v[70:71]
	global_load_dwordx4 v[50:53], v[50:51], off
	s_nop 0
	global_load_dwordx4 v[54:57], v[54:55], off
	v_lshl_add_u64 v[30:31], v[30:31], 0, v[60:61]
	global_load_dwordx4 v[58:61], v[58:59], off
	s_nop 0
	global_load_dwordx4 v[62:65], v[30:31], off
	v_readlane_b32 s17, v254, 24
	v_readlane_b32 s18, v254, 25
	v_readlane_b32 s19, v254, 26
	v_and_b32_e32 v17, 15, v206
	v_mad_u64_u32 v[30:31], s[6:7], v24, s33, v[16:17]
	v_lshl_add_u32 v19, v30, 1, 0
	s_waitcnt vmcnt(7)
	ds_write_b128 v19, v[26:29]
	v_mad_u64_u32 v[26:27], s[6:7], v22, s33, v[16:17]
	v_lshl_add_u32 v19, v26, 1, 0
	v_mad_u64_u32 v[26:27], s[6:7], v20, s33, v[16:17]
	s_waitcnt vmcnt(6)
	ds_write_b128 v19, v[38:41]
	v_lshl_add_u32 v19, v26, 1, 0
	v_mad_u64_u32 v[26:27], s[6:7], v18, s33, v[16:17]
	s_waitcnt vmcnt(5)
	ds_write_b128 v19, v[42:45]
	v_lshl_add_u32 v19, v26, 1, 0
	v_mad_u64_u32 v[26:27], s[6:7], v34, s33, v[16:17]
	s_waitcnt vmcnt(4)
	ds_write_b128 v19, v[46:49]
	v_lshl_add_u32 v19, v26, 1, 0
	v_mad_u64_u32 v[26:27], s[6:7], v66, s33, v[16:17]
	s_waitcnt vmcnt(3)
	ds_write_b128 v19, v[50:53]
	v_lshl_add_u32 v19, v26, 1, 0
	v_mad_u64_u32 v[26:27], s[6:7], v68, s33, v[16:17]
	s_waitcnt vmcnt(2)
	ds_write_b128 v19, v[54:57]
	v_lshl_add_u32 v19, v26, 1, 0
	v_mad_u64_u32 v[26:27], s[6:7], v70, s33, v[16:17]
	s_waitcnt vmcnt(1)
	ds_write_b128 v19, v[58:61]
	v_lshl_add_u32 v19, v26, 1, 0
	s_waitcnt vmcnt(0)
	ds_write_b128 v19, v[62:65]
	v_lshrrev_b32_e32 v19, 1, v206
	v_bfe_u32 v21, v206, 2, 2
	v_and_or_b32 v19, v19, 24, v21
	v_mul_u32_u24_e32 v19, 0x110, v19
	v_lshlrev_b32_e32 v21, 2, v206
	v_and_or_b32 v19, v21, 12, v19
	v_lshlrev_b32_e32 v19, 1, v19
	v_add_u32_e32 v19, s65, v19
	v_and_b32_e32 v21, 48, v206
	s_add_i32 s6, 0, 0x1a9d0
	v_mul_u32_u24_e32 v23, 0x110, v17
	s_waitcnt lgkmcnt(0)
	s_barrier
	ds_read_b64_tr_b16 v[28:29], v19 offset:2176
	ds_read_b64_tr_b16 v[26:27], v19
	ds_read_b64_tr_b16 v[40:41], v19 offset:2208
	ds_read_b64_tr_b16 v[38:39], v19 offset:32
	v_add3_u32 v23, s6, v21, v23
	ds_read_b64_tr_b16 v[44:45], v19 offset:19584
	ds_read_b64_tr_b16 v[42:43], v19 offset:17408
	ds_read_b64_tr_b16 v[48:49], v19 offset:19616
	ds_read_b64_tr_b16 v[46:47], v19 offset:17440
	ds_read_b128 v[50:53], v23
	ds_read_b128 v[54:57], v23 offset:64
	ds_read_b128 v[58:61], v23 offset:4352
	ds_read_b128 v[62:65], v23 offset:4416
	ds_read_b128 v[66:69], v23 offset:8704
	ds_read_b128 v[70:73], v23 offset:8768
	ds_read_b128 v[74:77], v23 offset:13056
	ds_read_b128 v[78:81], v23 offset:13120
	s_waitcnt lgkmcnt(7)
	v_mfma_f32_16x16x32_bf16 v[82:85], v[26:29], v[50:53], 0
	v_mfma_f32_16x16x32_bf16 v[50:53], v[38:41], v[50:53], 0
	s_waitcnt lgkmcnt(5)
	v_mfma_f32_16x16x32_bf16 v[86:89], v[26:29], v[58:61], 0
	v_mfma_f32_16x16x32_bf16 v[58:61], v[38:41], v[58:61], 0
	s_waitcnt lgkmcnt(3)
	v_mfma_f32_16x16x32_bf16 v[90:93], v[26:29], v[66:69], 0
	v_mfma_f32_16x16x32_bf16 v[66:69], v[38:41], v[66:69], 0
	s_waitcnt lgkmcnt(1)
	v_mfma_f32_16x16x32_bf16 v[26:29], v[26:29], v[74:77], 0
	v_mfma_f32_16x16x32_bf16 v[38:41], v[38:41], v[74:77], 0
	ds_read_b64_tr_b16 v[76:77], v19 offset:36992
	ds_read_b64_tr_b16 v[74:75], v19 offset:34816
	ds_read_b64_tr_b16 v[96:97], v19 offset:37024
	ds_read_b64_tr_b16 v[94:95], v19 offset:34848
	ds_read_b128 v[98:101], v23 offset:128
	ds_read_b128 v[102:105], v23 offset:4480
	ds_read_b128 v[106:109], v23 offset:8832
	ds_read_b128 v[110:113], v23 offset:13184
	v_mfma_f32_16x16x32_bf16 v[82:85], v[42:45], v[54:57], v[82:85]
	v_mfma_f32_16x16x32_bf16 v[50:53], v[46:49], v[54:57], v[50:53]
	v_mfma_f32_16x16x32_bf16 v[54:57], v[42:45], v[62:65], v[86:89]
	v_mfma_f32_16x16x32_bf16 v[58:61], v[46:49], v[62:65], v[58:61]
	v_mfma_f32_16x16x32_bf16 v[62:65], v[42:45], v[70:73], v[90:93]
	v_mfma_f32_16x16x32_bf16 v[66:69], v[46:49], v[70:73], v[66:69]
	s_waitcnt lgkmcnt(8)
	v_mfma_f32_16x16x32_bf16 v[26:29], v[42:45], v[78:81], v[26:29]
	v_mfma_f32_16x16x32_bf16 v[38:41], v[46:49], v[78:81], v[38:41]
	ds_read_b64_tr_b16 v[44:45], v19 offset:54400
	ds_read_b64_tr_b16 v[42:43], v19 offset:52224
	ds_read_b64_tr_b16 v[48:49], v19 offset:54432
	ds_read_b64_tr_b16 v[46:47], v19 offset:52256
	ds_read_b128 v[70:73], v23 offset:192
	ds_read_b128 v[78:81], v23 offset:4544
	ds_read_b128 v[86:89], v23 offset:8896
	ds_read_b128 v[90:93], v23 offset:13248
	s_waitcnt lgkmcnt(11)
	v_mfma_f32_16x16x32_bf16 v[82:85], v[74:77], v[98:101], v[82:85]
	v_mfma_f32_16x16x32_bf16 v[50:53], v[94:97], v[98:101], v[50:53]
	s_waitcnt lgkmcnt(10)
	v_mfma_f32_16x16x32_bf16 v[54:57], v[74:77], v[102:105], v[54:57]
	v_mfma_f32_16x16x32_bf16 v[58:61], v[94:97], v[102:105], v[58:61]
	s_waitcnt lgkmcnt(9)
	v_mfma_f32_16x16x32_bf16 v[62:65], v[74:77], v[106:109], v[62:65]
	v_mfma_f32_16x16x32_bf16 v[66:69], v[94:97], v[106:109], v[66:69]
	s_waitcnt lgkmcnt(8)
	v_mfma_f32_16x16x32_bf16 v[26:29], v[74:77], v[110:113], v[26:29]
	v_mfma_f32_16x16x32_bf16 v[38:41], v[94:97], v[110:113], v[38:41]
	s_waitcnt lgkmcnt(3)
	v_mfma_f32_16x16x32_bf16 v[74:77], v[42:45], v[70:73], v[82:85]
	v_mfma_f32_16x16x32_bf16 v[50:53], v[46:49], v[70:73], v[50:53]
	s_waitcnt lgkmcnt(2)
	v_mfma_f32_16x16x32_bf16 v[54:57], v[42:45], v[78:81], v[54:57]
	v_mfma_f32_16x16x32_bf16 v[58:61], v[46:49], v[78:81], v[58:61]
	s_waitcnt lgkmcnt(1)
	v_mfma_f32_16x16x32_bf16 v[62:65], v[42:45], v[86:89], v[62:65]
	v_mfma_f32_16x16x32_bf16 v[66:69], v[46:49], v[86:89], v[66:69]
	s_waitcnt lgkmcnt(0)
	v_mfma_f32_16x16x32_bf16 v[26:29], v[42:45], v[90:93], v[26:29]
	v_mfma_f32_16x16x32_bf16 v[38:41], v[46:49], v[90:93], v[38:41]
	s_mov_b32 s6, 0x3b000000
	v_mul_u32_u24_e32 v17, 0x420, v17
	v_pk_mul_f32 v[44:45], v[76:77], s[6:7] op_sel_hi:[1,0]
	v_pk_mul_f32 v[42:43], v[74:75], s[6:7] op_sel_hi:[1,0]
	v_readlane_b32 s7, v255, 4
	s_barrier
	s_nop 0
	v_add3_u32 v17, s7, v21, v17
	ds_write_b128 v17, v[42:45]
	v_pk_mul_f32 v[44:45], v[52:53], s[6:7] op_sel_hi:[1,0]
	v_pk_mul_f32 v[42:43], v[50:51], s[6:7] op_sel_hi:[1,0]
	v_and_b32_e32 v31, 0xffff0000, v12
	ds_write_b128 v17, v[42:45] offset:64
	v_pk_mul_f32 v[44:45], v[56:57], s[6:7] op_sel_hi:[1,0]
	v_pk_mul_f32 v[42:43], v[54:55], s[6:7] op_sel_hi:[1,0]
	v_mul_f32_e32 v19, 0xbfb8aa3b, v31
	ds_write_b128 v17, v[42:45] offset:16896
	v_pk_mul_f32 v[44:45], v[60:61], s[6:7] op_sel_hi:[1,0]
	v_pk_mul_f32 v[42:43], v[58:59], s[6:7] op_sel_hi:[1,0]
	v_pk_mul_f32 v[28:29], v[28:29], s[6:7] op_sel_hi:[1,0]
	v_pk_mul_f32 v[26:27], v[26:27], s[6:7] op_sel_hi:[1,0]
	v_exp_f32_e32 v19, v19
	ds_write_b128 v17, v[42:45] offset:16960
	v_pk_mul_f32 v[44:45], v[64:65], s[6:7] op_sel_hi:[1,0]
	v_pk_mul_f32 v[42:43], v[62:63], s[6:7] op_sel_hi:[1,0]
	ds_write_b128 v17, v[26:29] offset:50688
	v_pk_mul_f32 v[28:29], v[40:41], s[6:7] op_sel_hi:[1,0]
	v_pk_mul_f32 v[26:27], v[38:39], s[6:7] op_sel_hi:[1,0]
	s_movk_i32 s8, 0x108
	v_lshlrev_b32_e32 v30, 16, v12
	ds_write_b128 v17, v[42:45] offset:33792
	v_pk_mul_f32 v[44:45], v[68:69], s[6:7] op_sel_hi:[1,0]
	v_pk_mul_f32 v[42:43], v[66:67], s[6:7] op_sel_hi:[1,0]
	ds_write_b128 v17, v[26:29] offset:50752
	v_mad_u64_u32 v[26:27], s[6:7], v24, s8, v[16:17]
	v_mul_f32_e32 v12, 0xbfb8aa3b, v30
	v_lshlrev_b32_e32 v34, 16, v13
	ds_write_b128 v17, v[42:45] offset:33856
	v_lshl_add_u32 v17, v26, 2, 0
	v_exp_f32_e32 v12, v12
	v_and_b32_e32 v35, 0xffff0000, v13
	v_mul_f32_e32 v13, 0xbfb8aa3b, v34
	s_waitcnt lgkmcnt(0)
	s_barrier
	ds_read_b128 v[26:29], v17
	ds_read_b128 v[38:41], v17 offset:16
	v_add_f32_e32 v17, 1.0, v19
	v_exp_f32_e32 v19, v13
	v_mul_f32_e32 v13, 0xbfb8aa3b, v35
	v_exp_f32_e32 v21, v13
	v_add_f32_e32 v12, 1.0, v12
	v_rcp_f32_e32 v12, v12
	v_rcp_f32_e32 v13, v17
	v_add_f32_e32 v17, 1.0, v19
	v_rcp_f32_e32 v42, v17
	v_add_f32_e32 v17, 1.0, v21
	v_rcp_f32_e32 v43, v17
	v_pk_mul_f32 v[12:13], v[12:13], v[30:31]
	s_mov_b32 s12, 0x18c00000
	s_waitcnt lgkmcnt(1)
	v_pk_mul_f32 v[12:13], v[12:13], v[26:27]
	s_nop 0
	v_cvt_pk_bf16_f32 v26, v12, v13
	v_pk_mul_f32 v[12:13], v[42:43], v[34:35]
	v_lshlrev_b32_e32 v34, 16, v9
	v_pk_mul_f32 v[12:13], v[12:13], v[28:29]
	v_lshlrev_b32_e32 v28, 16, v14
	v_and_b32_e32 v29, 0xffff0000, v14
	v_mul_f32_e32 v14, 0xbfb8aa3b, v28
	v_exp_f32_e32 v14, v14
	v_mul_f32_e32 v17, 0xbfb8aa3b, v29
	v_exp_f32_e32 v17, v17
	v_cvt_pk_bf16_f32 v27, v12, v13
	v_add_f32_e32 v12, 1.0, v14
	v_lshlrev_b32_e32 v14, 16, v15
	v_add_f32_e32 v13, 1.0, v17
	v_and_b32_e32 v15, 0xffff0000, v15
	v_mul_f32_e32 v17, 0xbfb8aa3b, v14
	v_exp_f32_e32 v17, v17
	v_mul_f32_e32 v19, 0xbfb8aa3b, v15
	v_exp_f32_e32 v19, v19
	v_rcp_f32_e32 v12, v12
	v_rcp_f32_e32 v13, v13
	v_add_f32_e32 v17, 1.0, v17
	v_rcp_f32_e32 v30, v17
	v_add_f32_e32 v17, 1.0, v19
	v_rcp_f32_e32 v31, v17
	v_pk_mul_f32 v[12:13], v[12:13], v[28:29]
	v_and_b32_e32 v35, 0xffff0000, v9
	s_waitcnt lgkmcnt(0)
	v_pk_mul_f32 v[12:13], v[12:13], v[38:39]
	v_mul_f32_e32 v9, 0xbfb8aa3b, v34
	v_cvt_pk_bf16_f32 v28, v12, v13
	v_pk_mul_f32 v[12:13], v[30:31], v[14:15]
	v_lshl_add_u32 v14, v24, 6, s0
	v_pk_mul_f32 v[12:13], v[12:13], v[40:41]
	s_nop 0
	v_cvt_pk_bf16_f32 v29, v12, v13
	v_mov_b64_e32 v[12:13], s[48:49]
	v_mad_i64_i32 v[14:15], s[6:7], v14, s44, v[12:13]
	v_lshl_add_u64 v[14:15], v[14:15], 0, v[32:33]
	v_add_co_u32_e32 v14, vcc, s12, v14
	s_nop 1
	v_addc_co_u32_e32 v15, vcc, 0, v15, vcc
	global_store_dwordx4 v[14:15], v[26:29], off offset:2048 nt
	v_mad_u64_u32 v[14:15], s[6:7], v22, s8, v[16:17]
	v_and_b32_e32 v15, 0xffff0000, v8
	v_mul_f32_e32 v19, 0xbfb8aa3b, v15
	v_exp_f32_e32 v19, v19
	v_lshl_add_u32 v17, v14, 2, 0
	v_lshlrev_b32_e32 v14, 16, v8
	v_mul_f32_e32 v8, 0xbfb8aa3b, v14
	v_exp_f32_e32 v8, v8
	ds_read_b128 v[24:27], v17
	ds_read_b128 v[28:31], v17 offset:16
	v_add_f32_e32 v17, 1.0, v19
	v_exp_f32_e32 v19, v9
	v_mul_f32_e32 v9, 0xbfb8aa3b, v35
	v_exp_f32_e32 v21, v9
	v_add_f32_e32 v8, 1.0, v8
	v_rcp_f32_e32 v8, v8
	v_rcp_f32_e32 v9, v17
	v_add_f32_e32 v17, 1.0, v19
	v_rcp_f32_e32 v38, v17
	v_add_f32_e32 v17, 1.0, v21
	v_rcp_f32_e32 v39, v17
	v_pk_mul_f32 v[8:9], v[8:9], v[14:15]
	v_pk_mul_f32 v[14:15], v[38:39], v[34:35]
	s_waitcnt lgkmcnt(1)
	v_pk_mul_f32 v[8:9], v[8:9], v[24:25]
	v_lshlrev_b32_e32 v24, 16, v10
	v_cvt_pk_bf16_f32 v8, v8, v9
	v_and_b32_e32 v25, 0xffff0000, v10
	v_mul_f32_e32 v9, 0xbfb8aa3b, v24
	v_pk_mul_f32 v[14:15], v[14:15], v[26:27]
	v_exp_f32_e32 v10, v9
	v_mul_f32_e32 v9, 0xbfb8aa3b, v25
	v_exp_f32_e32 v17, v9
	v_cvt_pk_bf16_f32 v9, v14, v15
	v_lshlrev_b32_e32 v14, 16, v11
	v_and_b32_e32 v15, 0xffff0000, v11
	v_mul_f32_e32 v11, 0xbfb8aa3b, v14
	v_exp_f32_e32 v19, v11
	v_mul_f32_e32 v11, 0xbfb8aa3b, v15
	v_exp_f32_e32 v21, v11
	v_add_f32_e32 v17, 1.0, v17
	v_rcp_f32_e32 v11, v17
	v_add_f32_e32 v17, 1.0, v19
	v_add_f32_e32 v10, 1.0, v10
	v_rcp_f32_e32 v26, v17
	v_add_f32_e32 v17, 1.0, v21
	v_rcp_f32_e32 v10, v10
	v_rcp_f32_e32 v27, v17
	v_pk_mul_f32 v[10:11], v[10:11], v[24:25]
	v_pk_mul_f32 v[14:15], v[26:27], v[14:15]
	s_waitcnt lgkmcnt(0)
	v_pk_mul_f32 v[10:11], v[10:11], v[28:29]
	v_pk_mul_f32 v[14:15], v[14:15], v[30:31]
	v_cvt_pk_bf16_f32 v10, v10, v11
	v_cvt_pk_bf16_f32 v11, v14, v15
	v_lshl_add_u32 v14, v22, 6, s0
	v_mad_i64_i32 v[14:15], s[6:7], v14, s44, v[12:13]
	v_lshl_add_u64 v[14:15], v[14:15], 0, v[32:33]
	v_add_co_u32_e32 v14, vcc, s12, v14
	v_lshlrev_b32_e32 v26, 16, v5
	s_nop 0
	v_addc_co_u32_e32 v15, vcc, 0, v15, vcc
	global_store_dwordx4 v[14:15], v[8:11], off offset:2048 nt
	v_and_b32_e32 v15, 0xffff0000, v4
	v_lshlrev_b32_e32 v14, 16, v4
	v_mad_u64_u32 v[8:9], s[6:7], v20, s8, v[16:17]
	v_lshl_add_u32 v17, v8, 2, 0
	v_mul_f32_e32 v8, 0xbfb8aa3b, v15
	v_exp_f32_e32 v19, v8
	v_mul_f32_e32 v4, 0xbfb8aa3b, v14
	v_and_b32_e32 v27, 0xffff0000, v5
	v_mul_f32_e32 v5, 0xbfb8aa3b, v26
	v_exp_f32_e32 v4, v4
	ds_read_b128 v[8:11], v17
	ds_read_b128 v[22:25], v17 offset:16
	v_add_f32_e32 v17, 1.0, v19
	v_exp_f32_e32 v19, v5
	v_mul_f32_e32 v5, 0xbfb8aa3b, v27
	v_exp_f32_e32 v21, v5
	v_add_f32_e32 v4, 1.0, v4
	v_rcp_f32_e32 v5, v17
	v_add_f32_e32 v17, 1.0, v19
	v_rcp_f32_e32 v4, v4
	v_rcp_f32_e32 v28, v17
	v_add_f32_e32 v17, 1.0, v21
	v_rcp_f32_e32 v29, v17
	v_pk_mul_f32 v[4:5], v[4:5], v[14:15]
	s_waitcnt lgkmcnt(1)
	v_pk_mul_f32 v[4:5], v[4:5], v[8:9]
	v_pk_mul_f32 v[8:9], v[28:29], v[26:27]
	v_cvt_pk_bf16_f32 v4, v4, v5
	v_pk_mul_f32 v[8:9], v[8:9], v[10:11]
	v_lshlrev_b32_e32 v10, 16, v6
	v_and_b32_e32 v11, 0xffff0000, v6
	v_mul_f32_e32 v5, 0xbfb8aa3b, v10
	v_exp_f32_e32 v6, v5
	v_mul_f32_e32 v5, 0xbfb8aa3b, v11
	v_exp_f32_e32 v14, v5
	v_cvt_pk_bf16_f32 v5, v8, v9
	v_lshlrev_b32_e32 v8, 16, v7
	v_and_b32_e32 v9, 0xffff0000, v7
	v_mul_f32_e32 v7, 0xbfb8aa3b, v8
	v_exp_f32_e32 v15, v7
	v_mul_f32_e32 v7, 0xbfb8aa3b, v9
	v_exp_f32_e32 v17, v7
	v_add_f32_e32 v14, 1.0, v14
	v_add_f32_e32 v6, 1.0, v6
	v_rcp_f32_e32 v7, v14
	v_add_f32_e32 v14, 1.0, v15
	v_add_f32_e32 v15, 1.0, v17
	v_rcp_f32_e32 v6, v6
	v_rcp_f32_e32 v14, v14
	v_rcp_f32_e32 v15, v15
	v_pk_mul_f32 v[6:7], v[6:7], v[10:11]
	s_waitcnt lgkmcnt(0)
	v_pk_mul_f32 v[6:7], v[6:7], v[22:23]
	v_pk_mul_f32 v[8:9], v[14:15], v[8:9]
	v_cvt_pk_bf16_f32 v6, v6, v7
	v_pk_mul_f32 v[8:9], v[8:9], v[24:25]
	v_and_b32_e32 v15, 0xffff0000, v0
	v_cvt_pk_bf16_f32 v7, v8, v9
	v_lshl_add_u32 v8, v20, 6, s0
	v_mad_i64_i32 v[8:9], s[6:7], v8, s44, v[12:13]
	v_lshl_add_u64 v[8:9], v[8:9], 0, v[32:33]
	v_add_co_u32_e32 v8, vcc, s12, v8
	v_lshlrev_b32_e32 v14, 16, v0
	s_nop 0
	v_addc_co_u32_e32 v9, vcc, 0, v9, vcc
	global_store_dwordx4 v[8:9], v[4:7], off offset:2048 nt
	v_mul_f32_e32 v0, 0xbfb8aa3b, v14
	v_exp_f32_e32 v0, v0
	v_mad_u64_u32 v[4:5], s[6:7], v18, s8, v[16:17]
	v_lshl_add_u32 v8, v4, 2, 0
	v_mul_f32_e32 v4, 0xbfb8aa3b, v15
	v_exp_f32_e32 v16, v4
	v_and_b32_e32 v17, 0xffff0000, v1
	v_add_f32_e32 v0, 1.0, v0
	v_rcp_f32_e32 v0, v0
	v_add_f32_e32 v19, 1.0, v16
	v_lshlrev_b32_e32 v16, 16, v1
	v_mul_f32_e32 v1, 0xbfb8aa3b, v16
	v_exp_f32_e32 v20, v1
	v_mul_f32_e32 v1, 0xbfb8aa3b, v17
	v_exp_f32_e32 v21, v1
	v_rcp_f32_e32 v1, v19
	v_add_f32_e32 v19, 1.0, v20
	v_rcp_f32_e32 v20, v19
	v_add_f32_e32 v19, 1.0, v21
	ds_read_b128 v[4:7], v8
	ds_read_b128 v[8:11], v8 offset:16
	v_rcp_f32_e32 v21, v19
	v_pk_mul_f32 v[0:1], v[0:1], v[14:15]
	s_waitcnt lgkmcnt(1)
	v_pk_mul_f32 v[0:1], v[0:1], v[4:5]
	v_pk_mul_f32 v[4:5], v[20:21], v[16:17]
	v_cvt_pk_bf16_f32 v0, v0, v1
	v_pk_mul_f32 v[4:5], v[4:5], v[6:7]
	v_lshlrev_b32_e32 v6, 16, v2
	v_and_b32_e32 v7, 0xffff0000, v2
	v_mul_f32_e32 v1, 0xbfb8aa3b, v6
	v_exp_f32_e32 v2, v1
	v_mul_f32_e32 v1, 0xbfb8aa3b, v7
	v_exp_f32_e32 v14, v1
	v_cvt_pk_bf16_f32 v1, v4, v5
	v_lshlrev_b32_e32 v4, 16, v3
	v_and_b32_e32 v5, 0xffff0000, v3
	v_mul_f32_e32 v3, 0xbfb8aa3b, v4
	v_exp_f32_e32 v15, v3
	v_mul_f32_e32 v3, 0xbfb8aa3b, v5
	v_exp_f32_e32 v16, v3
	v_add_f32_e32 v14, 1.0, v14
	v_add_f32_e32 v2, 1.0, v2
	v_rcp_f32_e32 v3, v14
	v_add_f32_e32 v14, 1.0, v15
	v_add_f32_e32 v15, 1.0, v16
	v_rcp_f32_e32 v2, v2
	v_rcp_f32_e32 v14, v14
	v_rcp_f32_e32 v15, v15
	v_pk_mul_f32 v[2:3], v[2:3], v[6:7]
	s_waitcnt lgkmcnt(0)
	v_pk_mul_f32 v[2:3], v[2:3], v[8:9]
	v_pk_mul_f32 v[4:5], v[14:15], v[4:5]
	v_cvt_pk_bf16_f32 v2, v2, v3
	v_pk_mul_f32 v[4:5], v[4:5], v[10:11]
	s_nop 0
	v_cvt_pk_bf16_f32 v3, v4, v5
	v_lshl_add_u32 v4, v18, 6, s0
	v_mad_i64_i32 v[4:5], s[6:7], v4, s44, v[12:13]
	v_lshl_add_u64 v[4:5], v[4:5], 0, v[32:33]
	v_add_co_u32_e32 v4, vcc, 0x18c00000, v4
	s_nop 1
	v_addc_co_u32_e32 v5, vcc, 0, v5, vcc
	global_store_dwordx4 v[4:5], v[0:3], off offset:2048 nt

.LBB0_739:
	s_and_b32 s6, s18, 0xf0
	v_or_b32_e32 v8, s6, v35
	v_or_b32_e32 v8, s0, v8
	v_or_b32_e32 v12, 0x4000, v8
	v_lshrrev_b32_e32 v8, 2, v206
	v_lshlrev_b32_e32 v32, 13, v12
	v_and_b32_e32 v20, 12, v8
	v_lshl_add_u64 v[8:9], s[70:71], 0, v[32:33]
	s_mov_b64 s[6:7], 0x1e00
	v_lshl_add_u64 v[10:11], v[8:9], 0, s[6:7]
	v_mov_b64_e32 v[8:9], s[48:49]
	v_readlane_b32 s0, v254, 50
	v_mad_u64_u32 v[8:9], s[6:7], v12, s44, v[8:9]
	s_nop 0
	v_or_b32_e32 v12, s0, v20
	v_ashrrev_i32_e32 v13, 31, v12
	v_lshlrev_b64 v[12:13], 1, v[12:13]
	v_lshl_add_u64 v[14:15], v[10:11], 0, v[12:13]
	global_load_dwordx2 v[14:15], v[14:15], off
	s_brev_b32 s0, 60
	v_pk_mul_f32 v[4:5], v[4:5], s[0:1] op_sel_hi:[1,0]
	s_mov_b64 s[6:7], 0x18c00800
	v_pk_mul_f32 v[6:7], v[6:7], s[0:1] op_sel_hi:[1,0]
	v_lshl_add_u64 v[8:9], v[8:9], 0, s[6:7]
	v_readlane_b32 s6, v254, 51
	v_pk_mul_f32 v[0:1], v[0:1], s[0:1] op_sel_hi:[1,0]
	v_pk_mul_f32 v[2:3], v[2:3], s[0:1] op_sel_hi:[1,0]
	s_mov_b32 s18, s94
	s_waitcnt vmcnt(0)
	v_lshlrev_b32_e32 v16, 16, v14
	v_and_b32_e32 v17, 0xffff0000, v14
	v_mul_f32_e32 v14, 0xbfb8aa3b, v16
	v_exp_f32_e32 v14, v14
	s_nop 0
	v_add_f32_e32 v14, 1.0, v14
	v_rcp_f32_e32 v18, v14
	v_mul_f32_e32 v14, 0xbfb8aa3b, v17
	v_exp_f32_e32 v14, v14
	s_nop 0
	v_add_f32_e32 v14, 1.0, v14
	v_rcp_f32_e32 v19, v14
	v_lshlrev_b32_e32 v14, 16, v15
	v_and_b32_e32 v15, 0xffff0000, v15
	v_pk_mul_f32 v[16:17], v[18:19], v[16:17]
	s_nop 0
	v_pk_mul_f32 v[4:5], v[4:5], v[16:17]
	s_nop 0
	v_cvt_pk_bf16_f32 v4, v4, v5
	v_mul_f32_e32 v5, 0xbfb8aa3b, v14
	v_exp_f32_e32 v5, v5
	s_nop 0
	v_add_f32_e32 v5, 1.0, v5
	v_rcp_f32_e32 v16, v5
	v_mul_f32_e32 v5, 0xbfb8aa3b, v15
	v_exp_f32_e32 v5, v5
	s_nop 0
	v_add_f32_e32 v5, 1.0, v5
	v_rcp_f32_e32 v17, v5
	s_nop 0
	v_pk_mul_f32 v[14:15], v[16:17], v[14:15]
	s_nop 0
	v_pk_mul_f32 v[6:7], v[6:7], v[14:15]
	s_nop 0
	v_cvt_pk_bf16_f32 v5, v6, v7
	v_lshl_add_u64 v[6:7], v[8:9], 0, v[12:13]
	global_store_dwordx2 v[6:7], v[4:5], off nt
	v_or_b32_e32 v4, s6, v20
	v_ashrrev_i32_e32 v5, 31, v4
	v_lshlrev_b64 v[4:5], 1, v[4:5]
	v_lshl_add_u64 v[6:7], v[10:11], 0, v[4:5]
	global_load_dwordx2 v[6:7], v[6:7], off
	s_mov_b64 s[6:7], s[76:77]
	s_waitcnt vmcnt(0)
	v_lshlrev_b32_e32 v10, 16, v6
	v_and_b32_e32 v11, 0xffff0000, v6
	v_mul_f32_e32 v6, 0xbfb8aa3b, v10
	v_exp_f32_e32 v6, v6
	s_nop 0
	v_add_f32_e32 v6, 1.0, v6
	v_rcp_f32_e32 v12, v6
	v_mul_f32_e32 v6, 0xbfb8aa3b, v11
	v_exp_f32_e32 v6, v6
	s_nop 0
	v_add_f32_e32 v6, 1.0, v6
	v_rcp_f32_e32 v13, v6
	v_lshlrev_b32_e32 v6, 16, v7
	v_and_b32_e32 v7, 0xffff0000, v7
	v_pk_mul_f32 v[10:11], v[12:13], v[10:11]
	s_nop 0
	v_pk_mul_f32 v[0:1], v[0:1], v[10:11]
	s_nop 0
	v_cvt_pk_bf16_f32 v0, v0, v1
	v_mul_f32_e32 v1, 0xbfb8aa3b, v6
	v_exp_f32_e32 v1, v1
	s_nop 0
	v_add_f32_e32 v1, 1.0, v1
	v_rcp_f32_e32 v10, v1
	v_mul_f32_e32 v1, 0xbfb8aa3b, v7
	v_exp_f32_e32 v1, v1
	s_nop 0
	v_add_f32_e32 v1, 1.0, v1
	v_rcp_f32_e32 v11, v1
	s_nop 0
	v_pk_mul_f32 v[6:7], v[10:11], v[6:7]
	s_nop 0
	v_pk_mul_f32 v[2:3], v[2:3], v[6:7]
	s_nop 0
	v_cvt_pk_bf16_f32 v1, v2, v3
	v_lshl_add_u64 v[2:3], v[8:9], 0, v[4:5]
	global_store_dwordx2 v[2:3], v[0:1], off nt

.LBB0_760:
	v_lshrrev_b32_e32 v17, 3, v207
	s_waitcnt vmcnt(3)
	v_or_b32_e32 v122, s9, v17
	v_lshlrev_b32_e32 v18, 3, v207
	v_ashrrev_i32_e32 v123, 31, v122
	v_or_b32_e32 v120, 8, v122
	v_and_b32_e32 v37, 56, v18
	v_lshlrev_b64 v[18:19], 13, v[122:123]
	v_ashrrev_i32_e32 v121, 31, v120
	v_lshl_add_u64 v[18:19], s[70:71], 0, v[18:19]
	s_lshl_b32 s92, s8, 1
	v_lshlrev_b64 v[34:35], 13, v[120:121]
	v_lshl_add_u64 v[18:19], v[18:19], 0, s[92:93]
	v_lshlrev_b32_e32 v32, 1, v37
	v_lshl_add_u64 v[34:35], s[70:71], 0, v[34:35]
	v_lshl_add_u64 v[18:19], v[18:19], 0, v[32:33]
	v_lshl_add_u64 v[34:35], v[34:35], 0, s[92:93]
	v_lshl_add_u64 v[34:35], v[34:35], 0, v[32:33]
	global_load_dwordx4 v[114:117], v[18:19], off offset:1536
	global_load_dwordx4 v[110:113], v[34:35], off offset:1536
	v_or_b32_e32 v118, 16, v122
	v_or_b32_e32 v74, 24, v122
	v_ashrrev_i32_e32 v119, 31, v118
	v_ashrrev_i32_e32 v75, 31, v74
	v_lshlrev_b64 v[18:19], 13, v[118:119]
	v_lshlrev_b64 v[34:35], 13, v[74:75]
	v_lshl_add_u64 v[18:19], s[70:71], 0, v[18:19]
	v_lshl_add_u64 v[34:35], s[70:71], 0, v[34:35]
	v_lshl_add_u64 v[18:19], v[18:19], 0, s[92:93]
	v_lshl_add_u64 v[34:35], v[34:35], 0, s[92:93]
	v_or_b32_e32 v46, 32, v122
	v_or_b32_e32 v38, 40, v122
	v_lshl_add_u64 v[18:19], v[18:19], 0, v[32:33]
	v_lshl_add_u64 v[34:35], v[34:35], 0, v[32:33]
	v_ashrrev_i32_e32 v47, 31, v46
	v_ashrrev_i32_e32 v39, 31, v38
	global_load_dwordx4 v[104:107], v[18:19], off offset:1536
	global_load_dwordx4 v[100:103], v[34:35], off offset:1536
	v_lshlrev_b64 v[18:19], 13, v[46:47]
	v_lshlrev_b64 v[34:35], 13, v[38:39]
	v_lshl_add_u64 v[18:19], s[70:71], 0, v[18:19]
	v_lshl_add_u64 v[34:35], s[70:71], 0, v[34:35]
	v_lshl_add_u64 v[18:19], v[18:19], 0, s[92:93]
	v_lshl_add_u64 v[34:35], v[34:35], 0, s[92:93]
	v_lshl_add_u64 v[18:19], v[18:19], 0, v[32:33]
	v_lshl_add_u64 v[34:35], v[34:35], 0, v[32:33]
	global_load_dwordx4 v[96:99], v[18:19], off offset:1536
	global_load_dwordx4 v[92:95], v[34:35], off offset:1536
	v_or_b32_e32 v34, 48, v122
	v_ashrrev_i32_e32 v35, 31, v34
	v_lshlrev_b64 v[18:19], 13, v[34:35]
	v_lshl_add_u64 v[18:19], s[70:71], 0, v[18:19]
	v_lshl_add_u64 v[18:19], v[18:19], 0, s[92:93]
	v_lshl_add_u64 v[66:67], v[18:19], 0, v[32:33]
	v_or_b32_e32 v18, 56, v122
	v_ashrrev_i32_e32 v19, 31, v18
	v_lshlrev_b64 v[68:69], 13, v[18:19]
	v_div_scale_f32 v19, s[6:7], v108, v108, 1.0
	v_rcp_f32_e32 v35, v19
	v_lshl_add_u64 v[68:69], s[70:71], 0, v[68:69]
	v_readlane_b32 s8, v254, 45
	v_lshl_add_u64 v[68:69], v[68:69], 0, s[92:93]
	v_fma_f32 v39, -v19, v35, 1.0
	v_fmac_f32_e32 v35, v39, v35
	v_div_scale_f32 v39, vcc, 1.0, v108, 1.0
	v_mul_f32_e32 v45, v39, v35
	v_fma_f32 v47, -v19, v45, v39
	v_fmac_f32_e32 v45, v47, v35
	v_fma_f32 v19, -v19, v45, v39
	v_div_fmas_f32 v19, v19, v35, v45
	v_div_scale_f32 v35, s[6:7], v64, v64, 1.0
	v_rcp_f32_e32 v39, v35
	v_div_fixup_f32 v108, v19, v108, 1.0
	v_add3_u32 v19, s8, v208, v209
	v_lshl_add_u64 v[68:69], v[68:69], 0, v[32:33]
	v_fma_f32 v45, -v35, v39, 1.0
	v_fmac_f32_e32 v39, v45, v39
	v_div_scale_f32 v45, vcc, 1.0, v64, 1.0
	v_mul_f32_e32 v47, v45, v39
	v_fma_f32 v65, -v35, v47, v45
	v_fmac_f32_e32 v47, v65, v39
	v_fma_f32 v35, -v35, v47, v45
	v_div_fmas_f32 v35, v35, v39, v47
	v_div_fixup_f32 v64, v35, v64, 1.0
	v_pk_mul_f32 v[62:63], v[64:65], v[62:63] op_sel_hi:[0,1]
	v_pk_mul_f32 v[60:61], v[64:65], v[60:61] op_sel_hi:[0,1]
	v_pk_mul_f32 v[50:51], v[64:65], v[50:51] op_sel_hi:[0,1]
	v_pk_mul_f32 v[48:49], v[64:65], v[48:49] op_sel_hi:[0,1]
	v_div_scale_f32 v39, s[6:7], v44, v44, 1.0
	v_cvt_pk_bf16_f32 v60, v60, v61
	v_cvt_pk_bf16_f32 v61, v62, v63
	v_cvt_pk_bf16_f32 v48, v48, v49
	v_cvt_pk_bf16_f32 v49, v50, v51
	v_add_u32_e32 v35, 0x800, v19
	v_rcp_f32_e32 v45, v39
	global_load_dwordx4 v[70:73], v[66:67], off offset:1536
	s_nop 0
	global_load_dwordx4 v[66:69], v[68:69], off offset:1536
	s_barrier
	ds_write2_b64 v35, v[60:61], v[48:49] offset0:32 offset1:36
	v_pk_mul_f32 v[48:49], v[64:65], v[58:59] op_sel_hi:[0,1]
	v_pk_mul_f32 v[50:51], v[64:65], v[56:57] op_sel_hi:[0,1]
	v_cvt_pk_bf16_f32 v50, v50, v51
	v_cvt_pk_bf16_f32 v51, v48, v49
	v_pk_mul_f32 v[48:49], v[64:65], v[54:55] op_sel_hi:[0,1]
	v_pk_mul_f32 v[52:53], v[64:65], v[52:53] op_sel_hi:[0,1]
	v_cvt_pk_bf16_f32 v52, v52, v53
	v_cvt_pk_bf16_f32 v53, v48, v49
	ds_write2_b64 v35, v[50:51], v[52:53] offset0:40 offset1:44
	v_fma_f32 v35, -v39, v45, 1.0
	v_fmac_f32_e32 v45, v35, v45
	v_div_scale_f32 v35, vcc, 1.0, v44, 1.0
	v_mul_f32_e32 v47, v35, v45
	v_fma_f32 v48, -v39, v47, v35
	v_fmac_f32_e32 v47, v48, v45
	v_fma_f32 v35, -v39, v47, v35
	v_div_fmas_f32 v35, v35, v45, v47
	v_div_fixup_f32 v44, v35, v44, 1.0
	v_pk_mul_f32 v[42:43], v[44:45], v[42:43] op_sel_hi:[0,1]
	v_pk_mul_f32 v[40:41], v[44:45], v[40:41] op_sel_hi:[0,1]
	v_pk_mul_f32 v[22:23], v[44:45], v[22:23] op_sel_hi:[0,1]
	v_pk_mul_f32 v[20:21], v[44:45], v[20:21] op_sel_hi:[0,1]
	v_cvt_pk_bf16_f32 v40, v40, v41
	v_cvt_pk_bf16_f32 v41, v42, v43
	v_cvt_pk_bf16_f32 v20, v20, v21
	v_cvt_pk_bf16_f32 v21, v22, v23
	v_add_u32_e32 v35, 0x1000, v19
	ds_write2_b64 v35, v[40:41], v[20:21] offset0:64 offset1:68
	v_pk_mul_f32 v[20:21], v[44:45], v[30:31] op_sel_hi:[0,1]
	v_pk_mul_f32 v[22:23], v[44:45], v[28:29] op_sel_hi:[0,1]
	v_cvt_pk_bf16_f32 v22, v22, v23
	v_cvt_pk_bf16_f32 v23, v20, v21
	v_pk_mul_f32 v[20:21], v[44:45], v[26:27] op_sel_hi:[0,1]
	v_div_scale_f32 v26, s[6:7], v16, v16, 1.0
	v_rcp_f32_e32 v27, v26
	v_pk_mul_f32 v[24:25], v[44:45], v[24:25] op_sel_hi:[0,1]
	v_cvt_pk_bf16_f32 v24, v24, v25
	v_cvt_pk_bf16_f32 v25, v20, v21
	v_fma_f32 v20, -v26, v27, 1.0
	v_fmac_f32_e32 v27, v20, v27
	v_div_scale_f32 v20, vcc, 1.0, v16, 1.0
	v_mul_f32_e32 v21, v20, v27
	ds_write2_b64 v35, v[22:23], v[24:25] offset0:72 offset1:76
	v_fma_f32 v22, -v26, v21, v20
	v_fmac_f32_e32 v21, v22, v27
	v_fma_f32 v20, -v26, v21, v20
	v_div_fmas_f32 v20, v20, v27, v21
	v_div_fixup_f32 v16, v20, v16, 1.0
	v_pk_mul_f32 v[10:11], v[16:17], v[10:11] op_sel_hi:[0,1]
	v_pk_mul_f32 v[8:9], v[16:17], v[8:9] op_sel_hi:[0,1]
	v_pk_mul_f32 v[2:3], v[16:17], v[2:3] op_sel_hi:[0,1]
	v_pk_mul_f32 v[0:1], v[16:17], v[0:1] op_sel_hi:[0,1]
	v_cvt_pk_bf16_f32 v8, v8, v9
	v_cvt_pk_bf16_f32 v9, v10, v11
	v_cvt_pk_bf16_f32 v0, v0, v1
	v_cvt_pk_bf16_f32 v1, v2, v3
	v_add_u32_e32 v10, 0x1800, v19
	v_readlane_b32 s0, v254, 46
	ds_write2_b64 v10, v[8:9], v[0:1] offset0:96 offset1:100
	v_pk_mul_f32 v[0:1], v[16:17], v[14:15] op_sel_hi:[0,1]
	v_pk_mul_f32 v[2:3], v[16:17], v[12:13] op_sel_hi:[0,1]
	s_add_u32 s6, s0, s92
	v_readlane_b32 s0, v254, 47
	v_cvt_pk_bf16_f32 v2, v2, v3
	v_cvt_pk_bf16_f32 v3, v0, v1
	v_pk_mul_f32 v[0:1], v[16:17], v[6:7] op_sel_hi:[0,1]
	v_pk_mul_f32 v[4:5], v[16:17], v[4:5] op_sel_hi:[0,1]
	s_addc_u32 s7, s0, 0
	s_movk_i32 s0, 0x48
	v_cvt_pk_bf16_f32 v4, v4, v5
	v_cvt_pk_bf16_f32 v5, v0, v1
	v_mad_u32_u24 v0, v17, s0, v37
	ds_write2_b64 v10, v[2:3], v[4:5] offset0:104 offset1:108
	v_lshl_add_u32 v2, v0, 1, s8
	s_waitcnt vmcnt(7)
	v_lshlrev_b32_e32 v0, 16, v114
	v_and_b32_e32 v1, 0xffff0000, v114
	v_mul_f32_e32 v3, 0xbfb8aa3b, v0
	v_pk_mul_f32 v[90:91], v[108:109], v[90:91] op_sel_hi:[0,1]
	v_pk_mul_f32 v[88:89], v[108:109], v[88:89] op_sel_hi:[0,1]
	v_pk_mul_f32 v[78:79], v[108:109], v[78:79] op_sel_hi:[0,1]
	v_pk_mul_f32 v[76:77], v[108:109], v[76:77] op_sel_hi:[0,1]
	v_exp_f32_e32 v3, v3
	v_mul_f32_e32 v4, 0xbfb8aa3b, v1
	v_cvt_pk_bf16_f32 v88, v88, v89
	v_cvt_pk_bf16_f32 v89, v90, v91
	v_cvt_pk_bf16_f32 v76, v76, v77
	v_cvt_pk_bf16_f32 v77, v78, v79
	v_exp_f32_e32 v8, v4
	ds_write2_b64 v19, v[88:89], v[76:77] offset1:4
	v_pk_mul_f32 v[76:77], v[108:109], v[86:87] op_sel_hi:[0,1]
	v_pk_mul_f32 v[78:79], v[108:109], v[84:85] op_sel_hi:[0,1]
	v_cvt_pk_bf16_f32 v78, v78, v79
	v_cvt_pk_bf16_f32 v79, v76, v77
	v_pk_mul_f32 v[76:77], v[108:109], v[82:83] op_sel_hi:[0,1]
	v_pk_mul_f32 v[80:81], v[108:109], v[80:81] op_sel_hi:[0,1]
	v_cvt_pk_bf16_f32 v80, v80, v81
	v_cvt_pk_bf16_f32 v81, v76, v77
	v_add_f32_e32 v3, 1.0, v3
	ds_write2_b64 v19, v[78:79], v[80:81] offset0:8 offset1:12
	v_rcp_f32_e32 v12, v3
	v_add_f32_e32 v3, 1.0, v8
	s_waitcnt lgkmcnt(0)
	v_rcp_f32_e32 v13, v3
	ds_read_b128 v[4:7], v2
	ds_read_b128 v[8:11], v2 offset:1152
	s_mov_b32 s18, s94
	v_pk_mul_f32 v[0:1], v[12:13], v[0:1]
	v_lshlrev_b32_e32 v12, 16, v115
	v_and_b32_e32 v13, 0xffff0000, v115
	v_mul_f32_e32 v3, 0xbfb8aa3b, v12
	s_waitcnt lgkmcnt(1)
	v_lshlrev_b32_e32 v14, 16, v4
	v_and_b32_e32 v15, 0xffff0000, v4
	v_exp_f32_e32 v3, v3
	v_mul_f32_e32 v4, 0xbfb8aa3b, v13
	v_exp_f32_e32 v4, v4
	v_pk_mul_f32 v[0:1], v[0:1], v[14:15]
	v_add_f32_e32 v3, 1.0, v3
	v_rcp_f32_e32 v14, v3
	v_add_f32_e32 v3, 1.0, v4
	v_rcp_f32_e32 v15, v3
	v_cvt_pk_bf16_f32 v4, v0, v1
	v_lshlrev_b32_e32 v0, 16, v5
	v_and_b32_e32 v1, 0xffff0000, v5
	v_pk_mul_f32 v[12:13], v[14:15], v[12:13]
	v_lshlrev_b32_e32 v14, 16, v116
	v_and_b32_e32 v15, 0xffff0000, v116
	v_mul_f32_e32 v3, 0xbfb8aa3b, v14
	v_exp_f32_e32 v3, v3
	v_mul_f32_e32 v5, 0xbfb8aa3b, v15
	v_exp_f32_e32 v5, v5
	v_pk_mul_f32 v[0:1], v[12:13], v[0:1]
	v_add_f32_e32 v3, 1.0, v3
	v_rcp_f32_e32 v12, v3
	v_add_f32_e32 v3, 1.0, v5
	v_rcp_f32_e32 v13, v3
	v_cvt_pk_bf16_f32 v5, v0, v1
	v_lshlrev_b32_e32 v0, 16, v6
	v_and_b32_e32 v1, 0xffff0000, v6
	v_pk_mul_f32 v[12:13], v[12:13], v[14:15]
	v_lshlrev_b32_e32 v14, 16, v117
	v_and_b32_e32 v15, 0xffff0000, v117
	v_mul_f32_e32 v3, 0xbfb8aa3b, v14
	v_exp_f32_e32 v3, v3
	v_mul_f32_e32 v6, 0xbfb8aa3b, v15
	v_exp_f32_e32 v6, v6
	v_pk_mul_f32 v[0:1], v[12:13], v[0:1]
	v_add_f32_e32 v3, 1.0, v3
	v_rcp_f32_e32 v12, v3
	v_add_f32_e32 v3, 1.0, v6
	v_rcp_f32_e32 v13, v3
	v_cvt_pk_bf16_f32 v6, v0, v1
	v_lshlrev_b32_e32 v0, 16, v7
	v_and_b32_e32 v1, 0xffff0000, v7
	v_pk_mul_f32 v[12:13], v[12:13], v[14:15]
	s_waitcnt vmcnt(6)
	v_lshlrev_b32_e32 v14, 16, v110
	v_and_b32_e32 v15, 0xffff0000, v110
	v_mul_f32_e32 v3, 0xbfb8aa3b, v14
	v_exp_f32_e32 v3, v3
	v_mul_f32_e32 v16, 0xbfb8aa3b, v15
	v_pk_mul_f32 v[0:1], v[12:13], v[0:1]
	v_exp_f32_e32 v17, v16
	v_cvt_pk_bf16_f32 v7, v0, v1
	v_mov_b64_e32 v[0:1], s[6:7]
	v_mad_i64_i32 v[12:13], s[6:7], v122, s44, v[0:1]
	v_lshl_add_u64 v[12:13], v[12:13], 0, v[32:33]
	v_add_f32_e32 v3, 1.0, v3
	v_rcp_f32_e32 v16, v3
	v_add_f32_e32 v3, 1.0, v17
	global_store_dwordx4 v[12:13], v[4:7], off nt
	v_lshlrev_b32_e32 v12, 16, v111
	v_rcp_f32_e32 v17, v3
	v_and_b32_e32 v13, 0xffff0000, v111
	v_mul_f32_e32 v3, 0xbfb8aa3b, v12
	s_waitcnt lgkmcnt(0)
	v_lshlrev_b32_e32 v4, 16, v8
	v_and_b32_e32 v5, 0xffff0000, v8
	v_exp_f32_e32 v3, v3
	v_mul_f32_e32 v8, 0xbfb8aa3b, v13
	v_exp_f32_e32 v8, v8
	v_pk_mul_f32 v[6:7], v[16:17], v[14:15]
	v_add_f32_e32 v3, 1.0, v3
	v_pk_mul_f32 v[4:5], v[6:7], v[4:5]
	v_rcp_f32_e32 v6, v3
	v_add_f32_e32 v3, 1.0, v8
	v_rcp_f32_e32 v7, v3
	v_cvt_pk_bf16_f32 v4, v4, v5
	v_lshlrev_b32_e32 v8, 16, v9
	v_and_b32_e32 v9, 0xffff0000, v9
	v_pk_mul_f32 v[6:7], v[6:7], v[12:13]
	v_lshlrev_b32_e32 v12, 16, v112
	v_and_b32_e32 v13, 0xffff0000, v112
	v_mul_f32_e32 v3, 0xbfb8aa3b, v12
	v_exp_f32_e32 v3, v3
	v_mul_f32_e32 v5, 0xbfb8aa3b, v13
	v_exp_f32_e32 v5, v5
	v_pk_mul_f32 v[6:7], v[6:7], v[8:9]
	v_add_f32_e32 v3, 1.0, v3
	v_rcp_f32_e32 v8, v3
	v_add_f32_e32 v3, 1.0, v5
	v_rcp_f32_e32 v9, v3
	v_cvt_pk_bf16_f32 v5, v6, v7
	v_lshlrev_b32_e32 v6, 16, v10
	v_and_b32_e32 v7, 0xffff0000, v10
	v_pk_mul_f32 v[8:9], v[8:9], v[12:13]
	v_lshlrev_b32_e32 v12, 16, v113
	v_and_b32_e32 v13, 0xffff0000, v113
	v_mul_f32_e32 v3, 0xbfb8aa3b, v12
	v_exp_f32_e32 v3, v3
	v_mul_f32_e32 v10, 0xbfb8aa3b, v13
	v_exp_f32_e32 v10, v10
	v_pk_mul_f32 v[6:7], v[8:9], v[6:7]
	v_add_f32_e32 v3, 1.0, v3
	v_rcp_f32_e32 v8, v3
	v_add_f32_e32 v3, 1.0, v10
	v_rcp_f32_e32 v9, v3
	v_lshlrev_b32_e32 v10, 16, v11
	v_and_b32_e32 v11, 0xffff0000, v11
	v_cvt_pk_bf16_f32 v6, v6, v7
	v_pk_mul_f32 v[8:9], v[8:9], v[12:13]
	s_waitcnt vmcnt(6)
	v_lshlrev_b32_e32 v12, 16, v104
	v_pk_mul_f32 v[8:9], v[8:9], v[10:11]
	v_and_b32_e32 v13, 0xffff0000, v104
	v_cvt_pk_bf16_f32 v7, v8, v9
	v_mad_i64_i32 v[8:9], s[6:7], v120, s44, v[0:1]
	v_lshl_add_u64 v[8:9], v[8:9], 0, v[32:33]
	v_mul_f32_e32 v3, 0xbfb8aa3b, v12
	global_store_dwordx4 v[8:9], v[4:7], off nt
	v_exp_f32_e32 v3, v3
	s_nop 0
	v_mul_f32_e32 v4, 0xbfb8aa3b, v13
	v_exp_f32_e32 v8, v4
	v_add_f32_e32 v3, 1.0, v3
	v_rcp_f32_e32 v14, v3
	ds_read_b128 v[4:7], v2 offset:2304
	v_add_f32_e32 v3, 1.0, v8
	v_rcp_f32_e32 v15, v3
	ds_read_b128 v[8:11], v2 offset:3456
	s_waitcnt lgkmcnt(1)
	v_lshlrev_b32_e32 v16, 16, v4
	v_pk_mul_f32 v[12:13], v[14:15], v[12:13]
	v_lshlrev_b32_e32 v14, 16, v105
	v_and_b32_e32 v15, 0xffff0000, v105
	v_mul_f32_e32 v3, 0xbfb8aa3b, v14
	v_and_b32_e32 v17, 0xffff0000, v4
	v_exp_f32_e32 v3, v3
	v_mul_f32_e32 v4, 0xbfb8aa3b, v15
	v_exp_f32_e32 v4, v4
	v_pk_mul_f32 v[12:13], v[12:13], v[16:17]
	v_add_f32_e32 v3, 1.0, v3
	v_rcp_f32_e32 v16, v3
	v_add_f32_e32 v3, 1.0, v4
	v_rcp_f32_e32 v17, v3
	v_cvt_pk_bf16_f32 v4, v12, v13
	v_lshlrev_b32_e32 v12, 16, v5
	v_and_b32_e32 v13, 0xffff0000, v5
	v_pk_mul_f32 v[14:15], v[16:17], v[14:15]
	v_lshlrev_b32_e32 v16, 16, v106
	v_and_b32_e32 v17, 0xffff0000, v106
	v_mul_f32_e32 v3, 0xbfb8aa3b, v16
	v_exp_f32_e32 v3, v3
	v_mul_f32_e32 v5, 0xbfb8aa3b, v17
	v_exp_f32_e32 v5, v5
	v_pk_mul_f32 v[12:13], v[14:15], v[12:13]
	v_add_f32_e32 v3, 1.0, v3
	v_rcp_f32_e32 v14, v3
	v_add_f32_e32 v3, 1.0, v5
	v_rcp_f32_e32 v15, v3
	v_cvt_pk_bf16_f32 v5, v12, v13
	v_lshlrev_b32_e32 v12, 16, v6
	v_and_b32_e32 v13, 0xffff0000, v6
	v_pk_mul_f32 v[14:15], v[14:15], v[16:17]
	v_lshlrev_b32_e32 v16, 16, v107
	v_and_b32_e32 v17, 0xffff0000, v107
	v_mul_f32_e32 v3, 0xbfb8aa3b, v16
	v_exp_f32_e32 v3, v3
	v_mul_f32_e32 v6, 0xbfb8aa3b, v17
	v_exp_f32_e32 v6, v6
	v_pk_mul_f32 v[12:13], v[14:15], v[12:13]
	v_add_f32_e32 v3, 1.0, v3
	v_rcp_f32_e32 v14, v3
	v_add_f32_e32 v3, 1.0, v6
	v_rcp_f32_e32 v15, v3
	v_cvt_pk_bf16_f32 v6, v12, v13
	v_lshlrev_b32_e32 v12, 16, v7
	v_and_b32_e32 v13, 0xffff0000, v7
	v_pk_mul_f32 v[14:15], v[14:15], v[16:17]
	s_nop 0
	v_pk_mul_f32 v[12:13], v[14:15], v[12:13]
	s_waitcnt vmcnt(6)
	v_lshlrev_b32_e32 v14, 16, v100
	v_and_b32_e32 v15, 0xffff0000, v100
	v_mul_f32_e32 v3, 0xbfb8aa3b, v14
	v_exp_f32_e32 v3, v3
	v_mul_f32_e32 v16, 0xbfb8aa3b, v15
	v_exp_f32_e32 v17, v16
	v_cvt_pk_bf16_f32 v7, v12, v13
	v_mad_i64_i32 v[12:13], s[6:7], v118, s44, v[0:1]
	v_lshl_add_u64 v[12:13], v[12:13], 0, v[32:33]
	v_add_f32_e32 v3, 1.0, v3
	v_rcp_f32_e32 v16, v3
	v_add_f32_e32 v3, 1.0, v17
	global_store_dwordx4 v[12:13], v[4:7], off nt
	v_lshlrev_b32_e32 v12, 16, v101
	v_rcp_f32_e32 v17, v3
	v_and_b32_e32 v13, 0xffff0000, v101
	v_mul_f32_e32 v3, 0xbfb8aa3b, v12
	s_waitcnt lgkmcnt(0)
	v_lshlrev_b32_e32 v4, 16, v8
	v_and_b32_e32 v5, 0xffff0000, v8
	v_exp_f32_e32 v3, v3
	v_mul_f32_e32 v8, 0xbfb8aa3b, v13
	v_exp_f32_e32 v8, v8
	v_pk_mul_f32 v[6:7], v[16:17], v[14:15]
	v_add_f32_e32 v3, 1.0, v3
	v_pk_mul_f32 v[4:5], v[6:7], v[4:5]
	v_rcp_f32_e32 v6, v3
	v_add_f32_e32 v3, 1.0, v8
	v_rcp_f32_e32 v7, v3
	v_cvt_pk_bf16_f32 v4, v4, v5
	v_lshlrev_b32_e32 v8, 16, v9
	v_and_b32_e32 v9, 0xffff0000, v9
	v_pk_mul_f32 v[6:7], v[6:7], v[12:13]
	v_lshlrev_b32_e32 v12, 16, v102
	v_and_b32_e32 v13, 0xffff0000, v102
	v_mul_f32_e32 v3, 0xbfb8aa3b, v12
	v_exp_f32_e32 v3, v3
	v_mul_f32_e32 v5, 0xbfb8aa3b, v13
	v_exp_f32_e32 v5, v5
	v_pk_mul_f32 v[6:7], v[6:7], v[8:9]
	v_add_f32_e32 v3, 1.0, v3
	v_rcp_f32_e32 v8, v3
	v_add_f32_e32 v3, 1.0, v5
	v_rcp_f32_e32 v9, v3
	v_cvt_pk_bf16_f32 v5, v6, v7
	v_lshlrev_b32_e32 v6, 16, v10
	v_and_b32_e32 v7, 0xffff0000, v10
	v_pk_mul_f32 v[8:9], v[8:9], v[12:13]
	v_lshlrev_b32_e32 v12, 16, v103
	v_and_b32_e32 v13, 0xffff0000, v103
	v_mul_f32_e32 v3, 0xbfb8aa3b, v12
	v_exp_f32_e32 v3, v3
	v_mul_f32_e32 v10, 0xbfb8aa3b, v13
	v_exp_f32_e32 v10, v10
	v_pk_mul_f32 v[6:7], v[8:9], v[6:7]
	v_add_f32_e32 v3, 1.0, v3
	v_rcp_f32_e32 v8, v3
	v_add_f32_e32 v3, 1.0, v10
	v_rcp_f32_e32 v9, v3
	v_lshlrev_b32_e32 v10, 16, v11
	v_and_b32_e32 v11, 0xffff0000, v11
	v_cvt_pk_bf16_f32 v6, v6, v7
	v_pk_mul_f32 v[8:9], v[8:9], v[12:13]
	s_waitcnt vmcnt(6)
	v_lshlrev_b32_e32 v12, 16, v96
	v_pk_mul_f32 v[8:9], v[8:9], v[10:11]
	v_and_b32_e32 v13, 0xffff0000, v96
	v_cvt_pk_bf16_f32 v7, v8, v9
	v_mad_i64_i32 v[8:9], s[6:7], v74, s44, v[0:1]
	v_lshl_add_u64 v[8:9], v[8:9], 0, v[32:33]
	v_mul_f32_e32 v3, 0xbfb8aa3b, v12
	global_store_dwordx4 v[8:9], v[4:7], off nt
	v_exp_f32_e32 v3, v3
	s_nop 0
	v_mul_f32_e32 v4, 0xbfb8aa3b, v13
	v_exp_f32_e32 v8, v4
	v_add_f32_e32 v3, 1.0, v3
	v_rcp_f32_e32 v14, v3
	ds_read_b128 v[4:7], v2 offset:4608
	v_add_f32_e32 v3, 1.0, v8
	v_rcp_f32_e32 v15, v3
	ds_read_b128 v[8:11], v2 offset:5760
	s_waitcnt lgkmcnt(1)
	v_lshlrev_b32_e32 v16, 16, v4
	v_pk_mul_f32 v[12:13], v[14:15], v[12:13]
	v_lshlrev_b32_e32 v14, 16, v97
	v_and_b32_e32 v15, 0xffff0000, v97
	v_mul_f32_e32 v3, 0xbfb8aa3b, v14
	v_and_b32_e32 v17, 0xffff0000, v4
	v_exp_f32_e32 v3, v3
	v_mul_f32_e32 v4, 0xbfb8aa3b, v15
	v_exp_f32_e32 v4, v4
	v_pk_mul_f32 v[12:13], v[12:13], v[16:17]
	v_add_f32_e32 v3, 1.0, v3
	v_rcp_f32_e32 v16, v3
	v_add_f32_e32 v3, 1.0, v4
	v_rcp_f32_e32 v17, v3
	v_cvt_pk_bf16_f32 v4, v12, v13
	v_lshlrev_b32_e32 v12, 16, v5
	v_and_b32_e32 v13, 0xffff0000, v5
	v_pk_mul_f32 v[14:15], v[16:17], v[14:15]
	v_lshlrev_b32_e32 v16, 16, v98
	v_and_b32_e32 v17, 0xffff0000, v98
	v_mul_f32_e32 v3, 0xbfb8aa3b, v16
	v_exp_f32_e32 v3, v3
	v_mul_f32_e32 v5, 0xbfb8aa3b, v17
	v_exp_f32_e32 v5, v5
	v_pk_mul_f32 v[12:13], v[14:15], v[12:13]
	v_add_f32_e32 v3, 1.0, v3
	v_rcp_f32_e32 v14, v3
	v_add_f32_e32 v3, 1.0, v5
	v_rcp_f32_e32 v15, v3
	v_cvt_pk_bf16_f32 v5, v12, v13
	v_lshlrev_b32_e32 v12, 16, v6
	v_and_b32_e32 v13, 0xffff0000, v6
	v_pk_mul_f32 v[14:15], v[14:15], v[16:17]
	v_lshlrev_b32_e32 v16, 16, v99
	v_and_b32_e32 v17, 0xffff0000, v99
	v_mul_f32_e32 v3, 0xbfb8aa3b, v16
	v_exp_f32_e32 v3, v3
	v_mul_f32_e32 v6, 0xbfb8aa3b, v17
	v_exp_f32_e32 v6, v6
	v_pk_mul_f32 v[12:13], v[14:15], v[12:13]
	v_add_f32_e32 v3, 1.0, v3
	v_rcp_f32_e32 v14, v3
	v_add_f32_e32 v3, 1.0, v6
	v_rcp_f32_e32 v15, v3
	v_cvt_pk_bf16_f32 v6, v12, v13
	v_lshlrev_b32_e32 v12, 16, v7
	v_and_b32_e32 v13, 0xffff0000, v7
	v_pk_mul_f32 v[14:15], v[14:15], v[16:17]
	s_nop 0
	v_pk_mul_f32 v[12:13], v[14:15], v[12:13]
	s_waitcnt vmcnt(6)
	v_lshlrev_b32_e32 v14, 16, v92
	v_and_b32_e32 v15, 0xffff0000, v92
	v_mul_f32_e32 v3, 0xbfb8aa3b, v14
	v_exp_f32_e32 v3, v3
	v_mul_f32_e32 v16, 0xbfb8aa3b, v15
	v_exp_f32_e32 v17, v16
	v_cvt_pk_bf16_f32 v7, v12, v13
	v_mad_i64_i32 v[12:13], s[6:7], v46, s44, v[0:1]
	v_lshl_add_u64 v[12:13], v[12:13], 0, v[32:33]
	v_add_f32_e32 v3, 1.0, v3
	v_rcp_f32_e32 v16, v3
	v_add_f32_e32 v3, 1.0, v17
	global_store_dwordx4 v[12:13], v[4:7], off nt
	v_lshlrev_b32_e32 v12, 16, v93
	v_rcp_f32_e32 v17, v3
	v_and_b32_e32 v13, 0xffff0000, v93
	v_mul_f32_e32 v3, 0xbfb8aa3b, v12
	s_waitcnt lgkmcnt(0)
	v_lshlrev_b32_e32 v4, 16, v8
	v_and_b32_e32 v5, 0xffff0000, v8
	v_exp_f32_e32 v3, v3
	v_mul_f32_e32 v8, 0xbfb8aa3b, v13
	v_exp_f32_e32 v8, v8
	v_pk_mul_f32 v[6:7], v[16:17], v[14:15]
	v_add_f32_e32 v3, 1.0, v3
	v_pk_mul_f32 v[4:5], v[6:7], v[4:5]
	v_rcp_f32_e32 v6, v3
	v_add_f32_e32 v3, 1.0, v8
	v_rcp_f32_e32 v7, v3
	v_cvt_pk_bf16_f32 v4, v4, v5
	v_lshlrev_b32_e32 v8, 16, v9
	v_and_b32_e32 v9, 0xffff0000, v9
	v_pk_mul_f32 v[6:7], v[6:7], v[12:13]
	v_lshlrev_b32_e32 v12, 16, v94
	v_and_b32_e32 v13, 0xffff0000, v94
	v_mul_f32_e32 v3, 0xbfb8aa3b, v12
	v_exp_f32_e32 v3, v3
	v_mul_f32_e32 v5, 0xbfb8aa3b, v13
	v_exp_f32_e32 v5, v5
	v_pk_mul_f32 v[6:7], v[6:7], v[8:9]
	v_add_f32_e32 v3, 1.0, v3
	v_rcp_f32_e32 v8, v3
	v_add_f32_e32 v3, 1.0, v5
	v_rcp_f32_e32 v9, v3
	v_cvt_pk_bf16_f32 v5, v6, v7
	v_lshlrev_b32_e32 v6, 16, v10
	v_and_b32_e32 v7, 0xffff0000, v10
	v_pk_mul_f32 v[8:9], v[8:9], v[12:13]
	v_lshlrev_b32_e32 v12, 16, v95
	v_and_b32_e32 v13, 0xffff0000, v95
	v_mul_f32_e32 v3, 0xbfb8aa3b, v12
	v_exp_f32_e32 v3, v3
	v_mul_f32_e32 v10, 0xbfb8aa3b, v13
	v_exp_f32_e32 v10, v10
	v_pk_mul_f32 v[6:7], v[8:9], v[6:7]
	v_add_f32_e32 v3, 1.0, v3
	v_rcp_f32_e32 v8, v3
	v_add_f32_e32 v3, 1.0, v10
	v_rcp_f32_e32 v9, v3
	v_lshlrev_b32_e32 v10, 16, v11
	v_and_b32_e32 v11, 0xffff0000, v11
	v_cvt_pk_bf16_f32 v6, v6, v7
	v_pk_mul_f32 v[8:9], v[8:9], v[12:13]
	s_waitcnt vmcnt(6)
	v_lshlrev_b32_e32 v12, 16, v70
	v_pk_mul_f32 v[8:9], v[8:9], v[10:11]
	v_and_b32_e32 v13, 0xffff0000, v70
	v_cvt_pk_bf16_f32 v7, v8, v9
	v_mad_i64_i32 v[8:9], s[6:7], v38, s44, v[0:1]
	v_lshl_add_u64 v[8:9], v[8:9], 0, v[32:33]
	v_mul_f32_e32 v3, 0xbfb8aa3b, v12
	global_store_dwordx4 v[8:9], v[4:7], off nt
	v_exp_f32_e32 v3, v3
	s_nop 0
	v_mul_f32_e32 v4, 0xbfb8aa3b, v13
	v_exp_f32_e32 v8, v4
	v_add_f32_e32 v3, 1.0, v3
	v_rcp_f32_e32 v14, v3
	ds_read_b128 v[4:7], v2 offset:6912
	v_add_f32_e32 v3, 1.0, v8
	v_rcp_f32_e32 v15, v3
	ds_read_b128 v[8:11], v2 offset:8064
	s_waitcnt lgkmcnt(1)
	v_lshlrev_b32_e32 v2, 16, v4
	v_pk_mul_f32 v[12:13], v[14:15], v[12:13]
	v_lshlrev_b32_e32 v14, 16, v71
	v_and_b32_e32 v3, 0xffff0000, v4
	v_and_b32_e32 v15, 0xffff0000, v71
	v_mul_f32_e32 v4, 0xbfb8aa3b, v14
	v_exp_f32_e32 v4, v4
	v_mul_f32_e32 v16, 0xbfb8aa3b, v15
	v_exp_f32_e32 v16, v16
	v_pk_mul_f32 v[2:3], v[12:13], v[2:3]
	v_add_f32_e32 v4, 1.0, v4
	v_rcp_f32_e32 v12, v4
	v_add_f32_e32 v4, 1.0, v16
	v_rcp_f32_e32 v13, v4
	v_cvt_pk_bf16_f32 v2, v2, v3
	v_lshlrev_b32_e32 v4, 16, v5
	v_and_b32_e32 v5, 0xffff0000, v5
	v_pk_mul_f32 v[12:13], v[12:13], v[14:15]
	v_lshlrev_b32_e32 v14, 16, v72
	v_and_b32_e32 v15, 0xffff0000, v72
	v_mul_f32_e32 v3, 0xbfb8aa3b, v14
	v_exp_f32_e32 v3, v3
	v_mul_f32_e32 v16, 0xbfb8aa3b, v15
	v_exp_f32_e32 v16, v16
	v_pk_mul_f32 v[4:5], v[12:13], v[4:5]
	v_add_f32_e32 v3, 1.0, v3
	v_rcp_f32_e32 v12, v3
	v_add_f32_e32 v3, 1.0, v16
	v_rcp_f32_e32 v13, v3
	v_cvt_pk_bf16_f32 v3, v4, v5
	v_lshlrev_b32_e32 v4, 16, v6
	v_and_b32_e32 v5, 0xffff0000, v6
	v_pk_mul_f32 v[12:13], v[12:13], v[14:15]
	v_lshlrev_b32_e32 v14, 16, v73
	v_and_b32_e32 v15, 0xffff0000, v73
	v_mul_f32_e32 v6, 0xbfb8aa3b, v14
	v_exp_f32_e32 v6, v6
	v_mul_f32_e32 v16, 0xbfb8aa3b, v15
	v_exp_f32_e32 v16, v16
	v_pk_mul_f32 v[4:5], v[12:13], v[4:5]
	v_add_f32_e32 v6, 1.0, v6
	v_rcp_f32_e32 v12, v6
	v_add_f32_e32 v6, 1.0, v16
	v_rcp_f32_e32 v13, v6
	v_lshlrev_b32_e32 v6, 16, v7
	v_and_b32_e32 v7, 0xffff0000, v7
	v_cvt_pk_bf16_f32 v4, v4, v5
	v_pk_mul_f32 v[12:13], v[12:13], v[14:15]
	s_nop 0
	v_pk_mul_f32 v[6:7], v[12:13], v[6:7]
	s_waitcnt vmcnt(6)
	v_lshlrev_b32_e32 v12, 16, v66
	v_and_b32_e32 v13, 0xffff0000, v66
	v_mul_f32_e32 v14, 0xbfb8aa3b, v12
	v_mul_f32_e32 v15, 0xbfb8aa3b, v13
	v_exp_f32_e32 v14, v14
	v_exp_f32_e32 v15, v15
	v_cvt_pk_bf16_f32 v5, v6, v7
	v_mad_i64_i32 v[6:7], s[6:7], v34, s44, v[0:1]
	v_add_f32_e32 v14, 1.0, v14
	v_add_f32_e32 v15, 1.0, v15
	v_rcp_f32_e32 v14, v14
	v_rcp_f32_e32 v15, v15
	v_lshl_add_u64 v[6:7], v[6:7], 0, v[32:33]
	global_store_dwordx4 v[6:7], v[2:5], off nt
	v_lshlrev_b32_e32 v6, 16, v67
	v_and_b32_e32 v7, 0xffff0000, v67
	s_waitcnt lgkmcnt(0)
	v_lshlrev_b32_e32 v2, 16, v8
	v_and_b32_e32 v3, 0xffff0000, v8
	v_pk_mul_f32 v[4:5], v[14:15], v[12:13]
	v_mul_f32_e32 v8, 0xbfb8aa3b, v6
	v_mul_f32_e32 v12, 0xbfb8aa3b, v7
	v_exp_f32_e32 v8, v8
	v_exp_f32_e32 v12, v12
	v_pk_mul_f32 v[2:3], v[4:5], v[2:3]
	v_mad_i64_i32 v[0:1], s[6:7], v18, s44, v[0:1]
	v_add_f32_e32 v4, 1.0, v8
	v_add_f32_e32 v5, 1.0, v12
	v_rcp_f32_e32 v4, v4
	v_rcp_f32_e32 v5, v5
	v_cvt_pk_bf16_f32 v2, v2, v3
	v_lshlrev_b32_e32 v8, 16, v9
	v_and_b32_e32 v9, 0xffff0000, v9
	v_pk_mul_f32 v[4:5], v[4:5], v[6:7]
	v_lshlrev_b32_e32 v6, 16, v68
	v_and_b32_e32 v7, 0xffff0000, v68
	v_mul_f32_e32 v3, 0xbfb8aa3b, v6
	v_exp_f32_e32 v3, v3
	v_mul_f32_e32 v12, 0xbfb8aa3b, v7
	v_exp_f32_e32 v12, v12
	v_pk_mul_f32 v[4:5], v[4:5], v[8:9]
	v_add_f32_e32 v3, 1.0, v3
	v_rcp_f32_e32 v8, v3
	v_add_f32_e32 v3, 1.0, v12
	v_rcp_f32_e32 v9, v3
	v_cvt_pk_bf16_f32 v3, v4, v5
	v_lshlrev_b32_e32 v4, 16, v10
	v_and_b32_e32 v5, 0xffff0000, v10
	v_pk_mul_f32 v[6:7], v[8:9], v[6:7]
	v_lshlrev_b32_e32 v8, 16, v69
	v_and_b32_e32 v9, 0xffff0000, v69
	v_mul_f32_e32 v10, 0xbfb8aa3b, v8
	v_mul_f32_e32 v12, 0xbfb8aa3b, v9
	v_exp_f32_e32 v10, v10
	v_exp_f32_e32 v12, v12
	v_pk_mul_f32 v[4:5], v[6:7], v[4:5]
	v_lshl_add_u64 v[0:1], v[0:1], 0, v[32:33]
	v_add_f32_e32 v6, 1.0, v10
	v_add_f32_e32 v7, 1.0, v12
	v_rcp_f32_e32 v6, v6
	v_rcp_f32_e32 v7, v7
	v_lshlrev_b32_e32 v10, 16, v11
	v_and_b32_e32 v11, 0xffff0000, v11
	v_cvt_pk_bf16_f32 v4, v4, v5
	v_pk_mul_f32 v[6:7], v[6:7], v[8:9]
	s_mov_b64 s[6:7], s[76:77]
	v_pk_mul_f32 v[6:7], v[6:7], v[10:11]
	s_nop 0
	v_cvt_pk_bf16_f32 v5, v6, v7
	global_store_dwordx4 v[0:1], v[2:5], off nt

.LBB0_803:
	v_lshrrev_b32_e32 v17, 3, v207
	s_waitcnt vmcnt(3)
	v_or_b32_e32 v122, s82, v17
	v_lshlrev_b32_e32 v18, 3, v207
	v_ashrrev_i32_e32 v123, 31, v122
	v_or_b32_e32 v120, 8, v122
	v_and_b32_e32 v37, 56, v18
	v_lshlrev_b64 v[18:19], 13, v[122:123]
	v_ashrrev_i32_e32 v121, 31, v120
	v_lshl_add_u64 v[18:19], s[70:71], 0, v[18:19]
	s_lshl_b32 s92, s57, 1
	v_lshlrev_b64 v[34:35], 13, v[120:121]
	v_lshl_add_u64 v[18:19], v[18:19], 0, s[92:93]
	v_lshlrev_b32_e32 v32, 1, v37
	v_lshl_add_u64 v[34:35], s[70:71], 0, v[34:35]
	v_lshl_add_u64 v[18:19], v[18:19], 0, v[32:33]
	v_lshl_add_u64 v[34:35], v[34:35], 0, s[92:93]
	v_lshl_add_u64 v[34:35], v[34:35], 0, v[32:33]
	global_load_dwordx4 v[112:115], v[18:19], off offset:1536
	global_load_dwordx4 v[108:111], v[34:35], off offset:1536
	v_or_b32_e32 v118, 16, v122
	v_or_b32_e32 v66, 24, v122
	v_ashrrev_i32_e32 v119, 31, v118
	v_ashrrev_i32_e32 v67, 31, v66
	v_lshlrev_b64 v[18:19], 13, v[118:119]
	v_lshlrev_b64 v[34:35], 13, v[66:67]
	v_lshl_add_u64 v[18:19], s[70:71], 0, v[18:19]
	v_lshl_add_u64 v[34:35], s[70:71], 0, v[34:35]
	v_lshl_add_u64 v[18:19], v[18:19], 0, s[92:93]
	v_lshl_add_u64 v[34:35], v[34:35], 0, s[92:93]
	v_or_b32_e32 v46, 32, v122
	v_or_b32_e32 v38, 40, v122
	v_lshl_add_u64 v[18:19], v[18:19], 0, v[32:33]
	v_lshl_add_u64 v[34:35], v[34:35], 0, v[32:33]
	v_ashrrev_i32_e32 v47, 31, v46
	v_ashrrev_i32_e32 v39, 31, v38
	global_load_dwordx4 v[104:107], v[18:19], off offset:1536
	global_load_dwordx4 v[100:103], v[34:35], off offset:1536
	v_lshlrev_b64 v[18:19], 13, v[46:47]
	v_lshlrev_b64 v[34:35], 13, v[38:39]
	v_lshl_add_u64 v[18:19], s[70:71], 0, v[18:19]
	v_lshl_add_u64 v[34:35], s[70:71], 0, v[34:35]
	v_lshl_add_u64 v[18:19], v[18:19], 0, s[92:93]
	v_lshl_add_u64 v[34:35], v[34:35], 0, s[92:93]
	v_lshl_add_u64 v[18:19], v[18:19], 0, v[32:33]
	v_lshl_add_u64 v[34:35], v[34:35], 0, v[32:33]
	global_load_dwordx4 v[88:91], v[18:19], off offset:1536
	global_load_dwordx4 v[84:87], v[34:35], off offset:1536
	v_or_b32_e32 v34, 48, v122
	v_ashrrev_i32_e32 v35, 31, v34
	v_lshlrev_b64 v[18:19], 13, v[34:35]
	v_lshl_add_u64 v[18:19], s[70:71], 0, v[18:19]
	v_lshl_add_u64 v[18:19], v[18:19], 0, s[92:93]
	v_lshl_add_u64 v[72:73], v[18:19], 0, v[32:33]
	v_or_b32_e32 v18, 56, v122
	v_ashrrev_i32_e32 v19, 31, v18
	v_lshlrev_b64 v[74:75], 13, v[18:19]
	v_div_scale_f32 v19, s[6:7], v116, v116, 1.0
	v_rcp_f32_e32 v35, v19
	v_lshl_add_u64 v[74:75], s[70:71], 0, v[74:75]
	v_readlane_b32 s5, v254, 45
	v_lshl_add_u64 v[74:75], v[74:75], 0, s[92:93]
	v_fma_f32 v39, -v19, v35, 1.0
	v_fmac_f32_e32 v35, v39, v35
	v_div_scale_f32 v39, vcc, 1.0, v116, 1.0
	v_mul_f32_e32 v45, v39, v35
	v_fma_f32 v47, -v19, v45, v39
	v_fmac_f32_e32 v45, v47, v35
	v_fma_f32 v19, -v19, v45, v39
	v_div_fmas_f32 v19, v19, v35, v45
	v_div_scale_f32 v35, s[6:7], v64, v64, 1.0
	v_rcp_f32_e32 v39, v35
	v_div_fixup_f32 v116, v19, v116, 1.0
	v_mul_u32_u24_e32 v19, 0x90, v201
	v_add3_u32 v19, s5, v204, v19
	v_fma_f32 v45, -v35, v39, 1.0
	v_fmac_f32_e32 v39, v45, v39
	v_div_scale_f32 v45, vcc, 1.0, v64, 1.0
	v_mul_f32_e32 v47, v45, v39
	v_fma_f32 v65, -v35, v47, v45
	v_fmac_f32_e32 v47, v65, v39
	v_fma_f32 v35, -v35, v47, v45
	v_div_fmas_f32 v35, v35, v39, v47
	v_div_fixup_f32 v64, v35, v64, 1.0
	v_pk_mul_f32 v[62:63], v[62:63], v[64:65] op_sel_hi:[1,0]
	v_pk_mul_f32 v[60:61], v[60:61], v[64:65] op_sel_hi:[1,0]
	v_pk_mul_f32 v[50:51], v[50:51], v[64:65] op_sel_hi:[1,0]
	v_pk_mul_f32 v[48:49], v[48:49], v[64:65] op_sel_hi:[1,0]
	v_div_scale_f32 v39, s[6:7], v44, v44, 1.0
	v_lshl_add_u64 v[74:75], v[74:75], 0, v[32:33]
	v_cvt_pk_bf16_f32 v60, v60, v61
	v_cvt_pk_bf16_f32 v61, v62, v63
	v_cvt_pk_bf16_f32 v48, v48, v49
	v_cvt_pk_bf16_f32 v49, v50, v51
	v_add_u32_e32 v35, 0x800, v19
	v_rcp_f32_e32 v45, v39
	global_load_dwordx4 v[76:79], v[72:73], off offset:1536
	s_nop 0
	global_load_dwordx4 v[72:75], v[74:75], off offset:1536
	s_barrier
	ds_write2_b64 v35, v[60:61], v[48:49] offset0:32 offset1:36
	v_pk_mul_f32 v[48:49], v[58:59], v[64:65] op_sel_hi:[1,0]
	v_pk_mul_f32 v[50:51], v[56:57], v[64:65] op_sel_hi:[1,0]
	v_pk_mul_f32 v[52:53], v[64:65], v[52:53] op_sel_hi:[0,1]
	v_cvt_pk_bf16_f32 v50, v50, v51
	v_cvt_pk_bf16_f32 v51, v48, v49
	v_pk_mul_f32 v[48:49], v[64:65], v[54:55] op_sel_hi:[0,1]
	v_cvt_pk_bf16_f32 v52, v52, v53
	v_cvt_pk_bf16_f32 v53, v48, v49
	ds_write2_b64 v35, v[50:51], v[52:53] offset0:40 offset1:44
	v_fma_f32 v35, -v39, v45, 1.0
	v_fmac_f32_e32 v45, v35, v45
	v_div_scale_f32 v35, vcc, 1.0, v44, 1.0
	v_mul_f32_e32 v47, v35, v45
	v_fma_f32 v48, -v39, v47, v35
	v_fmac_f32_e32 v47, v48, v45
	v_fma_f32 v35, -v39, v47, v35
	v_div_fmas_f32 v35, v35, v45, v47
	v_div_fixup_f32 v44, v35, v44, 1.0
	v_pk_mul_f32 v[42:43], v[42:43], v[44:45] op_sel_hi:[1,0]
	v_pk_mul_f32 v[40:41], v[40:41], v[44:45] op_sel_hi:[1,0]
	v_pk_mul_f32 v[22:23], v[22:23], v[44:45] op_sel_hi:[1,0]
	v_pk_mul_f32 v[20:21], v[20:21], v[44:45] op_sel_hi:[1,0]
	v_cvt_pk_bf16_f32 v40, v40, v41
	v_cvt_pk_bf16_f32 v41, v42, v43
	v_cvt_pk_bf16_f32 v20, v20, v21
	v_cvt_pk_bf16_f32 v21, v22, v23
	v_add_u32_e32 v35, 0x1000, v19
	ds_write2_b64 v35, v[40:41], v[20:21] offset0:64 offset1:68
	v_pk_mul_f32 v[20:21], v[44:45], v[30:31] op_sel_hi:[0,1]
	v_pk_mul_f32 v[22:23], v[44:45], v[28:29] op_sel_hi:[0,1]
	v_cvt_pk_bf16_f32 v22, v22, v23
	v_cvt_pk_bf16_f32 v23, v20, v21
	v_pk_mul_f32 v[20:21], v[44:45], v[26:27] op_sel_hi:[0,1]
	v_div_scale_f32 v26, s[6:7], v16, v16, 1.0
	v_rcp_f32_e32 v27, v26
	v_pk_mul_f32 v[24:25], v[44:45], v[24:25] op_sel_hi:[0,1]
	v_cvt_pk_bf16_f32 v24, v24, v25
	v_cvt_pk_bf16_f32 v25, v20, v21
	v_fma_f32 v20, -v26, v27, 1.0
	v_fmac_f32_e32 v27, v20, v27
	v_div_scale_f32 v20, vcc, 1.0, v16, 1.0
	v_mul_f32_e32 v21, v20, v27
	ds_write2_b64 v35, v[22:23], v[24:25] offset0:72 offset1:76
	v_fma_f32 v22, -v26, v21, v20
	v_fmac_f32_e32 v21, v22, v27
	v_fma_f32 v20, -v26, v21, v20
	v_div_fmas_f32 v20, v20, v27, v21
	v_div_fixup_f32 v16, v20, v16, 1.0
	v_pk_mul_f32 v[10:11], v[10:11], v[16:17] op_sel_hi:[1,0]
	v_pk_mul_f32 v[8:9], v[8:9], v[16:17] op_sel_hi:[1,0]
	v_pk_mul_f32 v[2:3], v[2:3], v[16:17] op_sel_hi:[1,0]
	v_pk_mul_f32 v[0:1], v[0:1], v[16:17] op_sel_hi:[1,0]
	v_cvt_pk_bf16_f32 v8, v8, v9
	v_cvt_pk_bf16_f32 v9, v10, v11
	v_cvt_pk_bf16_f32 v0, v0, v1
	v_cvt_pk_bf16_f32 v1, v2, v3
	v_add_u32_e32 v10, 0x1800, v19
	v_readlane_b32 s0, v254, 46
	ds_write2_b64 v10, v[8:9], v[0:1] offset0:96 offset1:100
	v_pk_mul_f32 v[0:1], v[16:17], v[14:15] op_sel_hi:[0,1]
	v_pk_mul_f32 v[2:3], v[16:17], v[12:13] op_sel_hi:[0,1]
	s_add_u32 s6, s0, s92
	v_readlane_b32 s0, v254, 47
	v_cvt_pk_bf16_f32 v2, v2, v3
	v_cvt_pk_bf16_f32 v3, v0, v1
	v_pk_mul_f32 v[0:1], v[16:17], v[6:7] op_sel_hi:[0,1]
	v_pk_mul_f32 v[4:5], v[16:17], v[4:5] op_sel_hi:[0,1]
	s_addc_u32 s7, s0, 0
	s_movk_i32 s0, 0x48
	v_cvt_pk_bf16_f32 v4, v4, v5
	v_cvt_pk_bf16_f32 v5, v0, v1
	v_mad_u32_u24 v0, v17, s0, v37
	ds_write2_b64 v10, v[2:3], v[4:5] offset0:104 offset1:108
	v_lshl_add_u32 v2, v0, 1, s5
	s_waitcnt vmcnt(7)
	v_lshlrev_b32_e32 v0, 16, v112
	v_and_b32_e32 v1, 0xffff0000, v112
	v_mul_f32_e32 v3, 0xbfb8aa3b, v0
	v_pk_mul_f32 v[98:99], v[98:99], v[116:117] op_sel_hi:[1,0]
	v_pk_mul_f32 v[96:97], v[96:97], v[116:117] op_sel_hi:[1,0]
	v_pk_mul_f32 v[70:71], v[70:71], v[116:117] op_sel_hi:[1,0]
	v_pk_mul_f32 v[68:69], v[68:69], v[116:117] op_sel_hi:[1,0]
	v_exp_f32_e32 v3, v3
	v_mul_f32_e32 v4, 0xbfb8aa3b, v1
	v_cvt_pk_bf16_f32 v96, v96, v97
	v_cvt_pk_bf16_f32 v97, v98, v99
	v_cvt_pk_bf16_f32 v68, v68, v69
	v_cvt_pk_bf16_f32 v69, v70, v71
	v_exp_f32_e32 v8, v4
	ds_write2_b64 v19, v[96:97], v[68:69] offset1:4
	v_pk_mul_f32 v[68:69], v[94:95], v[116:117] op_sel_hi:[1,0]
	v_pk_mul_f32 v[70:71], v[92:93], v[116:117] op_sel_hi:[1,0]
	v_pk_mul_f32 v[80:81], v[116:117], v[80:81] op_sel_hi:[0,1]
	v_cvt_pk_bf16_f32 v70, v70, v71
	v_cvt_pk_bf16_f32 v71, v68, v69
	v_pk_mul_f32 v[68:69], v[116:117], v[82:83] op_sel_hi:[0,1]
	v_cvt_pk_bf16_f32 v80, v80, v81
	v_cvt_pk_bf16_f32 v81, v68, v69
	v_add_f32_e32 v3, 1.0, v3
	ds_write2_b64 v19, v[70:71], v[80:81] offset0:8 offset1:12
	v_rcp_f32_e32 v12, v3
	v_add_f32_e32 v3, 1.0, v8
	s_waitcnt lgkmcnt(0)
	v_rcp_f32_e32 v13, v3
	ds_read_b128 v[4:7], v2
	ds_read_b128 v[8:11], v2 offset:1152
	s_mov_b32 s18, s94
	v_pk_mul_f32 v[0:1], v[12:13], v[0:1]
	v_lshlrev_b32_e32 v12, 16, v113
	v_and_b32_e32 v13, 0xffff0000, v113
	v_mul_f32_e32 v3, 0xbfb8aa3b, v12
	s_waitcnt lgkmcnt(1)
	v_lshlrev_b32_e32 v14, 16, v4
	v_and_b32_e32 v15, 0xffff0000, v4
	v_exp_f32_e32 v3, v3
	v_mul_f32_e32 v4, 0xbfb8aa3b, v13
	v_exp_f32_e32 v4, v4
	v_pk_mul_f32 v[0:1], v[0:1], v[14:15]
	v_add_f32_e32 v3, 1.0, v3
	v_rcp_f32_e32 v14, v3
	v_add_f32_e32 v3, 1.0, v4
	v_rcp_f32_e32 v15, v3
	v_cvt_pk_bf16_f32 v4, v0, v1
	v_lshlrev_b32_e32 v0, 16, v5
	v_and_b32_e32 v1, 0xffff0000, v5
	v_pk_mul_f32 v[12:13], v[14:15], v[12:13]
	v_lshlrev_b32_e32 v14, 16, v114
	v_and_b32_e32 v15, 0xffff0000, v114
	v_mul_f32_e32 v3, 0xbfb8aa3b, v14
	v_exp_f32_e32 v3, v3
	v_mul_f32_e32 v5, 0xbfb8aa3b, v15
	v_exp_f32_e32 v5, v5
	v_pk_mul_f32 v[0:1], v[12:13], v[0:1]
	v_add_f32_e32 v3, 1.0, v3
	v_rcp_f32_e32 v12, v3
	v_add_f32_e32 v3, 1.0, v5
	v_rcp_f32_e32 v13, v3
	v_cvt_pk_bf16_f32 v5, v0, v1
	v_lshlrev_b32_e32 v0, 16, v6
	v_and_b32_e32 v1, 0xffff0000, v6
	v_pk_mul_f32 v[12:13], v[12:13], v[14:15]
	v_lshlrev_b32_e32 v14, 16, v115
	v_and_b32_e32 v15, 0xffff0000, v115
	v_mul_f32_e32 v3, 0xbfb8aa3b, v14
	v_exp_f32_e32 v3, v3
	v_mul_f32_e32 v6, 0xbfb8aa3b, v15
	v_exp_f32_e32 v6, v6
	v_pk_mul_f32 v[0:1], v[12:13], v[0:1]
	v_add_f32_e32 v3, 1.0, v3
	v_rcp_f32_e32 v12, v3
	v_add_f32_e32 v3, 1.0, v6
	v_rcp_f32_e32 v13, v3
	v_cvt_pk_bf16_f32 v6, v0, v1
	v_lshlrev_b32_e32 v0, 16, v7
	v_and_b32_e32 v1, 0xffff0000, v7
	v_pk_mul_f32 v[12:13], v[12:13], v[14:15]
	s_waitcnt vmcnt(6)
	v_lshlrev_b32_e32 v14, 16, v108
	v_and_b32_e32 v15, 0xffff0000, v108
	v_mul_f32_e32 v3, 0xbfb8aa3b, v14
	v_exp_f32_e32 v3, v3
	v_mul_f32_e32 v16, 0xbfb8aa3b, v15
	v_pk_mul_f32 v[0:1], v[12:13], v[0:1]
	v_exp_f32_e32 v17, v16
	v_cvt_pk_bf16_f32 v7, v0, v1
	v_mov_b64_e32 v[0:1], s[6:7]
	v_mad_i64_i32 v[12:13], s[6:7], v122, s44, v[0:1]
	v_lshl_add_u64 v[12:13], v[12:13], 0, v[32:33]
	v_add_f32_e32 v3, 1.0, v3
	v_rcp_f32_e32 v16, v3
	v_add_f32_e32 v3, 1.0, v17
	global_store_dwordx4 v[12:13], v[4:7], off nt
	v_lshlrev_b32_e32 v12, 16, v109
	v_rcp_f32_e32 v17, v3
	v_and_b32_e32 v13, 0xffff0000, v109
	v_mul_f32_e32 v3, 0xbfb8aa3b, v12
	s_waitcnt lgkmcnt(0)
	v_lshlrev_b32_e32 v4, 16, v8
	v_and_b32_e32 v5, 0xffff0000, v8
	v_exp_f32_e32 v3, v3
	v_mul_f32_e32 v8, 0xbfb8aa3b, v13
	v_exp_f32_e32 v8, v8
	v_pk_mul_f32 v[6:7], v[16:17], v[14:15]
	v_add_f32_e32 v3, 1.0, v3
	v_pk_mul_f32 v[4:5], v[6:7], v[4:5]
	v_rcp_f32_e32 v6, v3
	v_add_f32_e32 v3, 1.0, v8
	v_rcp_f32_e32 v7, v3
	v_cvt_pk_bf16_f32 v4, v4, v5
	v_lshlrev_b32_e32 v8, 16, v9
	v_and_b32_e32 v9, 0xffff0000, v9
	v_pk_mul_f32 v[6:7], v[6:7], v[12:13]
	v_lshlrev_b32_e32 v12, 16, v110
	v_and_b32_e32 v13, 0xffff0000, v110
	v_mul_f32_e32 v3, 0xbfb8aa3b, v12
	v_exp_f32_e32 v3, v3
	v_mul_f32_e32 v5, 0xbfb8aa3b, v13
	v_exp_f32_e32 v5, v5
	v_pk_mul_f32 v[6:7], v[6:7], v[8:9]
	v_add_f32_e32 v3, 1.0, v3
	v_rcp_f32_e32 v8, v3
	v_add_f32_e32 v3, 1.0, v5
	v_rcp_f32_e32 v9, v3
	v_cvt_pk_bf16_f32 v5, v6, v7
	v_lshlrev_b32_e32 v6, 16, v10
	v_and_b32_e32 v7, 0xffff0000, v10
	v_pk_mul_f32 v[8:9], v[8:9], v[12:13]
	v_lshlrev_b32_e32 v12, 16, v111
	v_and_b32_e32 v13, 0xffff0000, v111
	v_mul_f32_e32 v3, 0xbfb8aa3b, v12
	v_exp_f32_e32 v3, v3
	v_mul_f32_e32 v10, 0xbfb8aa3b, v13
	v_exp_f32_e32 v10, v10
	v_pk_mul_f32 v[6:7], v[8:9], v[6:7]
	v_add_f32_e32 v3, 1.0, v3
	v_rcp_f32_e32 v8, v3
	v_add_f32_e32 v3, 1.0, v10
	v_rcp_f32_e32 v9, v3
	v_lshlrev_b32_e32 v10, 16, v11
	v_and_b32_e32 v11, 0xffff0000, v11
	v_cvt_pk_bf16_f32 v6, v6, v7
	v_pk_mul_f32 v[8:9], v[8:9], v[12:13]
	s_waitcnt vmcnt(6)
	v_lshlrev_b32_e32 v12, 16, v104
	v_pk_mul_f32 v[8:9], v[8:9], v[10:11]
	v_and_b32_e32 v13, 0xffff0000, v104
	v_cvt_pk_bf16_f32 v7, v8, v9
	v_mad_i64_i32 v[8:9], s[6:7], v120, s44, v[0:1]
	v_lshl_add_u64 v[8:9], v[8:9], 0, v[32:33]
	v_mul_f32_e32 v3, 0xbfb8aa3b, v12
	global_store_dwordx4 v[8:9], v[4:7], off nt
	v_exp_f32_e32 v3, v3
	v_readlane_b32 s96, v254, 31
	v_mul_f32_e32 v4, 0xbfb8aa3b, v13
	v_exp_f32_e32 v8, v4
	v_add_f32_e32 v3, 1.0, v3
	v_rcp_f32_e32 v14, v3
	ds_read_b128 v[4:7], v2 offset:2304
	v_add_f32_e32 v3, 1.0, v8
	v_rcp_f32_e32 v15, v3
	ds_read_b128 v[8:11], v2 offset:3456
	v_readlane_b32 s83, v254, 33
	s_waitcnt lgkmcnt(1)
	v_lshlrev_b32_e32 v16, 16, v4
	v_pk_mul_f32 v[12:13], v[14:15], v[12:13]
	v_lshlrev_b32_e32 v14, 16, v105
	v_and_b32_e32 v15, 0xffff0000, v105
	v_mul_f32_e32 v3, 0xbfb8aa3b, v14
	v_and_b32_e32 v17, 0xffff0000, v4
	v_exp_f32_e32 v3, v3
	v_mul_f32_e32 v4, 0xbfb8aa3b, v15
	v_exp_f32_e32 v4, v4
	v_pk_mul_f32 v[12:13], v[12:13], v[16:17]
	v_add_f32_e32 v3, 1.0, v3
	v_rcp_f32_e32 v16, v3
	v_add_f32_e32 v3, 1.0, v4
	v_rcp_f32_e32 v17, v3
	v_cvt_pk_bf16_f32 v4, v12, v13
	v_lshlrev_b32_e32 v12, 16, v5
	v_and_b32_e32 v13, 0xffff0000, v5
	v_pk_mul_f32 v[14:15], v[16:17], v[14:15]
	v_lshlrev_b32_e32 v16, 16, v106
	v_and_b32_e32 v17, 0xffff0000, v106
	v_mul_f32_e32 v3, 0xbfb8aa3b, v16
	v_exp_f32_e32 v3, v3
	v_mul_f32_e32 v5, 0xbfb8aa3b, v17
	v_exp_f32_e32 v5, v5
	v_pk_mul_f32 v[12:13], v[14:15], v[12:13]
	v_add_f32_e32 v3, 1.0, v3
	v_rcp_f32_e32 v14, v3
	v_add_f32_e32 v3, 1.0, v5
	v_rcp_f32_e32 v15, v3
	v_cvt_pk_bf16_f32 v5, v12, v13
	v_lshlrev_b32_e32 v12, 16, v6
	v_and_b32_e32 v13, 0xffff0000, v6
	v_pk_mul_f32 v[14:15], v[14:15], v[16:17]
	v_lshlrev_b32_e32 v16, 16, v107
	v_and_b32_e32 v17, 0xffff0000, v107
	v_mul_f32_e32 v3, 0xbfb8aa3b, v16
	v_exp_f32_e32 v3, v3
	v_mul_f32_e32 v6, 0xbfb8aa3b, v17
	v_exp_f32_e32 v6, v6
	v_pk_mul_f32 v[12:13], v[14:15], v[12:13]
	v_add_f32_e32 v3, 1.0, v3
	v_rcp_f32_e32 v14, v3
	v_add_f32_e32 v3, 1.0, v6
	v_rcp_f32_e32 v15, v3
	v_cvt_pk_bf16_f32 v6, v12, v13
	v_lshlrev_b32_e32 v12, 16, v7
	v_and_b32_e32 v13, 0xffff0000, v7
	v_pk_mul_f32 v[14:15], v[14:15], v[16:17]
	s_movk_i32 s79, 0x100
	v_pk_mul_f32 v[12:13], v[14:15], v[12:13]
	s_waitcnt vmcnt(6)
	v_lshlrev_b32_e32 v14, 16, v100
	v_and_b32_e32 v15, 0xffff0000, v100
	v_mul_f32_e32 v3, 0xbfb8aa3b, v14
	v_exp_f32_e32 v3, v3
	v_mul_f32_e32 v16, 0xbfb8aa3b, v15
	v_exp_f32_e32 v17, v16
	v_cvt_pk_bf16_f32 v7, v12, v13
	v_mad_i64_i32 v[12:13], s[6:7], v118, s44, v[0:1]
	v_lshl_add_u64 v[12:13], v[12:13], 0, v[32:33]
	v_add_f32_e32 v3, 1.0, v3
	v_rcp_f32_e32 v16, v3
	v_add_f32_e32 v3, 1.0, v17
	global_store_dwordx4 v[12:13], v[4:7], off nt
	v_lshlrev_b32_e32 v12, 16, v101
	v_rcp_f32_e32 v17, v3
	v_and_b32_e32 v13, 0xffff0000, v101
	v_mul_f32_e32 v3, 0xbfb8aa3b, v12
	s_waitcnt lgkmcnt(0)
	v_lshlrev_b32_e32 v4, 16, v8
	v_and_b32_e32 v5, 0xffff0000, v8
	v_exp_f32_e32 v3, v3
	v_mul_f32_e32 v8, 0xbfb8aa3b, v13
	v_exp_f32_e32 v8, v8
	v_pk_mul_f32 v[6:7], v[16:17], v[14:15]
	v_add_f32_e32 v3, 1.0, v3
	v_pk_mul_f32 v[4:5], v[6:7], v[4:5]
	v_rcp_f32_e32 v6, v3
	v_add_f32_e32 v3, 1.0, v8
	v_rcp_f32_e32 v7, v3
	v_cvt_pk_bf16_f32 v4, v4, v5
	v_lshlrev_b32_e32 v8, 16, v9
	v_and_b32_e32 v9, 0xffff0000, v9
	v_pk_mul_f32 v[6:7], v[6:7], v[12:13]
	v_lshlrev_b32_e32 v12, 16, v102
	v_and_b32_e32 v13, 0xffff0000, v102
	v_mul_f32_e32 v3, 0xbfb8aa3b, v12
	v_exp_f32_e32 v3, v3
	v_mul_f32_e32 v5, 0xbfb8aa3b, v13
	v_exp_f32_e32 v5, v5
	v_pk_mul_f32 v[6:7], v[6:7], v[8:9]
	v_add_f32_e32 v3, 1.0, v3
	v_rcp_f32_e32 v8, v3
	v_add_f32_e32 v3, 1.0, v5
	v_rcp_f32_e32 v9, v3
	v_cvt_pk_bf16_f32 v5, v6, v7
	v_lshlrev_b32_e32 v6, 16, v10
	v_and_b32_e32 v7, 0xffff0000, v10
	v_pk_mul_f32 v[8:9], v[8:9], v[12:13]
	v_lshlrev_b32_e32 v12, 16, v103
	v_and_b32_e32 v13, 0xffff0000, v103
	v_mul_f32_e32 v3, 0xbfb8aa3b, v12
	v_exp_f32_e32 v3, v3
	v_mul_f32_e32 v10, 0xbfb8aa3b, v13
	v_exp_f32_e32 v10, v10
	v_pk_mul_f32 v[6:7], v[8:9], v[6:7]
	v_add_f32_e32 v3, 1.0, v3
	v_rcp_f32_e32 v8, v3
	v_add_f32_e32 v3, 1.0, v10
	v_rcp_f32_e32 v9, v3
	v_lshlrev_b32_e32 v10, 16, v11
	v_and_b32_e32 v11, 0xffff0000, v11
	v_cvt_pk_bf16_f32 v6, v6, v7
	v_pk_mul_f32 v[8:9], v[8:9], v[12:13]
	s_waitcnt vmcnt(6)
	v_lshlrev_b32_e32 v12, 16, v88
	v_pk_mul_f32 v[8:9], v[8:9], v[10:11]
	v_and_b32_e32 v13, 0xffff0000, v88
	v_cvt_pk_bf16_f32 v7, v8, v9
	v_mad_i64_i32 v[8:9], s[6:7], v66, s44, v[0:1]
	v_lshl_add_u64 v[8:9], v[8:9], 0, v[32:33]
	v_mul_f32_e32 v3, 0xbfb8aa3b, v12
	global_store_dwordx4 v[8:9], v[4:7], off nt
	v_exp_f32_e32 v3, v3
	s_movk_i32 s81, 0xff
	v_mul_f32_e32 v4, 0xbfb8aa3b, v13
	v_exp_f32_e32 v8, v4
	v_add_f32_e32 v3, 1.0, v3
	v_rcp_f32_e32 v14, v3
	ds_read_b128 v[4:7], v2 offset:4608
	v_add_f32_e32 v3, 1.0, v8
	v_rcp_f32_e32 v15, v3
	ds_read_b128 v[8:11], v2 offset:5760
	v_readlane_b32 s97, v254, 32
	s_waitcnt lgkmcnt(1)
	v_lshlrev_b32_e32 v16, 16, v4
	v_pk_mul_f32 v[12:13], v[14:15], v[12:13]
	v_lshlrev_b32_e32 v14, 16, v89
	v_and_b32_e32 v15, 0xffff0000, v89
	v_mul_f32_e32 v3, 0xbfb8aa3b, v14
	v_and_b32_e32 v17, 0xffff0000, v4
	v_exp_f32_e32 v3, v3
	v_mul_f32_e32 v4, 0xbfb8aa3b, v15
	v_exp_f32_e32 v4, v4
	v_pk_mul_f32 v[12:13], v[12:13], v[16:17]
	v_add_f32_e32 v3, 1.0, v3
	v_rcp_f32_e32 v16, v3
	v_add_f32_e32 v3, 1.0, v4
	v_rcp_f32_e32 v17, v3
	v_cvt_pk_bf16_f32 v4, v12, v13
	v_lshlrev_b32_e32 v12, 16, v5
	v_and_b32_e32 v13, 0xffff0000, v5
	v_pk_mul_f32 v[14:15], v[16:17], v[14:15]
	v_lshlrev_b32_e32 v16, 16, v90
	v_and_b32_e32 v17, 0xffff0000, v90
	v_mul_f32_e32 v3, 0xbfb8aa3b, v16
	v_exp_f32_e32 v3, v3
	v_mul_f32_e32 v5, 0xbfb8aa3b, v17
	v_exp_f32_e32 v5, v5
	v_pk_mul_f32 v[12:13], v[14:15], v[12:13]
	v_add_f32_e32 v3, 1.0, v3
	v_rcp_f32_e32 v14, v3
	v_add_f32_e32 v3, 1.0, v5
	v_rcp_f32_e32 v15, v3
	v_cvt_pk_bf16_f32 v5, v12, v13
	v_lshlrev_b32_e32 v12, 16, v6
	v_and_b32_e32 v13, 0xffff0000, v6
	v_pk_mul_f32 v[14:15], v[14:15], v[16:17]
	v_lshlrev_b32_e32 v16, 16, v91
	v_and_b32_e32 v17, 0xffff0000, v91
	v_mul_f32_e32 v3, 0xbfb8aa3b, v16
	v_exp_f32_e32 v3, v3
	v_mul_f32_e32 v6, 0xbfb8aa3b, v17
	v_exp_f32_e32 v6, v6
	v_pk_mul_f32 v[12:13], v[14:15], v[12:13]
	v_add_f32_e32 v3, 1.0, v3
	v_rcp_f32_e32 v14, v3
	v_add_f32_e32 v3, 1.0, v6
	v_rcp_f32_e32 v15, v3
	v_cvt_pk_bf16_f32 v6, v12, v13
	v_lshlrev_b32_e32 v12, 16, v7
	v_and_b32_e32 v13, 0xffff0000, v7
	v_pk_mul_f32 v[14:15], v[14:15], v[16:17]
	s_mov_b32 s82, 0x10000
	v_pk_mul_f32 v[12:13], v[14:15], v[12:13]
	s_waitcnt vmcnt(6)
	v_lshlrev_b32_e32 v14, 16, v84
	v_and_b32_e32 v15, 0xffff0000, v84
	v_mul_f32_e32 v3, 0xbfb8aa3b, v14
	v_exp_f32_e32 v3, v3
	v_mul_f32_e32 v16, 0xbfb8aa3b, v15
	v_exp_f32_e32 v17, v16
	v_cvt_pk_bf16_f32 v7, v12, v13
	v_mad_i64_i32 v[12:13], s[6:7], v46, s44, v[0:1]
	v_lshl_add_u64 v[12:13], v[12:13], 0, v[32:33]
	v_add_f32_e32 v3, 1.0, v3
	v_rcp_f32_e32 v16, v3
	v_add_f32_e32 v3, 1.0, v17
	global_store_dwordx4 v[12:13], v[4:7], off nt
	v_lshlrev_b32_e32 v12, 16, v85
	v_rcp_f32_e32 v17, v3
	v_and_b32_e32 v13, 0xffff0000, v85
	v_mul_f32_e32 v3, 0xbfb8aa3b, v12
	s_waitcnt lgkmcnt(0)
	v_lshlrev_b32_e32 v4, 16, v8
	v_and_b32_e32 v5, 0xffff0000, v8
	v_exp_f32_e32 v3, v3
	v_mul_f32_e32 v8, 0xbfb8aa3b, v13
	v_exp_f32_e32 v8, v8
	v_pk_mul_f32 v[6:7], v[16:17], v[14:15]
	v_add_f32_e32 v3, 1.0, v3
	v_pk_mul_f32 v[4:5], v[6:7], v[4:5]
	v_rcp_f32_e32 v6, v3
	v_add_f32_e32 v3, 1.0, v8
	v_rcp_f32_e32 v7, v3
	v_cvt_pk_bf16_f32 v4, v4, v5
	v_lshlrev_b32_e32 v8, 16, v9
	v_and_b32_e32 v9, 0xffff0000, v9
	v_pk_mul_f32 v[6:7], v[6:7], v[12:13]
	v_lshlrev_b32_e32 v12, 16, v86
	v_and_b32_e32 v13, 0xffff0000, v86
	v_mul_f32_e32 v3, 0xbfb8aa3b, v12
	v_exp_f32_e32 v3, v3
	v_mul_f32_e32 v5, 0xbfb8aa3b, v13
	v_exp_f32_e32 v5, v5
	v_pk_mul_f32 v[6:7], v[6:7], v[8:9]
	v_add_f32_e32 v3, 1.0, v3
	v_rcp_f32_e32 v8, v3
	v_add_f32_e32 v3, 1.0, v5
	v_rcp_f32_e32 v9, v3
	v_cvt_pk_bf16_f32 v5, v6, v7
	v_lshlrev_b32_e32 v6, 16, v10
	v_and_b32_e32 v7, 0xffff0000, v10
	v_pk_mul_f32 v[8:9], v[8:9], v[12:13]
	v_lshlrev_b32_e32 v12, 16, v87
	v_and_b32_e32 v13, 0xffff0000, v87
	v_mul_f32_e32 v3, 0xbfb8aa3b, v12
	v_exp_f32_e32 v3, v3
	v_mul_f32_e32 v10, 0xbfb8aa3b, v13
	v_exp_f32_e32 v10, v10
	v_pk_mul_f32 v[6:7], v[8:9], v[6:7]
	v_add_f32_e32 v3, 1.0, v3
	v_rcp_f32_e32 v8, v3
	v_add_f32_e32 v3, 1.0, v10
	v_rcp_f32_e32 v9, v3
	v_lshlrev_b32_e32 v10, 16, v11
	v_and_b32_e32 v11, 0xffff0000, v11
	v_cvt_pk_bf16_f32 v6, v6, v7
	v_pk_mul_f32 v[8:9], v[8:9], v[12:13]
	s_waitcnt vmcnt(6)
	v_lshlrev_b32_e32 v12, 16, v76
	v_pk_mul_f32 v[8:9], v[8:9], v[10:11]
	v_and_b32_e32 v13, 0xffff0000, v76
	v_cvt_pk_bf16_f32 v7, v8, v9
	v_mad_i64_i32 v[8:9], s[6:7], v38, s44, v[0:1]
	v_lshl_add_u64 v[8:9], v[8:9], 0, v[32:33]
	v_mul_f32_e32 v3, 0xbfb8aa3b, v12
	global_store_dwordx4 v[8:9], v[4:7], off nt
	v_exp_f32_e32 v3, v3
	s_nop 0
	v_mul_f32_e32 v4, 0xbfb8aa3b, v13
	v_exp_f32_e32 v8, v4
	v_add_f32_e32 v3, 1.0, v3
	v_rcp_f32_e32 v14, v3
	ds_read_b128 v[4:7], v2 offset:6912
	v_add_f32_e32 v3, 1.0, v8
	v_rcp_f32_e32 v15, v3
	ds_read_b128 v[8:11], v2 offset:8064
	s_waitcnt lgkmcnt(1)
	v_lshlrev_b32_e32 v2, 16, v4
	v_pk_mul_f32 v[12:13], v[14:15], v[12:13]
	v_lshlrev_b32_e32 v14, 16, v77
	v_and_b32_e32 v3, 0xffff0000, v4
	v_and_b32_e32 v15, 0xffff0000, v77
	v_mul_f32_e32 v4, 0xbfb8aa3b, v14
	v_exp_f32_e32 v4, v4
	v_mul_f32_e32 v16, 0xbfb8aa3b, v15
	v_exp_f32_e32 v16, v16
	v_pk_mul_f32 v[2:3], v[12:13], v[2:3]
	v_add_f32_e32 v4, 1.0, v4
	v_rcp_f32_e32 v12, v4
	v_add_f32_e32 v4, 1.0, v16
	v_rcp_f32_e32 v13, v4
	v_cvt_pk_bf16_f32 v2, v2, v3
	v_lshlrev_b32_e32 v4, 16, v5
	v_and_b32_e32 v5, 0xffff0000, v5
	v_pk_mul_f32 v[12:13], v[12:13], v[14:15]
	v_lshlrev_b32_e32 v14, 16, v78
	v_and_b32_e32 v15, 0xffff0000, v78
	v_mul_f32_e32 v3, 0xbfb8aa3b, v14
	v_exp_f32_e32 v3, v3
	v_mul_f32_e32 v16, 0xbfb8aa3b, v15
	v_exp_f32_e32 v16, v16
	v_pk_mul_f32 v[4:5], v[12:13], v[4:5]
	v_add_f32_e32 v3, 1.0, v3
	v_rcp_f32_e32 v12, v3
	v_add_f32_e32 v3, 1.0, v16
	v_rcp_f32_e32 v13, v3
	v_cvt_pk_bf16_f32 v3, v4, v5
	v_lshlrev_b32_e32 v4, 16, v6
	v_and_b32_e32 v5, 0xffff0000, v6
	v_pk_mul_f32 v[12:13], v[12:13], v[14:15]
	v_lshlrev_b32_e32 v14, 16, v79
	v_and_b32_e32 v15, 0xffff0000, v79
	v_mul_f32_e32 v6, 0xbfb8aa3b, v14
	v_exp_f32_e32 v6, v6
	v_mul_f32_e32 v16, 0xbfb8aa3b, v15
	v_exp_f32_e32 v16, v16
	v_pk_mul_f32 v[4:5], v[12:13], v[4:5]
	v_add_f32_e32 v6, 1.0, v6
	v_rcp_f32_e32 v12, v6
	v_add_f32_e32 v6, 1.0, v16
	v_rcp_f32_e32 v13, v6
	v_lshlrev_b32_e32 v6, 16, v7
	v_and_b32_e32 v7, 0xffff0000, v7
	v_cvt_pk_bf16_f32 v4, v4, v5
	v_pk_mul_f32 v[12:13], v[12:13], v[14:15]
	s_nop 0
	v_pk_mul_f32 v[6:7], v[12:13], v[6:7]
	s_waitcnt vmcnt(6)
	v_lshlrev_b32_e32 v12, 16, v72
	v_and_b32_e32 v13, 0xffff0000, v72
	v_mul_f32_e32 v14, 0xbfb8aa3b, v12
	v_mul_f32_e32 v15, 0xbfb8aa3b, v13
	v_exp_f32_e32 v14, v14
	v_exp_f32_e32 v15, v15
	v_cvt_pk_bf16_f32 v5, v6, v7
	v_mad_i64_i32 v[6:7], s[6:7], v34, s44, v[0:1]
	v_add_f32_e32 v14, 1.0, v14
	v_add_f32_e32 v15, 1.0, v15
	v_rcp_f32_e32 v14, v14
	v_rcp_f32_e32 v15, v15
	v_lshl_add_u64 v[6:7], v[6:7], 0, v[32:33]
	global_store_dwordx4 v[6:7], v[2:5], off nt
	v_lshlrev_b32_e32 v6, 16, v73
	v_and_b32_e32 v7, 0xffff0000, v73
	s_waitcnt lgkmcnt(0)
	v_lshlrev_b32_e32 v2, 16, v8
	v_and_b32_e32 v3, 0xffff0000, v8
	v_pk_mul_f32 v[4:5], v[14:15], v[12:13]
	v_mul_f32_e32 v8, 0xbfb8aa3b, v6
	v_mul_f32_e32 v12, 0xbfb8aa3b, v7
	v_exp_f32_e32 v8, v8
	v_exp_f32_e32 v12, v12
	v_pk_mul_f32 v[2:3], v[4:5], v[2:3]
	v_mad_i64_i32 v[0:1], s[6:7], v18, s44, v[0:1]
	v_add_f32_e32 v4, 1.0, v8
	v_add_f32_e32 v5, 1.0, v12
	v_rcp_f32_e32 v4, v4
	v_rcp_f32_e32 v5, v5
	v_cvt_pk_bf16_f32 v2, v2, v3
	v_lshlrev_b32_e32 v8, 16, v9
	v_and_b32_e32 v9, 0xffff0000, v9
	v_pk_mul_f32 v[4:5], v[4:5], v[6:7]
	v_lshlrev_b32_e32 v6, 16, v74
	v_and_b32_e32 v7, 0xffff0000, v74
	v_mul_f32_e32 v3, 0xbfb8aa3b, v6
	v_exp_f32_e32 v3, v3
	v_mul_f32_e32 v12, 0xbfb8aa3b, v7
	v_exp_f32_e32 v12, v12
	v_pk_mul_f32 v[4:5], v[4:5], v[8:9]
	v_add_f32_e32 v3, 1.0, v3
	v_rcp_f32_e32 v8, v3
	v_add_f32_e32 v3, 1.0, v12
	v_rcp_f32_e32 v9, v3
	v_cvt_pk_bf16_f32 v3, v4, v5
	v_lshlrev_b32_e32 v4, 16, v10
	v_and_b32_e32 v5, 0xffff0000, v10
	v_pk_mul_f32 v[6:7], v[8:9], v[6:7]
	v_lshlrev_b32_e32 v8, 16, v75
	v_and_b32_e32 v9, 0xffff0000, v75
	v_mul_f32_e32 v10, 0xbfb8aa3b, v8
	v_mul_f32_e32 v12, 0xbfb8aa3b, v9
	v_exp_f32_e32 v10, v10
	v_exp_f32_e32 v12, v12
	v_pk_mul_f32 v[4:5], v[6:7], v[4:5]
	v_lshl_add_u64 v[0:1], v[0:1], 0, v[32:33]
	v_add_f32_e32 v6, 1.0, v10
	v_add_f32_e32 v7, 1.0, v12
	v_rcp_f32_e32 v6, v6
	v_rcp_f32_e32 v7, v7
	v_lshlrev_b32_e32 v10, 16, v11
	v_and_b32_e32 v11, 0xffff0000, v11
	v_cvt_pk_bf16_f32 v4, v4, v5
	v_pk_mul_f32 v[6:7], v[6:7], v[8:9]
	s_mov_b64 s[6:7], s[76:77]
	v_pk_mul_f32 v[6:7], v[6:7], v[10:11]
	s_nop 0
	v_cvt_pk_bf16_f32 v5, v6, v7
	global_store_dwordx4 v[0:1], v[2:5], off nt
